# v13 with 3-deep residual prefetch (prologue temporaries reused as block temporaries)
# baseline (speedup 1.0000x reference)
;     __device__ __forceinline__ void operator()(const f32x4 (&acc)[2][2][4][2], const Unit& u, int wr, int wc, int fr, int fq) const {
;         const int row0 = u.pm * BM + wr * 64 + fr, col0 = u.pn * BM + wc * 32 + 4 * fq;
;         const float* rbase = (u.pm * BM < SEQ_P) ? resA : (resB - (size_t)SEQ_P * ldc);
;         f32x4 wv[2][2];
;         if (xn) {
; #pragma unroll
;             for (int bj = 0; bj < 2; ++bj)
; #pragma unroll
;                 for (int n = 0; n < 2; ++n) wv[bj][n] = *(const f32x4*)(wn + col0 + bj * HALF + n * 16);
;         }
; #pragma unroll
;         for (int ai = 0; ai < 2; ++ai)
; #pragma unroll
;             for (int m = 0; m < 4; ++m) {
;                 const int row = row0 + ai * HALF + m * 16;
;                 const size_t off = (size_t)row * ldc + col0;
;                 float q = 0.f;
; #pragma unroll
;                 for (int bj = 0; bj < 2; ++bj)
; #pragma unroll
;                     for (int n = 0; n < 2; ++n) {
;                         const f32x4 rv = *(const f32x4*)(rbase + off + bj * HALF + n * 16);
;                         const f32x4 v = rv + acc[ai][bj][m][n] * scale;
;                         if (out) *(f32x4*)(out + off + bj * HALF + n * 16) = v;
;                         if (xn) { q += (v.x * v.x + v.y * v.y) + (v.z * v.z + v.w * v.w); const f32x4 o = v * wv[bj][n];
;                             u32x2 p; p.x = pk2(o.x, o.y); p.y = pk2(o.z, o.w); *(u32x2*)(xn + off + bj * HALF + n * 16) = p; }
.LBB0_312:
	v_lshl_add_u32 v228, s62, 8, v168
	v_lshl_or_b32 v230, s61, 8, v170
	v_and_b32_e32 v249, 8, v174
	v_mov_b32_e32 v229, 0
	v_cmp_eq_u32_e64 s[34:35], 0, v249
	v_lshlrev_b32_e32 v175, 1, v249
	v_add_u32_e32 v232, v230, v175
	v_sub_u32_e32 v238, 16, v175
	v_add_u32_e32 v238, v230, v238
	v_mov_b32_e32 v230, v232
	v_mov_b32_e32 v232, v238
	v_mov_b32_e32 v231, 0
	v_mov_b32_e32 v233, 0
	v_sub_u32_e32 v226, v228, v249
	v_mov_b32_e32 v227, 0
	v_lshlrev_b64 v[224:225], 11, v[226:227]
	v_add_u32_e32 v226, 8, v226
	v_lshlrev_b64 v[226:227], 11, v[226:227]
	s_cmp_lt_i32 s62, 32
	s_cselect_b32 s31, s2, s54
	s_cselect_b32 s30, s33, s53
	v_lshl_add_u64 v[224:225], v[224:225], 0, v[230:231]
	v_lshl_add_u64 v[226:227], v[226:227], 0, v[232:233]
	v_lshl_add_u64 v[164:165], v[224:225], 2, s[30:31]
	v_lshl_add_u64 v[216:217], v[226:227], 2, s[30:31]
	v_lshl_add_u64 v[218:219], v[230:231], 2, s[10:11]
	v_lshl_add_u64 v[220:221], v[232:233], 2, s[10:11]
	global_load_dwordx4 v[64:67], v[218:219], off
	global_load_dwordx4 v[72:75], v[218:219], off offset:512
	global_load_dwordx4 v[80:83], v[220:221], off
	global_load_dwordx4 v[84:87], v[220:221], off offset:512
	global_load_dwordx4 v[156:159], v[164:165], off
	global_load_dwordx4 v[160:163], v[164:165], off offset:512
	global_load_dwordx4 v[176:179], v[216:217], off
	global_load_dwordx4 v[180:183], v[216:217], off offset:512
	s_mov_b64 vcc, 0x20000
	v_lshl_add_u64 v[164:165], v[164:165], 0, vcc
	v_lshl_add_u64 v[216:217], v[216:217], 0, vcc
	global_load_dwordx4 v[184:187], v[164:165], off
	global_load_dwordx4 v[188:191], v[164:165], off offset:512
	global_load_dwordx4 v[192:195], v[216:217], off
	global_load_dwordx4 v[196:199], v[216:217], off offset:512
	s_mov_b64 vcc, 0x20000
	v_lshl_add_u64 v[164:165], v[164:165], 0, vcc
	v_lshl_add_u64 v[216:217], v[216:217], 0, vcc
	global_load_dwordx4 v[200:203], v[164:165], off
	global_load_dwordx4 v[204:207], v[164:165], off offset:512
	global_load_dwordx4 v[208:211], v[216:217], off
	global_load_dwordx4 v[212:215], v[216:217], off offset:512
	s_mov_b64 vcc, 0x20000
	v_lshl_add_u64 v[164:165], v[164:165], 0, vcc
	v_lshl_add_u64 v[216:217], v[216:217], 0, vcc
	v_lshl_add_u64 v[234:235], v[224:225], 2, s[8:9]
	v_lshl_add_u64 v[236:237], v[226:227], 2, s[8:9]
	v_lshl_add_u64 v[218:219], v[224:225], 1, s[14:15]
	v_lshl_add_u64 v[220:221], v[226:227], 1, s[14:15]
	v_lshl_add_u64 v[222:223], v[228:229], 2, s[18:19]
	v_xor_b32_e32 v239, 16, v174
	v_xor_b32_e32 v248, 32, v174
	v_lshlrev_b32_e32 v239, 2, v239
	v_lshlrev_b32_e32 v248, 2, v248
	v_mov_b32_dpp v224, v136 row_ror:8 row_mask:0xf bank_mask:0xf
	v_mov_b32_dpp v225, v137 row_ror:8 row_mask:0xf bank_mask:0xf
	v_mov_b32_dpp v226, v138 row_ror:8 row_mask:0xf bank_mask:0xf
	v_mov_b32_dpp v227, v139 row_ror:8 row_mask:0xf bank_mask:0xf
	v_cndmask_b32_e64 v136, v224, v140, s[34:35]
	v_cndmask_b32_e64 v137, v225, v141, s[34:35]
	v_cndmask_b32_e64 v138, v226, v142, s[34:35]
	v_cndmask_b32_e64 v139, v227, v143, s[34:35]
	v_cndmask_b32_e64 v140, v140, v224, s[34:35]
	v_cndmask_b32_e64 v141, v141, v225, s[34:35]
	v_cndmask_b32_e64 v142, v142, v226, s[34:35]
	v_cndmask_b32_e64 v143, v143, v227, s[34:35]
	v_mov_b32_dpp v224, v128 row_ror:8 row_mask:0xf bank_mask:0xf
	v_mov_b32_dpp v225, v129 row_ror:8 row_mask:0xf bank_mask:0xf
	v_mov_b32_dpp v226, v130 row_ror:8 row_mask:0xf bank_mask:0xf
	v_mov_b32_dpp v227, v131 row_ror:8 row_mask:0xf bank_mask:0xf
	v_cndmask_b32_e64 v128, v224, v132, s[34:35]
	v_cndmask_b32_e64 v129, v225, v133, s[34:35]
	v_cndmask_b32_e64 v130, v226, v134, s[34:35]
	v_cndmask_b32_e64 v131, v227, v135, s[34:35]
	v_cndmask_b32_e64 v132, v132, v224, s[34:35]
	v_cndmask_b32_e64 v133, v133, v225, s[34:35]
	v_cndmask_b32_e64 v134, v134, v226, s[34:35]
	v_cndmask_b32_e64 v135, v135, v227, s[34:35]
	s_waitcnt vmcnt(8)
	v_pk_fma_f32 v[138:139], v[138:139], 0.5, v[158:159] op_sel_hi:[1,0,1]
	v_pk_fma_f32 v[136:137], v[136:137], 0.5, v[156:157] op_sel_hi:[1,0,1]
	global_store_dwordx4 v[234:235], v[136:139], off
	v_pk_mul_f32 v[240:241], v[64:65], v[136:137]
	v_pk_mul_f32 v[242:243], v[66:67], v[138:139]
	v_mul_f32_e32 v175, v136, v136
	v_add_u32_e32 v240, 0x8000, v240
	v_add_u32_e32 v241, 0x8000, v241
	v_add_u32_e32 v242, 0x8000, v242
	v_add_u32_e32 v243, 0x8000, v243
	v_fmac_f32_e32 v175, v137, v137
	v_fmac_f32_e32 v175, v138, v138
	v_fmac_f32_e32 v175, v139, v139
	v_perm_b32 v230, v241, v240, s58
	v_perm_b32 v231, v243, v242, s58
	global_store_dwordx2 v[218:219], v[230:231], off
	v_pk_fma_f32 v[130:131], v[130:131], 0.5, v[162:163] op_sel_hi:[1,0,1]
	v_pk_fma_f32 v[128:129], v[128:129], 0.5, v[160:161] op_sel_hi:[1,0,1]
	global_store_dwordx4 v[234:235], v[128:131], off offset:512
	v_pk_mul_f32 v[244:245], v[72:73], v[128:129]
	v_pk_mul_f32 v[246:247], v[74:75], v[130:131]
	v_fmac_f32_e32 v175, v128, v128
	v_add_u32_e32 v244, 0x8000, v244
	v_add_u32_e32 v245, 0x8000, v245
	v_add_u32_e32 v246, 0x8000, v246
	v_add_u32_e32 v247, 0x8000, v247
	v_fmac_f32_e32 v175, v129, v129
	v_fmac_f32_e32 v175, v130, v130
	v_fmac_f32_e32 v175, v131, v131
	v_perm_b32 v232, v245, v244, s58
	v_perm_b32 v233, v247, v246, s58
	global_store_dwordx2 v[218:219], v[232:233], off offset:256
	v_pk_fma_f32 v[142:143], v[142:143], 0.5, v[178:179] op_sel_hi:[1,0,1]
	v_pk_fma_f32 v[140:141], v[140:141], 0.5, v[176:177] op_sel_hi:[1,0,1]
	global_store_dwordx4 v[236:237], v[140:143], off
	v_pk_mul_f32 v[240:241], v[80:81], v[140:141]
	v_pk_mul_f32 v[242:243], v[82:83], v[142:143]
	v_mul_f32_e32 v238, v140, v140
	v_add_u32_e32 v240, 0x8000, v240
	v_add_u32_e32 v241, 0x8000, v241
	v_add_u32_e32 v242, 0x8000, v242
	v_add_u32_e32 v243, 0x8000, v243
;     __device__ __forceinline__ void operator()(const f32x4 (&acc)[2][2][4][2], const Unit& u, int wr, int wc, int fr, int fq) const {
;     ...
; #pragma unroll
;         for (int ai = 0; ai < 2; ++ai)
; #pragma unroll
;             for (int m = 0; m < 4; ++m) {
;                 const int row = row0 + ai * HALF + m * 16;
;                 const size_t off = (size_t)row * ldc + col0;
;                 float q = 0.f;
; #pragma unroll
;                 for (int bj = 0; bj < 2; ++bj)
; #pragma unroll
;                     for (int n = 0; n < 2; ++n) {
;                         const f32x4 rv = *(const f32x4*)(rbase + off + bj * HALF + n * 16);
;                         const f32x4 v = rv + acc[ai][bj][m][n] * scale;
;                         if (out) *(f32x4*)(out + off + bj * HALF + n * 16) = v;
;                         if (xn) { q += (v.x * v.x + v.y * v.y) + (v.z * v.z + v.w * v.w); const f32x4 o = v * wv[bj][n];
;                             u32x2 p; p.x = pk2(o.x, o.y); p.y = pk2(o.z, o.w); *(u32x2*)(xn + off + bj * HALF + n * 16) = p; }
;                     }
;                 if (xn) { q += __shfl_xor(q, 16); q += __shfl_xor(q, 32); if (fq == 0) (void)__hip_atomic_fetch_add(ss + row, q, __ATOMIC_RELAXED, __HIP_MEMORY_SCOPE_AGENT); }
;             }
	v_fmac_f32_e32 v238, v141, v141
	v_fmac_f32_e32 v238, v142, v142
	v_fmac_f32_e32 v238, v143, v143
	v_perm_b32 v230, v241, v240, s58
	v_perm_b32 v231, v243, v242, s58
	global_store_dwordx2 v[220:221], v[230:231], off
	v_pk_fma_f32 v[134:135], v[134:135], 0.5, v[182:183] op_sel_hi:[1,0,1]
	v_pk_fma_f32 v[132:133], v[132:133], 0.5, v[180:181] op_sel_hi:[1,0,1]
	global_store_dwordx4 v[236:237], v[132:135], off offset:512
	v_pk_mul_f32 v[244:245], v[84:85], v[132:133]
	v_pk_mul_f32 v[246:247], v[86:87], v[134:135]
	v_fmac_f32_e32 v238, v132, v132
	v_add_u32_e32 v244, 0x8000, v244
	v_add_u32_e32 v245, 0x8000, v245
	v_add_u32_e32 v246, 0x8000, v246
	v_add_u32_e32 v247, 0x8000, v247
	v_fmac_f32_e32 v238, v133, v133
	v_fmac_f32_e32 v238, v134, v134
	v_fmac_f32_e32 v238, v135, v135
	v_perm_b32 v232, v245, v244, s58
	v_perm_b32 v233, v247, v246, s58
	global_store_dwordx2 v[220:221], v[232:233], off offset:256
	s_nop 1
	v_mov_b32_dpp v228, v175 row_ror:8 row_mask:0xf bank_mask:0xf
	v_mov_b32_dpp v229, v238 row_ror:8 row_mask:0xf bank_mask:0xf
	v_add_f32_e32 v175, v175, v228
	v_add_f32_e32 v238, v238, v229
	v_cndmask_b32_e64 v175, v238, v175, s[34:35]
	s_nop 0
	ds_bpermute_b32 v228, v239, v175
	global_load_dwordx4 v[156:159], v[164:165], off
	global_load_dwordx4 v[160:163], v[164:165], off offset:512
	global_load_dwordx4 v[176:179], v[216:217], off
	global_load_dwordx4 v[180:183], v[216:217], off offset:512
	s_mov_b64 vcc, 0xa0000
	v_lshl_add_u64 v[164:165], v[164:165], 0, vcc
	v_lshl_add_u64 v[216:217], v[216:217], 0, vcc
	s_mov_b64 vcc, 0x20000
	v_lshl_add_u64 v[234:235], v[234:235], 0, vcc
	v_lshl_add_u64 v[236:237], v[236:237], 0, vcc
	s_mov_b64 vcc, 0x10000
	v_lshl_add_u64 v[218:219], v[218:219], 0, vcc
	v_lshl_add_u64 v[220:221], v[220:221], 0, vcc
	s_waitcnt lgkmcnt(0)
	v_add_f32_e32 v175, v175, v228
	s_nop 0
	ds_bpermute_b32 v229, v248, v175
	s_waitcnt lgkmcnt(0)
	v_add_f32_e32 v175, v175, v229
	s_mov_b64 exec, s[0:1]
	global_atomic_add_f32 v[222:223], v175, off
	s_mov_b64 exec, -1
	s_mov_b64 vcc, 64
	v_lshl_add_u64 v[222:223], v[222:223], 0, vcc
	v_mov_b32_dpp v224, v120 row_ror:8 row_mask:0xf bank_mask:0xf
	v_mov_b32_dpp v225, v121 row_ror:8 row_mask:0xf bank_mask:0xf
	v_mov_b32_dpp v226, v122 row_ror:8 row_mask:0xf bank_mask:0xf
	v_mov_b32_dpp v227, v123 row_ror:8 row_mask:0xf bank_mask:0xf
	v_cndmask_b32_e64 v120, v224, v124, s[34:35]
	v_cndmask_b32_e64 v121, v225, v125, s[34:35]
	v_cndmask_b32_e64 v122, v226, v126, s[34:35]
	v_cndmask_b32_e64 v123, v227, v127, s[34:35]
	v_cndmask_b32_e64 v124, v124, v224, s[34:35]
	v_cndmask_b32_e64 v125, v125, v225, s[34:35]
	v_cndmask_b32_e64 v126, v126, v226, s[34:35]
	v_cndmask_b32_e64 v127, v127, v227, s[34:35]
	v_mov_b32_dpp v224, v112 row_ror:8 row_mask:0xf bank_mask:0xf
	v_mov_b32_dpp v225, v113 row_ror:8 row_mask:0xf bank_mask:0xf
	v_mov_b32_dpp v226, v114 row_ror:8 row_mask:0xf bank_mask:0xf
	v_mov_b32_dpp v227, v115 row_ror:8 row_mask:0xf bank_mask:0xf
	v_cndmask_b32_e64 v112, v224, v116, s[34:35]
	v_cndmask_b32_e64 v113, v225, v117, s[34:35]
	v_cndmask_b32_e64 v114, v226, v118, s[34:35]
	v_cndmask_b32_e64 v115, v227, v119, s[34:35]
	v_cndmask_b32_e64 v116, v116, v224, s[34:35]
	v_cndmask_b32_e64 v117, v117, v225, s[34:35]
	v_cndmask_b32_e64 v118, v118, v226, s[34:35]
	v_cndmask_b32_e64 v119, v119, v227, s[34:35]
	s_waitcnt vmcnt(17)
	v_pk_fma_f32 v[122:123], v[122:123], 0.5, v[186:187] op_sel_hi:[1,0,1]
	v_pk_fma_f32 v[120:121], v[120:121], 0.5, v[184:185] op_sel_hi:[1,0,1]
	global_store_dwordx4 v[234:235], v[120:123], off
	v_pk_mul_f32 v[240:241], v[64:65], v[120:121]
	v_pk_mul_f32 v[242:243], v[66:67], v[122:123]
	v_mul_f32_e32 v175, v120, v120
	v_add_u32_e32 v240, 0x8000, v240
	v_add_u32_e32 v241, 0x8000, v241
	v_add_u32_e32 v242, 0x8000, v242
	v_add_u32_e32 v243, 0x8000, v243
	v_fmac_f32_e32 v175, v121, v121
	v_fmac_f32_e32 v175, v122, v122
	v_fmac_f32_e32 v175, v123, v123
	v_perm_b32 v230, v241, v240, s58
	v_perm_b32 v231, v243, v242, s58
	global_store_dwordx2 v[218:219], v[230:231], off
	v_pk_fma_f32 v[114:115], v[114:115], 0.5, v[190:191] op_sel_hi:[1,0,1]
	v_pk_fma_f32 v[112:113], v[112:113], 0.5, v[188:189] op_sel_hi:[1,0,1]
	global_store_dwordx4 v[234:235], v[112:115], off offset:512
	v_pk_mul_f32 v[244:245], v[72:73], v[112:113]
	v_pk_mul_f32 v[246:247], v[74:75], v[114:115]
	v_fmac_f32_e32 v175, v112, v112
	v_add_u32_e32 v244, 0x8000, v244
	v_add_u32_e32 v245, 0x8000, v245
	v_add_u32_e32 v246, 0x8000, v246
	v_add_u32_e32 v247, 0x8000, v247
	v_fmac_f32_e32 v175, v113, v113
	v_fmac_f32_e32 v175, v114, v114
	v_fmac_f32_e32 v175, v115, v115
	v_perm_b32 v232, v245, v244, s58
	v_perm_b32 v233, v247, v246, s58
	global_store_dwordx2 v[218:219], v[232:233], off offset:256
	v_pk_fma_f32 v[126:127], v[126:127], 0.5, v[194:195] op_sel_hi:[1,0,1]
	v_pk_fma_f32 v[124:125], v[124:125], 0.5, v[192:193] op_sel_hi:[1,0,1]
	global_store_dwordx4 v[236:237], v[124:127], off
	v_pk_mul_f32 v[240:241], v[80:81], v[124:125]
	v_pk_mul_f32 v[242:243], v[82:83], v[126:127]
	v_mul_f32_e32 v238, v124, v124
	v_add_u32_e32 v240, 0x8000, v240
	v_add_u32_e32 v241, 0x8000, v241
	v_add_u32_e32 v242, 0x8000, v242
	v_add_u32_e32 v243, 0x8000, v243
	v_fmac_f32_e32 v238, v125, v125
	v_fmac_f32_e32 v238, v126, v126
	v_fmac_f32_e32 v238, v127, v127
	v_perm_b32 v230, v241, v240, s58
	v_perm_b32 v231, v243, v242, s58
	global_store_dwordx2 v[220:221], v[230:231], off
	v_pk_fma_f32 v[118:119], v[118:119], 0.5, v[198:199] op_sel_hi:[1,0,1]
	v_pk_fma_f32 v[116:117], v[116:117], 0.5, v[196:197] op_sel_hi:[1,0,1]
	global_store_dwordx4 v[236:237], v[116:119], off offset:512
	v_pk_mul_f32 v[244:245], v[84:85], v[116:117]
	v_pk_mul_f32 v[246:247], v[86:87], v[118:119]
	v_fmac_f32_e32 v238, v116, v116
	v_add_u32_e32 v244, 0x8000, v244
	v_add_u32_e32 v245, 0x8000, v245
	v_add_u32_e32 v246, 0x8000, v246
	v_add_u32_e32 v247, 0x8000, v247
	v_fmac_f32_e32 v238, v117, v117
	v_fmac_f32_e32 v238, v118, v118
	v_fmac_f32_e32 v238, v119, v119
	v_perm_b32 v232, v245, v244, s58
	v_perm_b32 v233, v247, v246, s58
	global_store_dwordx2 v[220:221], v[232:233], off offset:256
	s_nop 1
	v_mov_b32_dpp v228, v175 row_ror:8 row_mask:0xf bank_mask:0xf
	v_mov_b32_dpp v229, v238 row_ror:8 row_mask:0xf bank_mask:0xf
	v_add_f32_e32 v175, v175, v228
	v_add_f32_e32 v238, v238, v229
	v_cndmask_b32_e64 v175, v238, v175, s[34:35]
	s_nop 0
	ds_bpermute_b32 v228, v239, v175
	global_load_dwordx4 v[184:187], v[164:165], off
	global_load_dwordx4 v[188:191], v[164:165], off offset:512
	global_load_dwordx4 v[192:195], v[216:217], off
	global_load_dwordx4 v[196:199], v[216:217], off offset:512
	s_mov_b64 vcc, 0x20000
	v_lshl_add_u64 v[164:165], v[164:165], 0, vcc
	v_lshl_add_u64 v[216:217], v[216:217], 0, vcc
	s_mov_b64 vcc, 0x20000
	v_lshl_add_u64 v[234:235], v[234:235], 0, vcc
	v_lshl_add_u64 v[236:237], v[236:237], 0, vcc
	s_mov_b64 vcc, 0x10000
	v_lshl_add_u64 v[218:219], v[218:219], 0, vcc
	v_lshl_add_u64 v[220:221], v[220:221], 0, vcc
	s_waitcnt lgkmcnt(0)
;     __device__ __forceinline__ void operator()(const f32x4 (&acc)[2][2][4][2], const Unit& u, int wr, int wc, int fr, int fq) const {
;     ...
; #pragma unroll
;         for (int ai = 0; ai < 2; ++ai)
; #pragma unroll
;             for (int m = 0; m < 4; ++m) {
;                 const int row = row0 + ai * HALF + m * 16;
;                 const size_t off = (size_t)row * ldc + col0;
;                 float q = 0.f;
; #pragma unroll
;                 for (int bj = 0; bj < 2; ++bj)
; #pragma unroll
;                     for (int n = 0; n < 2; ++n) {
;                         const f32x4 rv = *(const f32x4*)(rbase + off + bj * HALF + n * 16);
;                         const f32x4 v = rv + acc[ai][bj][m][n] * scale;
;                         if (out) *(f32x4*)(out + off + bj * HALF + n * 16) = v;
;                         if (xn) { q += (v.x * v.x + v.y * v.y) + (v.z * v.z + v.w * v.w); const f32x4 o = v * wv[bj][n];
;                             u32x2 p; p.x = pk2(o.x, o.y); p.y = pk2(o.z, o.w); *(u32x2*)(xn + off + bj * HALF + n * 16) = p; }
;                     }
;                 if (xn) { q += __shfl_xor(q, 16); q += __shfl_xor(q, 32); if (fq == 0) (void)__hip_atomic_fetch_add(ss + row, q, __ATOMIC_RELAXED, __HIP_MEMORY_SCOPE_AGENT); }
;             }
	v_add_f32_e32 v175, v175, v228
	s_nop 0
	ds_bpermute_b32 v229, v248, v175
	s_waitcnt lgkmcnt(0)
	v_add_f32_e32 v175, v175, v229
	s_mov_b64 exec, s[0:1]
	global_atomic_add_f32 v[222:223], v175, off
	s_mov_b64 exec, -1
	s_mov_b64 vcc, 64
	v_lshl_add_u64 v[222:223], v[222:223], 0, vcc
	v_mov_b32_dpp v224, v104 row_ror:8 row_mask:0xf bank_mask:0xf
	v_mov_b32_dpp v225, v105 row_ror:8 row_mask:0xf bank_mask:0xf
	v_mov_b32_dpp v226, v106 row_ror:8 row_mask:0xf bank_mask:0xf
	v_mov_b32_dpp v227, v107 row_ror:8 row_mask:0xf bank_mask:0xf
	v_cndmask_b32_e64 v104, v224, v108, s[34:35]
	v_cndmask_b32_e64 v105, v225, v109, s[34:35]
	v_cndmask_b32_e64 v106, v226, v110, s[34:35]
	v_cndmask_b32_e64 v107, v227, v111, s[34:35]
	v_cndmask_b32_e64 v108, v108, v224, s[34:35]
	v_cndmask_b32_e64 v109, v109, v225, s[34:35]
	v_cndmask_b32_e64 v110, v110, v226, s[34:35]
	v_cndmask_b32_e64 v111, v111, v227, s[34:35]
	v_mov_b32_dpp v224, v96 row_ror:8 row_mask:0xf bank_mask:0xf
	v_mov_b32_dpp v225, v97 row_ror:8 row_mask:0xf bank_mask:0xf
	v_mov_b32_dpp v226, v98 row_ror:8 row_mask:0xf bank_mask:0xf
	v_mov_b32_dpp v227, v99 row_ror:8 row_mask:0xf bank_mask:0xf
	v_cndmask_b32_e64 v96, v224, v100, s[34:35]
	v_cndmask_b32_e64 v97, v225, v101, s[34:35]
	v_cndmask_b32_e64 v98, v226, v102, s[34:35]
	v_cndmask_b32_e64 v99, v227, v103, s[34:35]
	v_cndmask_b32_e64 v100, v100, v224, s[34:35]
	v_cndmask_b32_e64 v101, v101, v225, s[34:35]
	v_cndmask_b32_e64 v102, v102, v226, s[34:35]
	v_cndmask_b32_e64 v103, v103, v227, s[34:35]
	s_waitcnt vmcnt(26)
	v_pk_fma_f32 v[106:107], v[106:107], 0.5, v[202:203] op_sel_hi:[1,0,1]
	v_pk_fma_f32 v[104:105], v[104:105], 0.5, v[200:201] op_sel_hi:[1,0,1]
	global_store_dwordx4 v[234:235], v[104:107], off
	v_pk_mul_f32 v[240:241], v[64:65], v[104:105]
	v_pk_mul_f32 v[242:243], v[66:67], v[106:107]
	v_mul_f32_e32 v175, v104, v104
	v_add_u32_e32 v240, 0x8000, v240
	v_add_u32_e32 v241, 0x8000, v241
	v_add_u32_e32 v242, 0x8000, v242
	v_add_u32_e32 v243, 0x8000, v243
	v_fmac_f32_e32 v175, v105, v105
	v_fmac_f32_e32 v175, v106, v106
	v_fmac_f32_e32 v175, v107, v107
	v_perm_b32 v230, v241, v240, s58
	v_perm_b32 v231, v243, v242, s58
	global_store_dwordx2 v[218:219], v[230:231], off
	v_pk_fma_f32 v[98:99], v[98:99], 0.5, v[206:207] op_sel_hi:[1,0,1]
	v_pk_fma_f32 v[96:97], v[96:97], 0.5, v[204:205] op_sel_hi:[1,0,1]
	global_store_dwordx4 v[234:235], v[96:99], off offset:512
	v_pk_mul_f32 v[244:245], v[72:73], v[96:97]
	v_pk_mul_f32 v[246:247], v[74:75], v[98:99]
	v_fmac_f32_e32 v175, v96, v96
	v_add_u32_e32 v244, 0x8000, v244
	v_add_u32_e32 v245, 0x8000, v245
	v_add_u32_e32 v246, 0x8000, v246
	v_add_u32_e32 v247, 0x8000, v247
	v_fmac_f32_e32 v175, v97, v97
	v_fmac_f32_e32 v175, v98, v98
	v_fmac_f32_e32 v175, v99, v99
	v_perm_b32 v232, v245, v244, s58
	v_perm_b32 v233, v247, v246, s58
	global_store_dwordx2 v[218:219], v[232:233], off offset:256
	v_pk_fma_f32 v[110:111], v[110:111], 0.5, v[210:211] op_sel_hi:[1,0,1]
	v_pk_fma_f32 v[108:109], v[108:109], 0.5, v[208:209] op_sel_hi:[1,0,1]
	global_store_dwordx4 v[236:237], v[108:111], off
	v_pk_mul_f32 v[240:241], v[80:81], v[108:109]
	v_pk_mul_f32 v[242:243], v[82:83], v[110:111]
	v_mul_f32_e32 v238, v108, v108
	v_add_u32_e32 v240, 0x8000, v240
	v_add_u32_e32 v241, 0x8000, v241
	v_add_u32_e32 v242, 0x8000, v242
	v_add_u32_e32 v243, 0x8000, v243
	v_fmac_f32_e32 v238, v109, v109
	v_fmac_f32_e32 v238, v110, v110
	v_fmac_f32_e32 v238, v111, v111
	v_perm_b32 v230, v241, v240, s58
	v_perm_b32 v231, v243, v242, s58
	global_store_dwordx2 v[220:221], v[230:231], off
	v_pk_fma_f32 v[102:103], v[102:103], 0.5, v[214:215] op_sel_hi:[1,0,1]
	v_pk_fma_f32 v[100:101], v[100:101], 0.5, v[212:213] op_sel_hi:[1,0,1]
	global_store_dwordx4 v[236:237], v[100:103], off offset:512
	v_pk_mul_f32 v[244:245], v[84:85], v[100:101]
	v_pk_mul_f32 v[246:247], v[86:87], v[102:103]
	v_fmac_f32_e32 v238, v100, v100
	v_add_u32_e32 v244, 0x8000, v244
	v_add_u32_e32 v245, 0x8000, v245
	v_add_u32_e32 v246, 0x8000, v246
	v_add_u32_e32 v247, 0x8000, v247
	v_fmac_f32_e32 v238, v101, v101
	v_fmac_f32_e32 v238, v102, v102
	v_fmac_f32_e32 v238, v103, v103
	v_perm_b32 v232, v245, v244, s58
	v_perm_b32 v233, v247, v246, s58
	global_store_dwordx2 v[220:221], v[232:233], off offset:256
	s_nop 1
	v_mov_b32_dpp v228, v175 row_ror:8 row_mask:0xf bank_mask:0xf
	v_mov_b32_dpp v229, v238 row_ror:8 row_mask:0xf bank_mask:0xf
	v_add_f32_e32 v175, v175, v228
	v_add_f32_e32 v238, v238, v229
	v_cndmask_b32_e64 v175, v238, v175, s[34:35]
	s_nop 0
	ds_bpermute_b32 v228, v239, v175
	global_load_dwordx4 v[200:203], v[164:165], off
	global_load_dwordx4 v[204:207], v[164:165], off offset:512
	global_load_dwordx4 v[208:211], v[216:217], off
	global_load_dwordx4 v[212:215], v[216:217], off offset:512
	s_mov_b64 vcc, 0x20000
	v_lshl_add_u64 v[164:165], v[164:165], 0, vcc
	v_lshl_add_u64 v[216:217], v[216:217], 0, vcc
	s_mov_b64 vcc, 0x20000
	v_lshl_add_u64 v[234:235], v[234:235], 0, vcc
	v_lshl_add_u64 v[236:237], v[236:237], 0, vcc
	s_mov_b64 vcc, 0x10000
	v_lshl_add_u64 v[218:219], v[218:219], 0, vcc
	v_lshl_add_u64 v[220:221], v[220:221], 0, vcc
	s_waitcnt lgkmcnt(0)
	v_add_f32_e32 v175, v175, v228
	s_nop 0
	ds_bpermute_b32 v229, v248, v175
	s_waitcnt lgkmcnt(0)
;     __device__ __forceinline__ void operator()(const f32x4 (&acc)[2][2][4][2], const Unit& u, int wr, int wc, int fr, int fq) const {
;     ...
; #pragma unroll
;         for (int ai = 0; ai < 2; ++ai)
; #pragma unroll
;             for (int m = 0; m < 4; ++m) {
;                 const int row = row0 + ai * HALF + m * 16;
;                 const size_t off = (size_t)row * ldc + col0;
;                 float q = 0.f;
; #pragma unroll
;                 for (int bj = 0; bj < 2; ++bj)
; #pragma unroll
;                     for (int n = 0; n < 2; ++n) {
;                         const f32x4 rv = *(const f32x4*)(rbase + off + bj * HALF + n * 16);
;                         const f32x4 v = rv + acc[ai][bj][m][n] * scale;
;                         if (out) *(f32x4*)(out + off + bj * HALF + n * 16) = v;
;                         if (xn) { q += (v.x * v.x + v.y * v.y) + (v.z * v.z + v.w * v.w); const f32x4 o = v * wv[bj][n];
;                             u32x2 p; p.x = pk2(o.x, o.y); p.y = pk2(o.z, o.w); *(u32x2*)(xn + off + bj * HALF + n * 16) = p; }
;                     }
;                 if (xn) { q += __shfl_xor(q, 16); q += __shfl_xor(q, 32); if (fq == 0) (void)__hip_atomic_fetch_add(ss + row, q, __ATOMIC_RELAXED, __HIP_MEMORY_SCOPE_AGENT); }
;             }
	v_add_f32_e32 v175, v175, v229
	s_mov_b64 exec, s[0:1]
	global_atomic_add_f32 v[222:223], v175, off
	s_mov_b64 exec, -1
	s_mov_b64 vcc, 64
	v_lshl_add_u64 v[222:223], v[222:223], 0, vcc
	v_mov_b32_dpp v224, v88 row_ror:8 row_mask:0xf bank_mask:0xf
	v_mov_b32_dpp v225, v89 row_ror:8 row_mask:0xf bank_mask:0xf
	v_mov_b32_dpp v226, v90 row_ror:8 row_mask:0xf bank_mask:0xf
	v_mov_b32_dpp v227, v91 row_ror:8 row_mask:0xf bank_mask:0xf
	v_cndmask_b32_e64 v88, v224, v92, s[34:35]
	v_cndmask_b32_e64 v89, v225, v93, s[34:35]
	v_cndmask_b32_e64 v90, v226, v94, s[34:35]
	v_cndmask_b32_e64 v91, v227, v95, s[34:35]
	v_cndmask_b32_e64 v92, v92, v224, s[34:35]
	v_cndmask_b32_e64 v93, v93, v225, s[34:35]
	v_cndmask_b32_e64 v94, v94, v226, s[34:35]
	v_cndmask_b32_e64 v95, v95, v227, s[34:35]
	v_mov_b32_dpp v224, v68 row_ror:8 row_mask:0xf bank_mask:0xf
	v_mov_b32_dpp v225, v69 row_ror:8 row_mask:0xf bank_mask:0xf
	v_mov_b32_dpp v226, v70 row_ror:8 row_mask:0xf bank_mask:0xf
	v_mov_b32_dpp v227, v71 row_ror:8 row_mask:0xf bank_mask:0xf
	v_cndmask_b32_e64 v68, v224, v76, s[34:35]
	v_cndmask_b32_e64 v69, v225, v77, s[34:35]
	v_cndmask_b32_e64 v70, v226, v78, s[34:35]
	v_cndmask_b32_e64 v71, v227, v79, s[34:35]
	v_cndmask_b32_e64 v76, v76, v224, s[34:35]
	v_cndmask_b32_e64 v77, v77, v225, s[34:35]
	v_cndmask_b32_e64 v78, v78, v226, s[34:35]
	v_cndmask_b32_e64 v79, v79, v227, s[34:35]
	s_waitcnt vmcnt(27)
	v_pk_fma_f32 v[90:91], v[90:91], 0.5, v[158:159] op_sel_hi:[1,0,1]
	v_pk_fma_f32 v[88:89], v[88:89], 0.5, v[156:157] op_sel_hi:[1,0,1]
	global_store_dwordx4 v[234:235], v[88:91], off
	v_pk_mul_f32 v[240:241], v[64:65], v[88:89]
	v_pk_mul_f32 v[242:243], v[66:67], v[90:91]
	v_mul_f32_e32 v175, v88, v88
	v_add_u32_e32 v240, 0x8000, v240
	v_add_u32_e32 v241, 0x8000, v241
	v_add_u32_e32 v242, 0x8000, v242
	v_add_u32_e32 v243, 0x8000, v243
	v_fmac_f32_e32 v175, v89, v89
	v_fmac_f32_e32 v175, v90, v90
	v_fmac_f32_e32 v175, v91, v91
	v_perm_b32 v230, v241, v240, s58
	v_perm_b32 v231, v243, v242, s58
	global_store_dwordx2 v[218:219], v[230:231], off
	v_pk_fma_f32 v[70:71], v[70:71], 0.5, v[162:163] op_sel_hi:[1,0,1]
	v_pk_fma_f32 v[68:69], v[68:69], 0.5, v[160:161] op_sel_hi:[1,0,1]
	global_store_dwordx4 v[234:235], v[68:71], off offset:512
	v_pk_mul_f32 v[244:245], v[72:73], v[68:69]
	v_pk_mul_f32 v[246:247], v[74:75], v[70:71]
	v_fmac_f32_e32 v175, v68, v68
	v_add_u32_e32 v244, 0x8000, v244
	v_add_u32_e32 v245, 0x8000, v245
	v_add_u32_e32 v246, 0x8000, v246
	v_add_u32_e32 v247, 0x8000, v247
	v_fmac_f32_e32 v175, v69, v69
	v_fmac_f32_e32 v175, v70, v70
	v_fmac_f32_e32 v175, v71, v71
	v_perm_b32 v232, v245, v244, s58
	v_perm_b32 v233, v247, v246, s58
	global_store_dwordx2 v[218:219], v[232:233], off offset:256
	v_pk_fma_f32 v[94:95], v[94:95], 0.5, v[178:179] op_sel_hi:[1,0,1]
	v_pk_fma_f32 v[92:93], v[92:93], 0.5, v[176:177] op_sel_hi:[1,0,1]
	global_store_dwordx4 v[236:237], v[92:95], off
	v_pk_mul_f32 v[240:241], v[80:81], v[92:93]
	v_pk_mul_f32 v[242:243], v[82:83], v[94:95]
	v_mul_f32_e32 v238, v92, v92
	v_add_u32_e32 v240, 0x8000, v240
	v_add_u32_e32 v241, 0x8000, v241
	v_add_u32_e32 v242, 0x8000, v242
	v_add_u32_e32 v243, 0x8000, v243
	v_fmac_f32_e32 v238, v93, v93
	v_fmac_f32_e32 v238, v94, v94
	v_fmac_f32_e32 v238, v95, v95
	v_perm_b32 v230, v241, v240, s58
	v_perm_b32 v231, v243, v242, s58
	global_store_dwordx2 v[220:221], v[230:231], off
	v_pk_fma_f32 v[78:79], v[78:79], 0.5, v[182:183] op_sel_hi:[1,0,1]
	v_pk_fma_f32 v[76:77], v[76:77], 0.5, v[180:181] op_sel_hi:[1,0,1]
	global_store_dwordx4 v[236:237], v[76:79], off offset:512
	v_pk_mul_f32 v[244:245], v[84:85], v[76:77]
	v_pk_mul_f32 v[246:247], v[86:87], v[78:79]
	v_fmac_f32_e32 v238, v76, v76
	v_add_u32_e32 v244, 0x8000, v244
	v_add_u32_e32 v245, 0x8000, v245
	v_add_u32_e32 v246, 0x8000, v246
	v_add_u32_e32 v247, 0x8000, v247
	v_fmac_f32_e32 v238, v77, v77
	v_fmac_f32_e32 v238, v78, v78
	v_fmac_f32_e32 v238, v79, v79
	v_perm_b32 v232, v245, v244, s58
	v_perm_b32 v233, v247, v246, s58
	global_store_dwordx2 v[220:221], v[232:233], off offset:256
	s_nop 1
	v_mov_b32_dpp v228, v175 row_ror:8 row_mask:0xf bank_mask:0xf
	v_mov_b32_dpp v229, v238 row_ror:8 row_mask:0xf bank_mask:0xf
	v_add_f32_e32 v175, v175, v228
	v_add_f32_e32 v238, v238, v229
	v_cndmask_b32_e64 v175, v238, v175, s[34:35]
	s_nop 0
	ds_bpermute_b32 v228, v239, v175
	global_load_dwordx4 v[156:159], v[164:165], off
	global_load_dwordx4 v[160:163], v[164:165], off offset:512
	global_load_dwordx4 v[176:179], v[216:217], off
	global_load_dwordx4 v[180:183], v[216:217], off offset:512
	s_mov_b64 vcc, 0x20000
	v_lshl_add_u64 v[164:165], v[164:165], 0, vcc
	v_lshl_add_u64 v[216:217], v[216:217], 0, vcc
	s_mov_b64 vcc, 0xa0000
	v_lshl_add_u64 v[234:235], v[234:235], 0, vcc
	v_lshl_add_u64 v[236:237], v[236:237], 0, vcc
	s_mov_b64 vcc, 0x50000
	v_lshl_add_u64 v[218:219], v[218:219], 0, vcc
	v_lshl_add_u64 v[220:221], v[220:221], 0, vcc
	s_waitcnt lgkmcnt(0)
	v_add_f32_e32 v175, v175, v228
	s_nop 0
	ds_bpermute_b32 v229, v248, v175
	s_waitcnt lgkmcnt(0)
;     __device__ __forceinline__ void operator()(const f32x4 (&acc)[2][2][4][2], const Unit& u, int wr, int wc, int fr, int fq) const {
;     ...
; #pragma unroll
;         for (int ai = 0; ai < 2; ++ai)
; #pragma unroll
;             for (int m = 0; m < 4; ++m) {
;                 const int row = row0 + ai * HALF + m * 16;
;                 const size_t off = (size_t)row * ldc + col0;
;                 float q = 0.f;
; #pragma unroll
;                 for (int bj = 0; bj < 2; ++bj)
; #pragma unroll
;                     for (int n = 0; n < 2; ++n) {
;                         const f32x4 rv = *(const f32x4*)(rbase + off + bj * HALF + n * 16);
;                         const f32x4 v = rv + acc[ai][bj][m][n] * scale;
;                         if (out) *(f32x4*)(out + off + bj * HALF + n * 16) = v;
;                         if (xn) { q += (v.x * v.x + v.y * v.y) + (v.z * v.z + v.w * v.w); const f32x4 o = v * wv[bj][n];
;                             u32x2 p; p.x = pk2(o.x, o.y); p.y = pk2(o.z, o.w); *(u32x2*)(xn + off + bj * HALF + n * 16) = p; }
;                     }
;                 if (xn) { q += __shfl_xor(q, 16); q += __shfl_xor(q, 32); if (fq == 0) (void)__hip_atomic_fetch_add(ss + row, q, __ATOMIC_RELAXED, __HIP_MEMORY_SCOPE_AGENT); }
;             }
	v_add_f32_e32 v175, v175, v229
	s_mov_b64 exec, s[0:1]
	global_atomic_add_f32 v[222:223], v175, off
	s_mov_b64 exec, -1
	s_mov_b64 vcc, 320
	v_lshl_add_u64 v[222:223], v[222:223], 0, vcc
	v_mov_b32_dpp v224, v56 row_ror:8 row_mask:0xf bank_mask:0xf
	v_mov_b32_dpp v225, v57 row_ror:8 row_mask:0xf bank_mask:0xf
	v_mov_b32_dpp v226, v58 row_ror:8 row_mask:0xf bank_mask:0xf
	v_mov_b32_dpp v227, v59 row_ror:8 row_mask:0xf bank_mask:0xf
	v_cndmask_b32_e64 v56, v224, v60, s[34:35]
	v_cndmask_b32_e64 v57, v225, v61, s[34:35]
	v_cndmask_b32_e64 v58, v226, v62, s[34:35]
	v_cndmask_b32_e64 v59, v227, v63, s[34:35]
	v_cndmask_b32_e64 v60, v60, v224, s[34:35]
	v_cndmask_b32_e64 v61, v61, v225, s[34:35]
	v_cndmask_b32_e64 v62, v62, v226, s[34:35]
	v_cndmask_b32_e64 v63, v63, v227, s[34:35]
	v_mov_b32_dpp v224, v48 row_ror:8 row_mask:0xf bank_mask:0xf
	v_mov_b32_dpp v225, v49 row_ror:8 row_mask:0xf bank_mask:0xf
	v_mov_b32_dpp v226, v50 row_ror:8 row_mask:0xf bank_mask:0xf
	v_mov_b32_dpp v227, v51 row_ror:8 row_mask:0xf bank_mask:0xf
	v_cndmask_b32_e64 v48, v224, v52, s[34:35]
	v_cndmask_b32_e64 v49, v225, v53, s[34:35]
	v_cndmask_b32_e64 v50, v226, v54, s[34:35]
	v_cndmask_b32_e64 v51, v227, v55, s[34:35]
	v_cndmask_b32_e64 v52, v52, v224, s[34:35]
	v_cndmask_b32_e64 v53, v53, v225, s[34:35]
	v_cndmask_b32_e64 v54, v54, v226, s[34:35]
	v_cndmask_b32_e64 v55, v55, v227, s[34:35]
	s_waitcnt vmcnt(27)
	v_pk_fma_f32 v[58:59], v[58:59], 0.5, v[186:187] op_sel_hi:[1,0,1]
	v_pk_fma_f32 v[56:57], v[56:57], 0.5, v[184:185] op_sel_hi:[1,0,1]
	global_store_dwordx4 v[234:235], v[56:59], off
	v_pk_mul_f32 v[240:241], v[64:65], v[56:57]
	v_pk_mul_f32 v[242:243], v[66:67], v[58:59]
	v_mul_f32_e32 v175, v56, v56
	v_add_u32_e32 v240, 0x8000, v240
	v_add_u32_e32 v241, 0x8000, v241
	v_add_u32_e32 v242, 0x8000, v242
	v_add_u32_e32 v243, 0x8000, v243
	v_fmac_f32_e32 v175, v57, v57
	v_fmac_f32_e32 v175, v58, v58
	v_fmac_f32_e32 v175, v59, v59
	v_perm_b32 v230, v241, v240, s58
	v_perm_b32 v231, v243, v242, s58
	global_store_dwordx2 v[218:219], v[230:231], off
	v_pk_fma_f32 v[50:51], v[50:51], 0.5, v[190:191] op_sel_hi:[1,0,1]
	v_pk_fma_f32 v[48:49], v[48:49], 0.5, v[188:189] op_sel_hi:[1,0,1]
	global_store_dwordx4 v[234:235], v[48:51], off offset:512
	v_pk_mul_f32 v[244:245], v[72:73], v[48:49]
	v_pk_mul_f32 v[246:247], v[74:75], v[50:51]
	v_fmac_f32_e32 v175, v48, v48
	v_add_u32_e32 v244, 0x8000, v244
	v_add_u32_e32 v245, 0x8000, v245
	v_add_u32_e32 v246, 0x8000, v246
	v_add_u32_e32 v247, 0x8000, v247
	v_fmac_f32_e32 v175, v49, v49
	v_fmac_f32_e32 v175, v50, v50
	v_fmac_f32_e32 v175, v51, v51
	v_perm_b32 v232, v245, v244, s58
	v_perm_b32 v233, v247, v246, s58
	global_store_dwordx2 v[218:219], v[232:233], off offset:256
	v_pk_fma_f32 v[62:63], v[62:63], 0.5, v[194:195] op_sel_hi:[1,0,1]
	v_pk_fma_f32 v[60:61], v[60:61], 0.5, v[192:193] op_sel_hi:[1,0,1]
	global_store_dwordx4 v[236:237], v[60:63], off
	v_pk_mul_f32 v[240:241], v[80:81], v[60:61]
	v_pk_mul_f32 v[242:243], v[82:83], v[62:63]
	v_mul_f32_e32 v238, v60, v60
	v_add_u32_e32 v240, 0x8000, v240
	v_add_u32_e32 v241, 0x8000, v241
	v_add_u32_e32 v242, 0x8000, v242
	v_add_u32_e32 v243, 0x8000, v243
	v_fmac_f32_e32 v238, v61, v61
	v_fmac_f32_e32 v238, v62, v62
	v_fmac_f32_e32 v238, v63, v63
	v_perm_b32 v230, v241, v240, s58
	v_perm_b32 v231, v243, v242, s58
	global_store_dwordx2 v[220:221], v[230:231], off
	v_pk_fma_f32 v[54:55], v[54:55], 0.5, v[198:199] op_sel_hi:[1,0,1]
	v_pk_fma_f32 v[52:53], v[52:53], 0.5, v[196:197] op_sel_hi:[1,0,1]
	global_store_dwordx4 v[236:237], v[52:55], off offset:512
	v_pk_mul_f32 v[244:245], v[84:85], v[52:53]
	v_pk_mul_f32 v[246:247], v[86:87], v[54:55]
	v_fmac_f32_e32 v238, v52, v52
	v_add_u32_e32 v244, 0x8000, v244
	v_add_u32_e32 v245, 0x8000, v245
	v_add_u32_e32 v246, 0x8000, v246
	v_add_u32_e32 v247, 0x8000, v247
	v_fmac_f32_e32 v238, v53, v53
	v_fmac_f32_e32 v238, v54, v54
	v_fmac_f32_e32 v238, v55, v55
	v_perm_b32 v232, v245, v244, s58
	v_perm_b32 v233, v247, v246, s58
	global_store_dwordx2 v[220:221], v[232:233], off offset:256
	s_nop 1
	v_mov_b32_dpp v228, v175 row_ror:8 row_mask:0xf bank_mask:0xf
	v_mov_b32_dpp v229, v238 row_ror:8 row_mask:0xf bank_mask:0xf
	v_add_f32_e32 v175, v175, v228
	v_add_f32_e32 v238, v238, v229
	v_cndmask_b32_e64 v175, v238, v175, s[34:35]
	s_nop 0
	ds_bpermute_b32 v228, v239, v175
	global_load_dwordx4 v[184:187], v[164:165], off
	global_load_dwordx4 v[188:191], v[164:165], off offset:512
	global_load_dwordx4 v[192:195], v[216:217], off
	global_load_dwordx4 v[196:199], v[216:217], off offset:512
	s_mov_b64 vcc, 0x20000
	v_lshl_add_u64 v[234:235], v[234:235], 0, vcc
	v_lshl_add_u64 v[236:237], v[236:237], 0, vcc
	s_mov_b64 vcc, 0x10000
	v_lshl_add_u64 v[218:219], v[218:219], 0, vcc
	v_lshl_add_u64 v[220:221], v[220:221], 0, vcc
	s_waitcnt lgkmcnt(0)
	v_add_f32_e32 v175, v175, v228
	s_nop 0
	ds_bpermute_b32 v229, v248, v175
	s_waitcnt lgkmcnt(0)
	v_add_f32_e32 v175, v175, v229
	s_mov_b64 exec, s[0:1]
	global_atomic_add_f32 v[222:223], v175, off
	s_mov_b64 exec, -1
	s_mov_b64 vcc, 64
	v_lshl_add_u64 v[222:223], v[222:223], 0, vcc
	v_mov_b32_dpp v224, v40 row_ror:8 row_mask:0xf bank_mask:0xf
	v_mov_b32_dpp v225, v41 row_ror:8 row_mask:0xf bank_mask:0xf
	v_mov_b32_dpp v226, v42 row_ror:8 row_mask:0xf bank_mask:0xf
	v_mov_b32_dpp v227, v43 row_ror:8 row_mask:0xf bank_mask:0xf
	v_cndmask_b32_e64 v40, v224, v44, s[34:35]
	v_cndmask_b32_e64 v41, v225, v45, s[34:35]
	v_cndmask_b32_e64 v42, v226, v46, s[34:35]
	v_cndmask_b32_e64 v43, v227, v47, s[34:35]
	v_cndmask_b32_e64 v44, v44, v224, s[34:35]
	v_cndmask_b32_e64 v45, v45, v225, s[34:35]
	v_cndmask_b32_e64 v46, v46, v226, s[34:35]
	v_cndmask_b32_e64 v47, v47, v227, s[34:35]
	v_mov_b32_dpp v224, v32 row_ror:8 row_mask:0xf bank_mask:0xf
	v_mov_b32_dpp v225, v33 row_ror:8 row_mask:0xf bank_mask:0xf
	v_mov_b32_dpp v226, v34 row_ror:8 row_mask:0xf bank_mask:0xf
	v_mov_b32_dpp v227, v35 row_ror:8 row_mask:0xf bank_mask:0xf
	v_cndmask_b32_e64 v32, v224, v36, s[34:35]
	v_cndmask_b32_e64 v33, v225, v37, s[34:35]
	v_cndmask_b32_e64 v34, v226, v38, s[34:35]
	v_cndmask_b32_e64 v35, v227, v39, s[34:35]
	v_cndmask_b32_e64 v36, v36, v224, s[34:35]
	v_cndmask_b32_e64 v37, v37, v225, s[34:35]
	v_cndmask_b32_e64 v38, v38, v226, s[34:35]
	v_cndmask_b32_e64 v39, v39, v227, s[34:35]
	s_waitcnt vmcnt(27)
;     __device__ __forceinline__ void operator()(const f32x4 (&acc)[2][2][4][2], const Unit& u, int wr, int wc, int fr, int fq) const {
;     ...
; #pragma unroll
;         for (int ai = 0; ai < 2; ++ai)
; #pragma unroll
;             for (int m = 0; m < 4; ++m) {
;                 const int row = row0 + ai * HALF + m * 16;
;                 const size_t off = (size_t)row * ldc + col0;
;                 float q = 0.f;
; #pragma unroll
;                 for (int bj = 0; bj < 2; ++bj)
; #pragma unroll
;                     for (int n = 0; n < 2; ++n) {
;                         const f32x4 rv = *(const f32x4*)(rbase + off + bj * HALF + n * 16);
;                         const f32x4 v = rv + acc[ai][bj][m][n] * scale;
;                         if (out) *(f32x4*)(out + off + bj * HALF + n * 16) = v;
;                         if (xn) { q += (v.x * v.x + v.y * v.y) + (v.z * v.z + v.w * v.w); const f32x4 o = v * wv[bj][n];
;                             u32x2 p; p.x = pk2(o.x, o.y); p.y = pk2(o.z, o.w); *(u32x2*)(xn + off + bj * HALF + n * 16) = p; }
;                     }
;                 if (xn) { q += __shfl_xor(q, 16); q += __shfl_xor(q, 32); if (fq == 0) (void)__hip_atomic_fetch_add(ss + row, q, __ATOMIC_RELAXED, __HIP_MEMORY_SCOPE_AGENT); }
;             }
	v_pk_fma_f32 v[42:43], v[42:43], 0.5, v[202:203] op_sel_hi:[1,0,1]
	v_pk_fma_f32 v[40:41], v[40:41], 0.5, v[200:201] op_sel_hi:[1,0,1]
	global_store_dwordx4 v[234:235], v[40:43], off
	v_pk_mul_f32 v[240:241], v[64:65], v[40:41]
	v_pk_mul_f32 v[242:243], v[66:67], v[42:43]
	v_mul_f32_e32 v175, v40, v40
	v_add_u32_e32 v240, 0x8000, v240
	v_add_u32_e32 v241, 0x8000, v241
	v_add_u32_e32 v242, 0x8000, v242
	v_add_u32_e32 v243, 0x8000, v243
	v_fmac_f32_e32 v175, v41, v41
	v_fmac_f32_e32 v175, v42, v42
	v_fmac_f32_e32 v175, v43, v43
	v_perm_b32 v230, v241, v240, s58
	v_perm_b32 v231, v243, v242, s58
	global_store_dwordx2 v[218:219], v[230:231], off
	v_pk_fma_f32 v[34:35], v[34:35], 0.5, v[206:207] op_sel_hi:[1,0,1]
	v_pk_fma_f32 v[32:33], v[32:33], 0.5, v[204:205] op_sel_hi:[1,0,1]
	global_store_dwordx4 v[234:235], v[32:35], off offset:512
	v_pk_mul_f32 v[244:245], v[72:73], v[32:33]
	v_pk_mul_f32 v[246:247], v[74:75], v[34:35]
	v_fmac_f32_e32 v175, v32, v32
	v_add_u32_e32 v244, 0x8000, v244
	v_add_u32_e32 v245, 0x8000, v245
	v_add_u32_e32 v246, 0x8000, v246
	v_add_u32_e32 v247, 0x8000, v247
	v_fmac_f32_e32 v175, v33, v33
	v_fmac_f32_e32 v175, v34, v34
	v_fmac_f32_e32 v175, v35, v35
	v_perm_b32 v232, v245, v244, s58
	v_perm_b32 v233, v247, v246, s58
	global_store_dwordx2 v[218:219], v[232:233], off offset:256
	v_pk_fma_f32 v[46:47], v[46:47], 0.5, v[210:211] op_sel_hi:[1,0,1]
	v_pk_fma_f32 v[44:45], v[44:45], 0.5, v[208:209] op_sel_hi:[1,0,1]
	global_store_dwordx4 v[236:237], v[44:47], off
	v_pk_mul_f32 v[240:241], v[80:81], v[44:45]
	v_pk_mul_f32 v[242:243], v[82:83], v[46:47]
	v_mul_f32_e32 v238, v44, v44
	v_add_u32_e32 v240, 0x8000, v240
	v_add_u32_e32 v241, 0x8000, v241
	v_add_u32_e32 v242, 0x8000, v242
	v_add_u32_e32 v243, 0x8000, v243
	v_fmac_f32_e32 v238, v45, v45
	v_fmac_f32_e32 v238, v46, v46
	v_fmac_f32_e32 v238, v47, v47
	v_perm_b32 v230, v241, v240, s58
	v_perm_b32 v231, v243, v242, s58
	global_store_dwordx2 v[220:221], v[230:231], off
	v_pk_fma_f32 v[38:39], v[38:39], 0.5, v[214:215] op_sel_hi:[1,0,1]
	v_pk_fma_f32 v[36:37], v[36:37], 0.5, v[212:213] op_sel_hi:[1,0,1]
	global_store_dwordx4 v[236:237], v[36:39], off offset:512
	v_pk_mul_f32 v[244:245], v[84:85], v[36:37]
	v_pk_mul_f32 v[246:247], v[86:87], v[38:39]
	v_fmac_f32_e32 v238, v36, v36
	v_add_u32_e32 v244, 0x8000, v244
	v_add_u32_e32 v245, 0x8000, v245
	v_add_u32_e32 v246, 0x8000, v246
	v_add_u32_e32 v247, 0x8000, v247
	v_fmac_f32_e32 v238, v37, v37
	v_fmac_f32_e32 v238, v38, v38
	v_fmac_f32_e32 v238, v39, v39
	v_perm_b32 v232, v245, v244, s58
	v_perm_b32 v233, v247, v246, s58
	global_store_dwordx2 v[220:221], v[232:233], off offset:256
	s_nop 1
	v_mov_b32_dpp v228, v175 row_ror:8 row_mask:0xf bank_mask:0xf
	v_mov_b32_dpp v229, v238 row_ror:8 row_mask:0xf bank_mask:0xf
	v_add_f32_e32 v175, v175, v228
	v_add_f32_e32 v238, v238, v229
	v_cndmask_b32_e64 v175, v238, v175, s[34:35]
	s_nop 0
	ds_bpermute_b32 v228, v239, v175
	s_mov_b64 vcc, 0x20000
	v_lshl_add_u64 v[234:235], v[234:235], 0, vcc
	v_lshl_add_u64 v[236:237], v[236:237], 0, vcc
	s_mov_b64 vcc, 0x10000
	v_lshl_add_u64 v[218:219], v[218:219], 0, vcc
	v_lshl_add_u64 v[220:221], v[220:221], 0, vcc
	s_waitcnt lgkmcnt(0)
	v_add_f32_e32 v175, v175, v228
	s_nop 0
	ds_bpermute_b32 v229, v248, v175
	s_waitcnt lgkmcnt(0)
	v_add_f32_e32 v175, v175, v229
	s_mov_b64 exec, s[0:1]
	global_atomic_add_f32 v[222:223], v175, off
	s_mov_b64 exec, -1
	s_mov_b64 vcc, 64
	v_lshl_add_u64 v[222:223], v[222:223], 0, vcc
	v_mov_b32_dpp v224, v24 row_ror:8 row_mask:0xf bank_mask:0xf
	v_mov_b32_dpp v225, v25 row_ror:8 row_mask:0xf bank_mask:0xf
	v_mov_b32_dpp v226, v26 row_ror:8 row_mask:0xf bank_mask:0xf
	v_mov_b32_dpp v227, v27 row_ror:8 row_mask:0xf bank_mask:0xf
	v_cndmask_b32_e64 v24, v224, v28, s[34:35]
	v_cndmask_b32_e64 v25, v225, v29, s[34:35]
	v_cndmask_b32_e64 v26, v226, v30, s[34:35]
	v_cndmask_b32_e64 v27, v227, v31, s[34:35]
	v_cndmask_b32_e64 v28, v28, v224, s[34:35]
	v_cndmask_b32_e64 v29, v29, v225, s[34:35]
	v_cndmask_b32_e64 v30, v30, v226, s[34:35]
	v_cndmask_b32_e64 v31, v31, v227, s[34:35]
	v_mov_b32_dpp v224, v16 row_ror:8 row_mask:0xf bank_mask:0xf
	v_mov_b32_dpp v225, v17 row_ror:8 row_mask:0xf bank_mask:0xf
	v_mov_b32_dpp v226, v18 row_ror:8 row_mask:0xf bank_mask:0xf
	v_mov_b32_dpp v227, v19 row_ror:8 row_mask:0xf bank_mask:0xf
	v_cndmask_b32_e64 v16, v224, v20, s[34:35]
	v_cndmask_b32_e64 v17, v225, v21, s[34:35]
	v_cndmask_b32_e64 v18, v226, v22, s[34:35]
	v_cndmask_b32_e64 v19, v227, v23, s[34:35]
	v_cndmask_b32_e64 v20, v20, v224, s[34:35]
	v_cndmask_b32_e64 v21, v21, v225, s[34:35]
	v_cndmask_b32_e64 v22, v22, v226, s[34:35]
	v_cndmask_b32_e64 v23, v23, v227, s[34:35]
	s_waitcnt vmcnt(23)
;     __device__ __forceinline__ void operator()(const f32x4 (&acc)[2][2][4][2], const Unit& u, int wr, int wc, int fr, int fq) const {
;     ...
; #pragma unroll
;         for (int ai = 0; ai < 2; ++ai)
; #pragma unroll
;             for (int m = 0; m < 4; ++m) {
;                 const int row = row0 + ai * HALF + m * 16;
;                 const size_t off = (size_t)row * ldc + col0;
;                 float q = 0.f;
; #pragma unroll
;                 for (int bj = 0; bj < 2; ++bj)
; #pragma unroll
;                     for (int n = 0; n < 2; ++n) {
;                         const f32x4 rv = *(const f32x4*)(rbase + off + bj * HALF + n * 16);
;                         const f32x4 v = rv + acc[ai][bj][m][n] * scale;
;                         if (out) *(f32x4*)(out + off + bj * HALF + n * 16) = v;
;                         if (xn) { q += (v.x * v.x + v.y * v.y) + (v.z * v.z + v.w * v.w); const f32x4 o = v * wv[bj][n];
;                             u32x2 p; p.x = pk2(o.x, o.y); p.y = pk2(o.z, o.w); *(u32x2*)(xn + off + bj * HALF + n * 16) = p; }
;                     }
;                 if (xn) { q += __shfl_xor(q, 16); q += __shfl_xor(q, 32); if (fq == 0) (void)__hip_atomic_fetch_add(ss + row, q, __ATOMIC_RELAXED, __HIP_MEMORY_SCOPE_AGENT); }
;             }
	v_pk_fma_f32 v[26:27], v[26:27], 0.5, v[158:159] op_sel_hi:[1,0,1]
	v_pk_fma_f32 v[24:25], v[24:25], 0.5, v[156:157] op_sel_hi:[1,0,1]
	global_store_dwordx4 v[234:235], v[24:27], off
	v_pk_mul_f32 v[240:241], v[64:65], v[24:25]
	v_pk_mul_f32 v[242:243], v[66:67], v[26:27]
	v_mul_f32_e32 v175, v24, v24
	v_add_u32_e32 v240, 0x8000, v240
	v_add_u32_e32 v241, 0x8000, v241
	v_add_u32_e32 v242, 0x8000, v242
	v_add_u32_e32 v243, 0x8000, v243
	v_fmac_f32_e32 v175, v25, v25
	v_fmac_f32_e32 v175, v26, v26
	v_fmac_f32_e32 v175, v27, v27
	v_perm_b32 v230, v241, v240, s58
	v_perm_b32 v231, v243, v242, s58
	global_store_dwordx2 v[218:219], v[230:231], off
	v_pk_fma_f32 v[18:19], v[18:19], 0.5, v[162:163] op_sel_hi:[1,0,1]
	v_pk_fma_f32 v[16:17], v[16:17], 0.5, v[160:161] op_sel_hi:[1,0,1]
	global_store_dwordx4 v[234:235], v[16:19], off offset:512
	v_pk_mul_f32 v[244:245], v[72:73], v[16:17]
	v_pk_mul_f32 v[246:247], v[74:75], v[18:19]
	v_fmac_f32_e32 v175, v16, v16
	v_add_u32_e32 v244, 0x8000, v244
	v_add_u32_e32 v245, 0x8000, v245
	v_add_u32_e32 v246, 0x8000, v246
	v_add_u32_e32 v247, 0x8000, v247
	v_fmac_f32_e32 v175, v17, v17
	v_fmac_f32_e32 v175, v18, v18
	v_fmac_f32_e32 v175, v19, v19
	v_perm_b32 v232, v245, v244, s58
	v_perm_b32 v233, v247, v246, s58
	global_store_dwordx2 v[218:219], v[232:233], off offset:256
	v_pk_fma_f32 v[30:31], v[30:31], 0.5, v[178:179] op_sel_hi:[1,0,1]
	v_pk_fma_f32 v[28:29], v[28:29], 0.5, v[176:177] op_sel_hi:[1,0,1]
	global_store_dwordx4 v[236:237], v[28:31], off
	v_pk_mul_f32 v[240:241], v[80:81], v[28:29]
	v_pk_mul_f32 v[242:243], v[82:83], v[30:31]
	v_mul_f32_e32 v238, v28, v28
	v_add_u32_e32 v240, 0x8000, v240
	v_add_u32_e32 v241, 0x8000, v241
	v_add_u32_e32 v242, 0x8000, v242
	v_add_u32_e32 v243, 0x8000, v243
	v_fmac_f32_e32 v238, v29, v29
	v_fmac_f32_e32 v238, v30, v30
	v_fmac_f32_e32 v238, v31, v31
	v_perm_b32 v230, v241, v240, s58
	v_perm_b32 v231, v243, v242, s58
	global_store_dwordx2 v[220:221], v[230:231], off
	v_pk_fma_f32 v[22:23], v[22:23], 0.5, v[182:183] op_sel_hi:[1,0,1]
	v_pk_fma_f32 v[20:21], v[20:21], 0.5, v[180:181] op_sel_hi:[1,0,1]
	global_store_dwordx4 v[236:237], v[20:23], off offset:512
	v_pk_mul_f32 v[244:245], v[84:85], v[20:21]
	v_pk_mul_f32 v[246:247], v[86:87], v[22:23]
	v_fmac_f32_e32 v238, v20, v20
	v_add_u32_e32 v244, 0x8000, v244
	v_add_u32_e32 v245, 0x8000, v245
	v_add_u32_e32 v246, 0x8000, v246
	v_add_u32_e32 v247, 0x8000, v247
	v_fmac_f32_e32 v238, v21, v21
	v_fmac_f32_e32 v238, v22, v22
	v_fmac_f32_e32 v238, v23, v23
	v_perm_b32 v232, v245, v244, s58
	v_perm_b32 v233, v247, v246, s58
	global_store_dwordx2 v[220:221], v[232:233], off offset:256
	s_nop 1
	v_mov_b32_dpp v228, v175 row_ror:8 row_mask:0xf bank_mask:0xf
	v_mov_b32_dpp v229, v238 row_ror:8 row_mask:0xf bank_mask:0xf
	v_add_f32_e32 v175, v175, v228
	v_add_f32_e32 v238, v238, v229
	v_cndmask_b32_e64 v175, v238, v175, s[34:35]
	s_nop 0
	ds_bpermute_b32 v228, v239, v175
	s_mov_b64 vcc, 0x20000
	v_lshl_add_u64 v[234:235], v[234:235], 0, vcc
	v_lshl_add_u64 v[236:237], v[236:237], 0, vcc
	s_mov_b64 vcc, 0x10000
	v_lshl_add_u64 v[218:219], v[218:219], 0, vcc
	v_lshl_add_u64 v[220:221], v[220:221], 0, vcc
	s_waitcnt lgkmcnt(0)
	v_add_f32_e32 v175, v175, v228
	s_nop 0
	ds_bpermute_b32 v229, v248, v175
	s_waitcnt lgkmcnt(0)
;     __device__ __forceinline__ void operator()(const f32x4 (&acc)[2][2][4][2], const Unit& u, int wr, int wc, int fr, int fq) const {
;     ...
; #pragma unroll
;         for (int ai = 0; ai < 2; ++ai)
; #pragma unroll
;             for (int m = 0; m < 4; ++m) {
;                 const int row = row0 + ai * HALF + m * 16;
;                 const size_t off = (size_t)row * ldc + col0;
;                 float q = 0.f;
; #pragma unroll
;                 for (int bj = 0; bj < 2; ++bj)
; #pragma unroll
;                     for (int n = 0; n < 2; ++n) {
;                         const f32x4 rv = *(const f32x4*)(rbase + off + bj * HALF + n * 16);
;                         const f32x4 v = rv + acc[ai][bj][m][n] * scale;
;                         if (out) *(f32x4*)(out + off + bj * HALF + n * 16) = v;
;                         if (xn) { q += (v.x * v.x + v.y * v.y) + (v.z * v.z + v.w * v.w); const f32x4 o = v * wv[bj][n];
;                             u32x2 p; p.x = pk2(o.x, o.y); p.y = pk2(o.z, o.w); *(u32x2*)(xn + off + bj * HALF + n * 16) = p; }
;                     }
;                 if (xn) { q += __shfl_xor(q, 16); q += __shfl_xor(q, 32); if (fq == 0) (void)__hip_atomic_fetch_add(ss + row, q, __ATOMIC_RELAXED, __HIP_MEMORY_SCOPE_AGENT); }
;             }
	v_add_f32_e32 v175, v175, v229
	s_mov_b64 exec, s[0:1]
	global_atomic_add_f32 v[222:223], v175, off
	s_mov_b64 exec, -1
	s_mov_b64 vcc, 64
	v_lshl_add_u64 v[222:223], v[222:223], 0, vcc
	v_mov_b32_dpp v224, v8 row_ror:8 row_mask:0xf bank_mask:0xf
	v_mov_b32_dpp v225, v9 row_ror:8 row_mask:0xf bank_mask:0xf
	v_mov_b32_dpp v226, v10 row_ror:8 row_mask:0xf bank_mask:0xf
	v_mov_b32_dpp v227, v11 row_ror:8 row_mask:0xf bank_mask:0xf
	v_cndmask_b32_e64 v8, v224, v12, s[34:35]
	v_cndmask_b32_e64 v9, v225, v13, s[34:35]
	v_cndmask_b32_e64 v10, v226, v14, s[34:35]
	v_cndmask_b32_e64 v11, v227, v15, s[34:35]
	v_cndmask_b32_e64 v12, v12, v224, s[34:35]
	v_cndmask_b32_e64 v13, v13, v225, s[34:35]
	v_cndmask_b32_e64 v14, v14, v226, s[34:35]
	v_cndmask_b32_e64 v15, v15, v227, s[34:35]
	v_mov_b32_dpp v224, v0 row_ror:8 row_mask:0xf bank_mask:0xf
	v_mov_b32_dpp v225, v1 row_ror:8 row_mask:0xf bank_mask:0xf
	v_mov_b32_dpp v226, v2 row_ror:8 row_mask:0xf bank_mask:0xf
	v_mov_b32_dpp v227, v3 row_ror:8 row_mask:0xf bank_mask:0xf
	v_cndmask_b32_e64 v0, v224, v4, s[34:35]
	v_cndmask_b32_e64 v1, v225, v5, s[34:35]
	v_cndmask_b32_e64 v2, v226, v6, s[34:35]
	v_cndmask_b32_e64 v3, v227, v7, s[34:35]
	v_cndmask_b32_e64 v4, v4, v224, s[34:35]
	v_cndmask_b32_e64 v5, v5, v225, s[34:35]
	v_cndmask_b32_e64 v6, v6, v226, s[34:35]
	v_cndmask_b32_e64 v7, v7, v227, s[34:35]
	s_waitcnt vmcnt(19)
	v_pk_fma_f32 v[10:11], v[10:11], 0.5, v[186:187] op_sel_hi:[1,0,1]
	v_pk_fma_f32 v[8:9], v[8:9], 0.5, v[184:185] op_sel_hi:[1,0,1]
	global_store_dwordx4 v[234:235], v[8:11], off
	v_pk_mul_f32 v[240:241], v[64:65], v[8:9]
	v_pk_mul_f32 v[242:243], v[66:67], v[10:11]
	v_mul_f32_e32 v175, v8, v8
	v_add_u32_e32 v240, 0x8000, v240
	v_add_u32_e32 v241, 0x8000, v241
	v_add_u32_e32 v242, 0x8000, v242
	v_add_u32_e32 v243, 0x8000, v243
	v_fmac_f32_e32 v175, v9, v9
	v_fmac_f32_e32 v175, v10, v10
	v_fmac_f32_e32 v175, v11, v11
	v_perm_b32 v230, v241, v240, s58
	v_perm_b32 v231, v243, v242, s58
	global_store_dwordx2 v[218:219], v[230:231], off
	v_pk_fma_f32 v[2:3], v[2:3], 0.5, v[190:191] op_sel_hi:[1,0,1]
	v_pk_fma_f32 v[0:1], v[0:1], 0.5, v[188:189] op_sel_hi:[1,0,1]
	global_store_dwordx4 v[234:235], v[0:3], off offset:512
	v_pk_mul_f32 v[244:245], v[72:73], v[0:1]
	v_pk_mul_f32 v[246:247], v[74:75], v[2:3]
	v_fmac_f32_e32 v175, v0, v0
	v_add_u32_e32 v244, 0x8000, v244
	v_add_u32_e32 v245, 0x8000, v245
	v_add_u32_e32 v246, 0x8000, v246
	v_add_u32_e32 v247, 0x8000, v247
	v_fmac_f32_e32 v175, v1, v1
	v_fmac_f32_e32 v175, v2, v2
	v_fmac_f32_e32 v175, v3, v3
	v_perm_b32 v232, v245, v244, s58
	v_perm_b32 v233, v247, v246, s58
	global_store_dwordx2 v[218:219], v[232:233], off offset:256
	v_pk_fma_f32 v[14:15], v[14:15], 0.5, v[194:195] op_sel_hi:[1,0,1]
	v_pk_fma_f32 v[12:13], v[12:13], 0.5, v[192:193] op_sel_hi:[1,0,1]
	global_store_dwordx4 v[236:237], v[12:15], off
	v_pk_mul_f32 v[240:241], v[80:81], v[12:13]
	v_pk_mul_f32 v[242:243], v[82:83], v[14:15]
	v_mul_f32_e32 v238, v12, v12
	v_add_u32_e32 v240, 0x8000, v240
	v_add_u32_e32 v241, 0x8000, v241
	v_add_u32_e32 v242, 0x8000, v242
	v_add_u32_e32 v243, 0x8000, v243
	v_fmac_f32_e32 v238, v13, v13
	v_fmac_f32_e32 v238, v14, v14
	v_fmac_f32_e32 v238, v15, v15
	v_perm_b32 v230, v241, v240, s58
	v_perm_b32 v231, v243, v242, s58
	global_store_dwordx2 v[220:221], v[230:231], off
	v_pk_fma_f32 v[6:7], v[6:7], 0.5, v[198:199] op_sel_hi:[1,0,1]
	v_pk_fma_f32 v[4:5], v[4:5], 0.5, v[196:197] op_sel_hi:[1,0,1]
	global_store_dwordx4 v[236:237], v[4:7], off offset:512
	v_pk_mul_f32 v[244:245], v[84:85], v[4:5]
	v_pk_mul_f32 v[246:247], v[86:87], v[6:7]
	v_fmac_f32_e32 v238, v4, v4
	v_add_u32_e32 v244, 0x8000, v244
	v_add_u32_e32 v245, 0x8000, v245
	v_add_u32_e32 v246, 0x8000, v246
	v_add_u32_e32 v247, 0x8000, v247
	v_fmac_f32_e32 v238, v5, v5
	v_fmac_f32_e32 v238, v6, v6
	v_fmac_f32_e32 v238, v7, v7
	v_perm_b32 v232, v245, v244, s58
	v_perm_b32 v233, v247, v246, s58
	global_store_dwordx2 v[220:221], v[232:233], off offset:256
	s_nop 1
	v_mov_b32_dpp v228, v175 row_ror:8 row_mask:0xf bank_mask:0xf
	v_mov_b32_dpp v229, v238 row_ror:8 row_mask:0xf bank_mask:0xf
	v_add_f32_e32 v175, v175, v228
	v_add_f32_e32 v238, v238, v229
	v_cndmask_b32_e64 v175, v238, v175, s[34:35]
	s_nop 0
	ds_bpermute_b32 v228, v239, v175
	s_waitcnt lgkmcnt(0)
	v_add_f32_e32 v175, v175, v228
	s_nop 0
	ds_bpermute_b32 v229, v248, v175
	s_waitcnt lgkmcnt(0)
	v_add_f32_e32 v175, v175, v229
	s_mov_b64 exec, s[0:1]
	global_atomic_add_f32 v[222:223], v175, off
	s_mov_b64 exec, -1
	s_and_b64 vcc, exec, s[6:7]
	s_mov_b64 s[4:5], -1
	s_cbranch_vccnz .LBB0_301
	s_andn2_b64 vcc, exec, s[12:13]
	s_cbranch_vccnz .LBB0_300
	s_barrier
	s_branch .LBB0_300

;     __device__ __forceinline__ void operator()(const f32x4 (&acc)[2][2][4][2], const Unit& u, int wr, int wc, int fr, int fq) const {
;         const int row0 = u.pm * BM + wr * 64 + fr, col0 = u.pn * BM + wc * 32 + 4 * fq;
;         const float* rbase = (u.pm * BM < SEQ_P) ? resA : (resB - (size_t)SEQ_P * ldc);
;         f32x4 wv[2][2];
;         if (xn) {
; #pragma unroll
;             for (int bj = 0; bj < 2; ++bj)
; #pragma unroll
;                 for (int n = 0; n < 2; ++n) wv[bj][n] = *(const f32x4*)(wn + col0 + bj * HALF + n * 16);
;         }
; #pragma unroll
;         for (int ai = 0; ai < 2; ++ai)
; #pragma unroll
;             for (int m = 0; m < 4; ++m) {
;                 const int row = row0 + ai * HALF + m * 16;
;                 const size_t off = (size_t)row * ldc + col0;
;                 float q = 0.f;
; #pragma unroll
;                 for (int bj = 0; bj < 2; ++bj)
; #pragma unroll
;                     for (int n = 0; n < 2; ++n) {
;                         const f32x4 rv = *(const f32x4*)(rbase + off + bj * HALF + n * 16);
;                         const f32x4 v = rv + acc[ai][bj][m][n] * scale;
;                         if (out) *(f32x4*)(out + off + bj * HALF + n * 16) = v;
;                         if (xn) { q += (v.x * v.x + v.y * v.y) + (v.z * v.z + v.w * v.w); const f32x4 o = v * wv[bj][n];
;                             u32x2 p; p.x = pk2(o.x, o.y); p.y = pk2(o.z, o.w); *(u32x2*)(xn + off + bj * HALF + n * 16) = p; }
.LBB0_1085:
	v_lshl_add_u32 v228, s34, 8, v164
	v_lshl_or_b32 v230, s4, 8, v168
	v_and_b32_e32 v249, 8, v172
	v_mov_b32_e32 v229, 0
	v_cmp_eq_u32_e64 s[34:35], 0, v249
	v_lshlrev_b32_e32 v173, 1, v249
	v_add_u32_e32 v232, v230, v173
	v_sub_u32_e32 v238, 16, v173
	v_add_u32_e32 v238, v230, v238
	v_mov_b32_e32 v230, v232
	v_mov_b32_e32 v232, v238
	v_mov_b32_e32 v231, 0
	v_mov_b32_e32 v233, 0
	v_sub_u32_e32 v226, v228, v249
	v_mov_b32_e32 v227, 0
	v_lshlrev_b64 v[224:225], 11, v[226:227]
	v_add_u32_e32 v226, 8, v226
	v_lshlrev_b64 v[226:227], 11, v[226:227]
	v_lshl_add_u64 v[224:225], v[224:225], 0, v[230:231]
	v_lshl_add_u64 v[226:227], v[226:227], 0, v[232:233]
	v_lshl_add_u64 v[174:175], v[224:225], 2, s[8:9]
	v_lshl_add_u64 v[216:217], v[226:227], 2, s[8:9]
	v_lshl_add_u64 v[218:219], v[230:231], 2, s[10:11]
	v_lshl_add_u64 v[220:221], v[232:233], 2, s[10:11]
	global_load_dwordx4 v[64:67], v[218:219], off
	global_load_dwordx4 v[72:75], v[218:219], off offset:512
	global_load_dwordx4 v[76:79], v[220:221], off
	global_load_dwordx4 v[84:87], v[220:221], off offset:512
	global_load_dwordx4 v[156:159], v[174:175], off
	global_load_dwordx4 v[160:163], v[174:175], off offset:512
	global_load_dwordx4 v[176:179], v[216:217], off
	global_load_dwordx4 v[180:183], v[216:217], off offset:512
	s_mov_b64 vcc, 0x20000
	v_lshl_add_u64 v[174:175], v[174:175], 0, vcc
	v_lshl_add_u64 v[216:217], v[216:217], 0, vcc
	global_load_dwordx4 v[184:187], v[174:175], off
	global_load_dwordx4 v[188:191], v[174:175], off offset:512
	global_load_dwordx4 v[192:195], v[216:217], off
	global_load_dwordx4 v[196:199], v[216:217], off offset:512
	s_mov_b64 vcc, 0x20000
	v_lshl_add_u64 v[174:175], v[174:175], 0, vcc
	v_lshl_add_u64 v[216:217], v[216:217], 0, vcc
	global_load_dwordx4 v[200:203], v[174:175], off
	global_load_dwordx4 v[204:207], v[174:175], off offset:512
	global_load_dwordx4 v[208:211], v[216:217], off
	global_load_dwordx4 v[212:215], v[216:217], off offset:512
	s_mov_b64 vcc, 0x20000
	v_lshl_add_u64 v[174:175], v[174:175], 0, vcc
	v_lshl_add_u64 v[216:217], v[216:217], 0, vcc
	v_lshl_add_u64 v[234:235], v[224:225], 2, s[8:9]
	v_lshl_add_u64 v[236:237], v[226:227], 2, s[8:9]
	v_lshl_add_u64 v[218:219], v[224:225], 1, s[14:15]
	v_lshl_add_u64 v[220:221], v[226:227], 1, s[14:15]
	v_lshl_add_u64 v[222:223], v[228:229], 2, s[16:17]
	v_xor_b32_e32 v239, 16, v172
	v_xor_b32_e32 v248, 32, v172
	v_lshlrev_b32_e32 v239, 2, v239
	v_lshlrev_b32_e32 v248, 2, v248
	v_mov_b32_dpp v224, v136 row_ror:8 row_mask:0xf bank_mask:0xf
	v_mov_b32_dpp v225, v137 row_ror:8 row_mask:0xf bank_mask:0xf
	v_mov_b32_dpp v226, v138 row_ror:8 row_mask:0xf bank_mask:0xf
	v_mov_b32_dpp v227, v139 row_ror:8 row_mask:0xf bank_mask:0xf
	v_cndmask_b32_e64 v136, v224, v140, s[34:35]
	v_cndmask_b32_e64 v137, v225, v141, s[34:35]
	v_cndmask_b32_e64 v138, v226, v142, s[34:35]
	v_cndmask_b32_e64 v139, v227, v143, s[34:35]
	v_cndmask_b32_e64 v140, v140, v224, s[34:35]
	v_cndmask_b32_e64 v141, v141, v225, s[34:35]
	v_cndmask_b32_e64 v142, v142, v226, s[34:35]
	v_cndmask_b32_e64 v143, v143, v227, s[34:35]
	v_mov_b32_dpp v224, v128 row_ror:8 row_mask:0xf bank_mask:0xf
	v_mov_b32_dpp v225, v129 row_ror:8 row_mask:0xf bank_mask:0xf
	v_mov_b32_dpp v226, v130 row_ror:8 row_mask:0xf bank_mask:0xf
	v_mov_b32_dpp v227, v131 row_ror:8 row_mask:0xf bank_mask:0xf
	v_cndmask_b32_e64 v128, v224, v132, s[34:35]
	v_cndmask_b32_e64 v129, v225, v133, s[34:35]
	v_cndmask_b32_e64 v130, v226, v134, s[34:35]
	v_cndmask_b32_e64 v131, v227, v135, s[34:35]
	v_cndmask_b32_e64 v132, v132, v224, s[34:35]
	v_cndmask_b32_e64 v133, v133, v225, s[34:35]
	v_cndmask_b32_e64 v134, v134, v226, s[34:35]
	v_cndmask_b32_e64 v135, v135, v227, s[34:35]
	s_waitcnt vmcnt(8)
	v_pk_add_f32 v[138:139], v[138:139], v[158:159]
	v_pk_add_f32 v[136:137], v[136:137], v[156:157]
	global_store_dwordx4 v[234:235], v[136:139], off
	v_pk_mul_f32 v[240:241], v[64:65], v[136:137]
	v_pk_mul_f32 v[242:243], v[66:67], v[138:139]
	v_mul_f32_e32 v173, v136, v136
	v_add_u32_e32 v240, 0x8000, v240
	v_add_u32_e32 v241, 0x8000, v241
	v_add_u32_e32 v242, 0x8000, v242
	v_add_u32_e32 v243, 0x8000, v243
	v_fmac_f32_e32 v173, v137, v137
	v_fmac_f32_e32 v173, v138, v138
	v_fmac_f32_e32 v173, v139, v139
	v_perm_b32 v230, v241, v240, s58
	v_perm_b32 v231, v243, v242, s58
	global_store_dwordx2 v[218:219], v[230:231], off
	v_pk_add_f32 v[130:131], v[130:131], v[162:163]
	v_pk_add_f32 v[128:129], v[128:129], v[160:161]
	global_store_dwordx4 v[234:235], v[128:131], off offset:512
	v_pk_mul_f32 v[244:245], v[72:73], v[128:129]
	v_pk_mul_f32 v[246:247], v[74:75], v[130:131]
	v_fmac_f32_e32 v173, v128, v128
	v_add_u32_e32 v244, 0x8000, v244
	v_add_u32_e32 v245, 0x8000, v245
	v_add_u32_e32 v246, 0x8000, v246
	v_add_u32_e32 v247, 0x8000, v247
	v_fmac_f32_e32 v173, v129, v129
	v_fmac_f32_e32 v173, v130, v130
	v_fmac_f32_e32 v173, v131, v131
	v_perm_b32 v232, v245, v244, s58
	v_perm_b32 v233, v247, v246, s58
	global_store_dwordx2 v[218:219], v[232:233], off offset:256
	v_pk_add_f32 v[142:143], v[142:143], v[178:179]
	v_pk_add_f32 v[140:141], v[140:141], v[176:177]
	global_store_dwordx4 v[236:237], v[140:143], off
	v_pk_mul_f32 v[240:241], v[76:77], v[140:141]
	v_pk_mul_f32 v[242:243], v[78:79], v[142:143]
	v_mul_f32_e32 v238, v140, v140
	v_add_u32_e32 v240, 0x8000, v240
	v_add_u32_e32 v241, 0x8000, v241
	v_add_u32_e32 v242, 0x8000, v242
	v_add_u32_e32 v243, 0x8000, v243
	v_fmac_f32_e32 v238, v141, v141
	v_fmac_f32_e32 v238, v142, v142
	v_fmac_f32_e32 v238, v143, v143
	v_perm_b32 v230, v241, v240, s58
	v_perm_b32 v231, v243, v242, s58
	global_store_dwordx2 v[220:221], v[230:231], off
;     __device__ __forceinline__ void operator()(const f32x4 (&acc)[2][2][4][2], const Unit& u, int wr, int wc, int fr, int fq) const {
;     ...
; #pragma unroll
;         for (int ai = 0; ai < 2; ++ai)
; #pragma unroll
;             for (int m = 0; m < 4; ++m) {
;                 const int row = row0 + ai * HALF + m * 16;
;                 const size_t off = (size_t)row * ldc + col0;
;                 float q = 0.f;
; #pragma unroll
;                 for (int bj = 0; bj < 2; ++bj)
; #pragma unroll
;                     for (int n = 0; n < 2; ++n) {
;                         const f32x4 rv = *(const f32x4*)(rbase + off + bj * HALF + n * 16);
;                         const f32x4 v = rv + acc[ai][bj][m][n] * scale;
;                         if (out) *(f32x4*)(out + off + bj * HALF + n * 16) = v;
;                         if (xn) { q += (v.x * v.x + v.y * v.y) + (v.z * v.z + v.w * v.w); const f32x4 o = v * wv[bj][n];
;                             u32x2 p; p.x = pk2(o.x, o.y); p.y = pk2(o.z, o.w); *(u32x2*)(xn + off + bj * HALF + n * 16) = p; }
;                     }
;                 if (xn) { q += __shfl_xor(q, 16); q += __shfl_xor(q, 32); if (fq == 0) (void)__hip_atomic_fetch_add(ss + row, q, __ATOMIC_RELAXED, __HIP_MEMORY_SCOPE_AGENT); }
;             }
	v_pk_add_f32 v[134:135], v[134:135], v[182:183]
	v_pk_add_f32 v[132:133], v[132:133], v[180:181]
	global_store_dwordx4 v[236:237], v[132:135], off offset:512
	v_pk_mul_f32 v[244:245], v[84:85], v[132:133]
	v_pk_mul_f32 v[246:247], v[86:87], v[134:135]
	v_fmac_f32_e32 v238, v132, v132
	v_add_u32_e32 v244, 0x8000, v244
	v_add_u32_e32 v245, 0x8000, v245
	v_add_u32_e32 v246, 0x8000, v246
	v_add_u32_e32 v247, 0x8000, v247
	v_fmac_f32_e32 v238, v133, v133
	v_fmac_f32_e32 v238, v134, v134
	v_fmac_f32_e32 v238, v135, v135
	v_perm_b32 v232, v245, v244, s58
	v_perm_b32 v233, v247, v246, s58
	global_store_dwordx2 v[220:221], v[232:233], off offset:256
	s_nop 1
	v_mov_b32_dpp v228, v173 row_ror:8 row_mask:0xf bank_mask:0xf
	v_mov_b32_dpp v229, v238 row_ror:8 row_mask:0xf bank_mask:0xf
	v_add_f32_e32 v173, v173, v228
	v_add_f32_e32 v238, v238, v229
	v_cndmask_b32_e64 v173, v238, v173, s[34:35]
	s_nop 0
	ds_bpermute_b32 v228, v239, v173
	global_load_dwordx4 v[156:159], v[174:175], off
	global_load_dwordx4 v[160:163], v[174:175], off offset:512
	global_load_dwordx4 v[176:179], v[216:217], off
	global_load_dwordx4 v[180:183], v[216:217], off offset:512
	s_mov_b64 vcc, 0xa0000
	v_lshl_add_u64 v[174:175], v[174:175], 0, vcc
	v_lshl_add_u64 v[216:217], v[216:217], 0, vcc
	s_mov_b64 vcc, 0x20000
	v_lshl_add_u64 v[234:235], v[234:235], 0, vcc
	v_lshl_add_u64 v[236:237], v[236:237], 0, vcc
	s_mov_b64 vcc, 0x10000
	v_lshl_add_u64 v[218:219], v[218:219], 0, vcc
	v_lshl_add_u64 v[220:221], v[220:221], 0, vcc
	s_waitcnt lgkmcnt(0)
	v_add_f32_e32 v173, v173, v228
	s_nop 0
	ds_bpermute_b32 v229, v248, v173
	s_waitcnt lgkmcnt(0)
	v_add_f32_e32 v173, v173, v229
	s_mov_b64 exec, s[0:1]
	global_atomic_add_f32 v[222:223], v173, off
	s_mov_b64 exec, -1
	s_mov_b64 vcc, 64
	v_lshl_add_u64 v[222:223], v[222:223], 0, vcc
	v_mov_b32_dpp v224, v120 row_ror:8 row_mask:0xf bank_mask:0xf
	v_mov_b32_dpp v225, v121 row_ror:8 row_mask:0xf bank_mask:0xf
	v_mov_b32_dpp v226, v122 row_ror:8 row_mask:0xf bank_mask:0xf
	v_mov_b32_dpp v227, v123 row_ror:8 row_mask:0xf bank_mask:0xf
	v_cndmask_b32_e64 v120, v224, v124, s[34:35]
	v_cndmask_b32_e64 v121, v225, v125, s[34:35]
	v_cndmask_b32_e64 v122, v226, v126, s[34:35]
	v_cndmask_b32_e64 v123, v227, v127, s[34:35]
	v_cndmask_b32_e64 v124, v124, v224, s[34:35]
	v_cndmask_b32_e64 v125, v125, v225, s[34:35]
	v_cndmask_b32_e64 v126, v126, v226, s[34:35]
	v_cndmask_b32_e64 v127, v127, v227, s[34:35]
	v_mov_b32_dpp v224, v112 row_ror:8 row_mask:0xf bank_mask:0xf
	v_mov_b32_dpp v225, v113 row_ror:8 row_mask:0xf bank_mask:0xf
	v_mov_b32_dpp v226, v114 row_ror:8 row_mask:0xf bank_mask:0xf
	v_mov_b32_dpp v227, v115 row_ror:8 row_mask:0xf bank_mask:0xf
	v_cndmask_b32_e64 v112, v224, v116, s[34:35]
	v_cndmask_b32_e64 v113, v225, v117, s[34:35]
	v_cndmask_b32_e64 v114, v226, v118, s[34:35]
	v_cndmask_b32_e64 v115, v227, v119, s[34:35]
	v_cndmask_b32_e64 v116, v116, v224, s[34:35]
	v_cndmask_b32_e64 v117, v117, v225, s[34:35]
	v_cndmask_b32_e64 v118, v118, v226, s[34:35]
	v_cndmask_b32_e64 v119, v119, v227, s[34:35]
	s_waitcnt vmcnt(17)
	v_pk_add_f32 v[122:123], v[122:123], v[186:187]
	v_pk_add_f32 v[120:121], v[120:121], v[184:185]
	global_store_dwordx4 v[234:235], v[120:123], off
	v_pk_mul_f32 v[240:241], v[64:65], v[120:121]
	v_pk_mul_f32 v[242:243], v[66:67], v[122:123]
	v_mul_f32_e32 v173, v120, v120
	v_add_u32_e32 v240, 0x8000, v240
	v_add_u32_e32 v241, 0x8000, v241
	v_add_u32_e32 v242, 0x8000, v242
	v_add_u32_e32 v243, 0x8000, v243
	v_fmac_f32_e32 v173, v121, v121
	v_fmac_f32_e32 v173, v122, v122
	v_fmac_f32_e32 v173, v123, v123
	v_perm_b32 v230, v241, v240, s58
	v_perm_b32 v231, v243, v242, s58
	global_store_dwordx2 v[218:219], v[230:231], off
	v_pk_add_f32 v[114:115], v[114:115], v[190:191]
	v_pk_add_f32 v[112:113], v[112:113], v[188:189]
	global_store_dwordx4 v[234:235], v[112:115], off offset:512
	v_pk_mul_f32 v[244:245], v[72:73], v[112:113]
	v_pk_mul_f32 v[246:247], v[74:75], v[114:115]
	v_fmac_f32_e32 v173, v112, v112
	v_add_u32_e32 v244, 0x8000, v244
	v_add_u32_e32 v245, 0x8000, v245
	v_add_u32_e32 v246, 0x8000, v246
	v_add_u32_e32 v247, 0x8000, v247
	v_fmac_f32_e32 v173, v113, v113
	v_fmac_f32_e32 v173, v114, v114
	v_fmac_f32_e32 v173, v115, v115
	v_perm_b32 v232, v245, v244, s58
	v_perm_b32 v233, v247, v246, s58
	global_store_dwordx2 v[218:219], v[232:233], off offset:256
	v_pk_add_f32 v[126:127], v[126:127], v[194:195]
	v_pk_add_f32 v[124:125], v[124:125], v[192:193]
	global_store_dwordx4 v[236:237], v[124:127], off
	v_pk_mul_f32 v[240:241], v[76:77], v[124:125]
	v_pk_mul_f32 v[242:243], v[78:79], v[126:127]
	v_mul_f32_e32 v238, v124, v124
	v_add_u32_e32 v240, 0x8000, v240
	v_add_u32_e32 v241, 0x8000, v241
	v_add_u32_e32 v242, 0x8000, v242
	v_add_u32_e32 v243, 0x8000, v243
	v_fmac_f32_e32 v238, v125, v125
	v_fmac_f32_e32 v238, v126, v126
	v_fmac_f32_e32 v238, v127, v127
	v_perm_b32 v230, v241, v240, s58
	v_perm_b32 v231, v243, v242, s58
	global_store_dwordx2 v[220:221], v[230:231], off
	v_pk_add_f32 v[118:119], v[118:119], v[198:199]
	v_pk_add_f32 v[116:117], v[116:117], v[196:197]
	global_store_dwordx4 v[236:237], v[116:119], off offset:512
	v_pk_mul_f32 v[244:245], v[84:85], v[116:117]
	v_pk_mul_f32 v[246:247], v[86:87], v[118:119]
	v_fmac_f32_e32 v238, v116, v116
	v_add_u32_e32 v244, 0x8000, v244
	v_add_u32_e32 v245, 0x8000, v245
	v_add_u32_e32 v246, 0x8000, v246
	v_add_u32_e32 v247, 0x8000, v247
	v_fmac_f32_e32 v238, v117, v117
	v_fmac_f32_e32 v238, v118, v118
	v_fmac_f32_e32 v238, v119, v119
	v_perm_b32 v232, v245, v244, s58
	v_perm_b32 v233, v247, v246, s58
	global_store_dwordx2 v[220:221], v[232:233], off offset:256
	s_nop 1
	v_mov_b32_dpp v228, v173 row_ror:8 row_mask:0xf bank_mask:0xf
	v_mov_b32_dpp v229, v238 row_ror:8 row_mask:0xf bank_mask:0xf
	v_add_f32_e32 v173, v173, v228
	v_add_f32_e32 v238, v238, v229
	v_cndmask_b32_e64 v173, v238, v173, s[34:35]
	s_nop 0
	ds_bpermute_b32 v228, v239, v173
	global_load_dwordx4 v[184:187], v[174:175], off
	global_load_dwordx4 v[188:191], v[174:175], off offset:512
	global_load_dwordx4 v[192:195], v[216:217], off
	global_load_dwordx4 v[196:199], v[216:217], off offset:512
	s_mov_b64 vcc, 0x20000
	v_lshl_add_u64 v[174:175], v[174:175], 0, vcc
	v_lshl_add_u64 v[216:217], v[216:217], 0, vcc
	s_mov_b64 vcc, 0x20000
	v_lshl_add_u64 v[234:235], v[234:235], 0, vcc
	v_lshl_add_u64 v[236:237], v[236:237], 0, vcc
	s_mov_b64 vcc, 0x10000
	v_lshl_add_u64 v[218:219], v[218:219], 0, vcc
	v_lshl_add_u64 v[220:221], v[220:221], 0, vcc
	s_waitcnt lgkmcnt(0)
;     __device__ __forceinline__ void operator()(const f32x4 (&acc)[2][2][4][2], const Unit& u, int wr, int wc, int fr, int fq) const {
;     ...
;         for (int ai = 0; ai < 2; ++ai)
; #pragma unroll
;             for (int m = 0; m < 4; ++m) {
;                 const int row = row0 + ai * HALF + m * 16;
;                 const size_t off = (size_t)row * ldc + col0;
;                 float q = 0.f;
; #pragma unroll
;                 for (int bj = 0; bj < 2; ++bj)
; #pragma unroll
;                     for (int n = 0; n < 2; ++n) {
;                         const f32x4 rv = *(const f32x4*)(rbase + off + bj * HALF + n * 16);
;                         const f32x4 v = rv + acc[ai][bj][m][n] * scale;
;                         if (out) *(f32x4*)(out + off + bj * HALF + n * 16) = v;
;                         if (xn) { q += (v.x * v.x + v.y * v.y) + (v.z * v.z + v.w * v.w); const f32x4 o = v * wv[bj][n];
;                             u32x2 p; p.x = pk2(o.x, o.y); p.y = pk2(o.z, o.w); *(u32x2*)(xn + off + bj * HALF + n * 16) = p; }
;                     }
;                 if (xn) { q += __shfl_xor(q, 16); q += __shfl_xor(q, 32); if (fq == 0) (void)__hip_atomic_fetch_add(ss + row, q, __ATOMIC_RELAXED, __HIP_MEMORY_SCOPE_AGENT); }
;             }
	v_add_f32_e32 v173, v173, v228
	s_nop 0
	ds_bpermute_b32 v229, v248, v173
	s_waitcnt lgkmcnt(0)
	v_add_f32_e32 v173, v173, v229
	s_mov_b64 exec, s[0:1]
	global_atomic_add_f32 v[222:223], v173, off
	s_mov_b64 exec, -1
	s_mov_b64 vcc, 64
	v_lshl_add_u64 v[222:223], v[222:223], 0, vcc
	v_mov_b32_dpp v224, v104 row_ror:8 row_mask:0xf bank_mask:0xf
	v_mov_b32_dpp v225, v105 row_ror:8 row_mask:0xf bank_mask:0xf
	v_mov_b32_dpp v226, v106 row_ror:8 row_mask:0xf bank_mask:0xf
	v_mov_b32_dpp v227, v107 row_ror:8 row_mask:0xf bank_mask:0xf
	v_cndmask_b32_e64 v104, v224, v108, s[34:35]
	v_cndmask_b32_e64 v105, v225, v109, s[34:35]
	v_cndmask_b32_e64 v106, v226, v110, s[34:35]
	v_cndmask_b32_e64 v107, v227, v111, s[34:35]
	v_cndmask_b32_e64 v108, v108, v224, s[34:35]
	v_cndmask_b32_e64 v109, v109, v225, s[34:35]
	v_cndmask_b32_e64 v110, v110, v226, s[34:35]
	v_cndmask_b32_e64 v111, v111, v227, s[34:35]
	v_mov_b32_dpp v224, v96 row_ror:8 row_mask:0xf bank_mask:0xf
	v_mov_b32_dpp v225, v97 row_ror:8 row_mask:0xf bank_mask:0xf
	v_mov_b32_dpp v226, v98 row_ror:8 row_mask:0xf bank_mask:0xf
	v_mov_b32_dpp v227, v99 row_ror:8 row_mask:0xf bank_mask:0xf
	v_cndmask_b32_e64 v96, v224, v100, s[34:35]
	v_cndmask_b32_e64 v97, v225, v101, s[34:35]
	v_cndmask_b32_e64 v98, v226, v102, s[34:35]
	v_cndmask_b32_e64 v99, v227, v103, s[34:35]
	v_cndmask_b32_e64 v100, v100, v224, s[34:35]
	v_cndmask_b32_e64 v101, v101, v225, s[34:35]
	v_cndmask_b32_e64 v102, v102, v226, s[34:35]
	v_cndmask_b32_e64 v103, v103, v227, s[34:35]
	s_waitcnt vmcnt(26)
	v_pk_add_f32 v[106:107], v[106:107], v[202:203]
	v_pk_add_f32 v[104:105], v[104:105], v[200:201]
	global_store_dwordx4 v[234:235], v[104:107], off
	v_pk_mul_f32 v[240:241], v[64:65], v[104:105]
	v_pk_mul_f32 v[242:243], v[66:67], v[106:107]
	v_mul_f32_e32 v173, v104, v104
	v_add_u32_e32 v240, 0x8000, v240
	v_add_u32_e32 v241, 0x8000, v241
	v_add_u32_e32 v242, 0x8000, v242
	v_add_u32_e32 v243, 0x8000, v243
	v_fmac_f32_e32 v173, v105, v105
	v_fmac_f32_e32 v173, v106, v106
	v_fmac_f32_e32 v173, v107, v107
	v_perm_b32 v230, v241, v240, s58
	v_perm_b32 v231, v243, v242, s58
	global_store_dwordx2 v[218:219], v[230:231], off
	v_pk_add_f32 v[98:99], v[98:99], v[206:207]
	v_pk_add_f32 v[96:97], v[96:97], v[204:205]
	global_store_dwordx4 v[234:235], v[96:99], off offset:512
	v_pk_mul_f32 v[244:245], v[72:73], v[96:97]
	v_pk_mul_f32 v[246:247], v[74:75], v[98:99]
	v_fmac_f32_e32 v173, v96, v96
	v_add_u32_e32 v244, 0x8000, v244
	v_add_u32_e32 v245, 0x8000, v245
	v_add_u32_e32 v246, 0x8000, v246
	v_add_u32_e32 v247, 0x8000, v247
	v_fmac_f32_e32 v173, v97, v97
	v_fmac_f32_e32 v173, v98, v98
	v_fmac_f32_e32 v173, v99, v99
	v_perm_b32 v232, v245, v244, s58
	v_perm_b32 v233, v247, v246, s58
	global_store_dwordx2 v[218:219], v[232:233], off offset:256
	v_pk_add_f32 v[110:111], v[110:111], v[210:211]
	v_pk_add_f32 v[108:109], v[108:109], v[208:209]
	global_store_dwordx4 v[236:237], v[108:111], off
	v_pk_mul_f32 v[240:241], v[76:77], v[108:109]
	v_pk_mul_f32 v[242:243], v[78:79], v[110:111]
	v_mul_f32_e32 v238, v108, v108
	v_add_u32_e32 v240, 0x8000, v240
	v_add_u32_e32 v241, 0x8000, v241
	v_add_u32_e32 v242, 0x8000, v242
	v_add_u32_e32 v243, 0x8000, v243
	v_fmac_f32_e32 v238, v109, v109
	v_fmac_f32_e32 v238, v110, v110
	v_fmac_f32_e32 v238, v111, v111
	v_perm_b32 v230, v241, v240, s58
	v_perm_b32 v231, v243, v242, s58
	global_store_dwordx2 v[220:221], v[230:231], off
	v_pk_add_f32 v[102:103], v[102:103], v[214:215]
	v_pk_add_f32 v[100:101], v[100:101], v[212:213]
	global_store_dwordx4 v[236:237], v[100:103], off offset:512
	v_pk_mul_f32 v[244:245], v[84:85], v[100:101]
	v_pk_mul_f32 v[246:247], v[86:87], v[102:103]
	v_fmac_f32_e32 v238, v100, v100
	v_add_u32_e32 v244, 0x8000, v244
	v_add_u32_e32 v245, 0x8000, v245
	v_add_u32_e32 v246, 0x8000, v246
	v_add_u32_e32 v247, 0x8000, v247
	v_fmac_f32_e32 v238, v101, v101
	v_fmac_f32_e32 v238, v102, v102
	v_fmac_f32_e32 v238, v103, v103
	v_perm_b32 v232, v245, v244, s58
	v_perm_b32 v233, v247, v246, s58
	global_store_dwordx2 v[220:221], v[232:233], off offset:256
	s_nop 1
	v_mov_b32_dpp v228, v173 row_ror:8 row_mask:0xf bank_mask:0xf
	v_mov_b32_dpp v229, v238 row_ror:8 row_mask:0xf bank_mask:0xf
	v_add_f32_e32 v173, v173, v228
	v_add_f32_e32 v238, v238, v229
	v_cndmask_b32_e64 v173, v238, v173, s[34:35]
	s_nop 0
	ds_bpermute_b32 v228, v239, v173
	global_load_dwordx4 v[200:203], v[174:175], off
	global_load_dwordx4 v[204:207], v[174:175], off offset:512
	global_load_dwordx4 v[208:211], v[216:217], off
	global_load_dwordx4 v[212:215], v[216:217], off offset:512
	s_mov_b64 vcc, 0x20000
	v_lshl_add_u64 v[174:175], v[174:175], 0, vcc
	v_lshl_add_u64 v[216:217], v[216:217], 0, vcc
	s_mov_b64 vcc, 0x20000
	v_lshl_add_u64 v[234:235], v[234:235], 0, vcc
	v_lshl_add_u64 v[236:237], v[236:237], 0, vcc
	s_mov_b64 vcc, 0x10000
	v_lshl_add_u64 v[218:219], v[218:219], 0, vcc
	v_lshl_add_u64 v[220:221], v[220:221], 0, vcc
	s_waitcnt lgkmcnt(0)
	v_add_f32_e32 v173, v173, v228
	s_nop 0
	ds_bpermute_b32 v229, v248, v173
	s_waitcnt lgkmcnt(0)
;     __device__ __forceinline__ void operator()(const f32x4 (&acc)[2][2][4][2], const Unit& u, int wr, int wc, int fr, int fq) const {
;     ...
;         for (int ai = 0; ai < 2; ++ai)
; #pragma unroll
;             for (int m = 0; m < 4; ++m) {
;                 const int row = row0 + ai * HALF + m * 16;
;                 const size_t off = (size_t)row * ldc + col0;
;                 float q = 0.f;
; #pragma unroll
;                 for (int bj = 0; bj < 2; ++bj)
; #pragma unroll
;                     for (int n = 0; n < 2; ++n) {
;                         const f32x4 rv = *(const f32x4*)(rbase + off + bj * HALF + n * 16);
;                         const f32x4 v = rv + acc[ai][bj][m][n] * scale;
;                         if (out) *(f32x4*)(out + off + bj * HALF + n * 16) = v;
;                         if (xn) { q += (v.x * v.x + v.y * v.y) + (v.z * v.z + v.w * v.w); const f32x4 o = v * wv[bj][n];
;                             u32x2 p; p.x = pk2(o.x, o.y); p.y = pk2(o.z, o.w); *(u32x2*)(xn + off + bj * HALF + n * 16) = p; }
;                     }
;                 if (xn) { q += __shfl_xor(q, 16); q += __shfl_xor(q, 32); if (fq == 0) (void)__hip_atomic_fetch_add(ss + row, q, __ATOMIC_RELAXED, __HIP_MEMORY_SCOPE_AGENT); }
;             }
	v_add_f32_e32 v173, v173, v229
	s_mov_b64 exec, s[0:1]
	global_atomic_add_f32 v[222:223], v173, off
	s_mov_b64 exec, -1
	s_mov_b64 vcc, 64
	v_lshl_add_u64 v[222:223], v[222:223], 0, vcc
	v_mov_b32_dpp v224, v88 row_ror:8 row_mask:0xf bank_mask:0xf
	v_mov_b32_dpp v225, v89 row_ror:8 row_mask:0xf bank_mask:0xf
	v_mov_b32_dpp v226, v90 row_ror:8 row_mask:0xf bank_mask:0xf
	v_mov_b32_dpp v227, v91 row_ror:8 row_mask:0xf bank_mask:0xf
	v_cndmask_b32_e64 v88, v224, v92, s[34:35]
	v_cndmask_b32_e64 v89, v225, v93, s[34:35]
	v_cndmask_b32_e64 v90, v226, v94, s[34:35]
	v_cndmask_b32_e64 v91, v227, v95, s[34:35]
	v_cndmask_b32_e64 v92, v92, v224, s[34:35]
	v_cndmask_b32_e64 v93, v93, v225, s[34:35]
	v_cndmask_b32_e64 v94, v94, v226, s[34:35]
	v_cndmask_b32_e64 v95, v95, v227, s[34:35]
	v_mov_b32_dpp v224, v68 row_ror:8 row_mask:0xf bank_mask:0xf
	v_mov_b32_dpp v225, v69 row_ror:8 row_mask:0xf bank_mask:0xf
	v_mov_b32_dpp v226, v70 row_ror:8 row_mask:0xf bank_mask:0xf
	v_mov_b32_dpp v227, v71 row_ror:8 row_mask:0xf bank_mask:0xf
	v_cndmask_b32_e64 v68, v224, v80, s[34:35]
	v_cndmask_b32_e64 v69, v225, v81, s[34:35]
	v_cndmask_b32_e64 v70, v226, v82, s[34:35]
	v_cndmask_b32_e64 v71, v227, v83, s[34:35]
	v_cndmask_b32_e64 v80, v80, v224, s[34:35]
	v_cndmask_b32_e64 v81, v81, v225, s[34:35]
	v_cndmask_b32_e64 v82, v82, v226, s[34:35]
	v_cndmask_b32_e64 v83, v83, v227, s[34:35]
	s_waitcnt vmcnt(27)
	v_pk_add_f32 v[90:91], v[90:91], v[158:159]
	v_pk_add_f32 v[88:89], v[88:89], v[156:157]
	global_store_dwordx4 v[234:235], v[88:91], off
	v_pk_mul_f32 v[240:241], v[64:65], v[88:89]
	v_pk_mul_f32 v[242:243], v[66:67], v[90:91]
	v_mul_f32_e32 v173, v88, v88
	v_add_u32_e32 v240, 0x8000, v240
	v_add_u32_e32 v241, 0x8000, v241
	v_add_u32_e32 v242, 0x8000, v242
	v_add_u32_e32 v243, 0x8000, v243
	v_fmac_f32_e32 v173, v89, v89
	v_fmac_f32_e32 v173, v90, v90
	v_fmac_f32_e32 v173, v91, v91
	v_perm_b32 v230, v241, v240, s58
	v_perm_b32 v231, v243, v242, s58
	global_store_dwordx2 v[218:219], v[230:231], off
	v_pk_add_f32 v[70:71], v[70:71], v[162:163]
	v_pk_add_f32 v[68:69], v[68:69], v[160:161]
	global_store_dwordx4 v[234:235], v[68:71], off offset:512
	v_pk_mul_f32 v[244:245], v[72:73], v[68:69]
	v_pk_mul_f32 v[246:247], v[74:75], v[70:71]
	v_fmac_f32_e32 v173, v68, v68
	v_add_u32_e32 v244, 0x8000, v244
	v_add_u32_e32 v245, 0x8000, v245
	v_add_u32_e32 v246, 0x8000, v246
	v_add_u32_e32 v247, 0x8000, v247
	v_fmac_f32_e32 v173, v69, v69
	v_fmac_f32_e32 v173, v70, v70
	v_fmac_f32_e32 v173, v71, v71
	v_perm_b32 v232, v245, v244, s58
	v_perm_b32 v233, v247, v246, s58
	global_store_dwordx2 v[218:219], v[232:233], off offset:256
	v_pk_add_f32 v[94:95], v[94:95], v[178:179]
	v_pk_add_f32 v[92:93], v[92:93], v[176:177]
	global_store_dwordx4 v[236:237], v[92:95], off
	v_pk_mul_f32 v[240:241], v[76:77], v[92:93]
	v_pk_mul_f32 v[242:243], v[78:79], v[94:95]
	v_mul_f32_e32 v238, v92, v92
	v_add_u32_e32 v240, 0x8000, v240
	v_add_u32_e32 v241, 0x8000, v241
	v_add_u32_e32 v242, 0x8000, v242
	v_add_u32_e32 v243, 0x8000, v243
	v_fmac_f32_e32 v238, v93, v93
	v_fmac_f32_e32 v238, v94, v94
	v_fmac_f32_e32 v238, v95, v95
	v_perm_b32 v230, v241, v240, s58
	v_perm_b32 v231, v243, v242, s58
	global_store_dwordx2 v[220:221], v[230:231], off
	v_pk_add_f32 v[82:83], v[82:83], v[182:183]
	v_pk_add_f32 v[80:81], v[80:81], v[180:181]
	global_store_dwordx4 v[236:237], v[80:83], off offset:512
	v_pk_mul_f32 v[244:245], v[84:85], v[80:81]
	v_pk_mul_f32 v[246:247], v[86:87], v[82:83]
	v_fmac_f32_e32 v238, v80, v80
	v_add_u32_e32 v244, 0x8000, v244
	v_add_u32_e32 v245, 0x8000, v245
	v_add_u32_e32 v246, 0x8000, v246
	v_add_u32_e32 v247, 0x8000, v247
	v_fmac_f32_e32 v238, v81, v81
	v_fmac_f32_e32 v238, v82, v82
	v_fmac_f32_e32 v238, v83, v83
	v_perm_b32 v232, v245, v244, s58
	v_perm_b32 v233, v247, v246, s58
	global_store_dwordx2 v[220:221], v[232:233], off offset:256
	s_nop 1
	v_mov_b32_dpp v228, v173 row_ror:8 row_mask:0xf bank_mask:0xf
	v_mov_b32_dpp v229, v238 row_ror:8 row_mask:0xf bank_mask:0xf
	v_add_f32_e32 v173, v173, v228
	v_add_f32_e32 v238, v238, v229
	v_cndmask_b32_e64 v173, v238, v173, s[34:35]
	s_nop 0
	ds_bpermute_b32 v228, v239, v173
	global_load_dwordx4 v[156:159], v[174:175], off
	global_load_dwordx4 v[160:163], v[174:175], off offset:512
	global_load_dwordx4 v[176:179], v[216:217], off
	global_load_dwordx4 v[180:183], v[216:217], off offset:512
	s_mov_b64 vcc, 0x20000
	v_lshl_add_u64 v[174:175], v[174:175], 0, vcc
	v_lshl_add_u64 v[216:217], v[216:217], 0, vcc
	s_mov_b64 vcc, 0xa0000
	v_lshl_add_u64 v[234:235], v[234:235], 0, vcc
	v_lshl_add_u64 v[236:237], v[236:237], 0, vcc
	s_mov_b64 vcc, 0x50000
	v_lshl_add_u64 v[218:219], v[218:219], 0, vcc
	v_lshl_add_u64 v[220:221], v[220:221], 0, vcc
	s_waitcnt lgkmcnt(0)
	v_add_f32_e32 v173, v173, v228
	s_nop 0
	ds_bpermute_b32 v229, v248, v173
	s_waitcnt lgkmcnt(0)
	v_add_f32_e32 v173, v173, v229
	s_mov_b64 exec, s[0:1]
	global_atomic_add_f32 v[222:223], v173, off
	s_mov_b64 exec, -1
	s_mov_b64 vcc, 320
	v_lshl_add_u64 v[222:223], v[222:223], 0, vcc
	v_mov_b32_dpp v224, v56 row_ror:8 row_mask:0xf bank_mask:0xf
	v_mov_b32_dpp v225, v57 row_ror:8 row_mask:0xf bank_mask:0xf
	v_mov_b32_dpp v226, v58 row_ror:8 row_mask:0xf bank_mask:0xf
	v_mov_b32_dpp v227, v59 row_ror:8 row_mask:0xf bank_mask:0xf
	v_cndmask_b32_e64 v56, v224, v60, s[34:35]
	v_cndmask_b32_e64 v57, v225, v61, s[34:35]
	v_cndmask_b32_e64 v58, v226, v62, s[34:35]
	v_cndmask_b32_e64 v59, v227, v63, s[34:35]
	v_cndmask_b32_e64 v60, v60, v224, s[34:35]
	v_cndmask_b32_e64 v61, v61, v225, s[34:35]
	v_cndmask_b32_e64 v62, v62, v226, s[34:35]
	v_cndmask_b32_e64 v63, v63, v227, s[34:35]
	v_mov_b32_dpp v224, v48 row_ror:8 row_mask:0xf bank_mask:0xf
	v_mov_b32_dpp v225, v49 row_ror:8 row_mask:0xf bank_mask:0xf
	v_mov_b32_dpp v226, v50 row_ror:8 row_mask:0xf bank_mask:0xf
	v_mov_b32_dpp v227, v51 row_ror:8 row_mask:0xf bank_mask:0xf
	v_cndmask_b32_e64 v48, v224, v52, s[34:35]
	v_cndmask_b32_e64 v49, v225, v53, s[34:35]
	v_cndmask_b32_e64 v50, v226, v54, s[34:35]
	v_cndmask_b32_e64 v51, v227, v55, s[34:35]
	v_cndmask_b32_e64 v52, v52, v224, s[34:35]
	v_cndmask_b32_e64 v53, v53, v225, s[34:35]
	v_cndmask_b32_e64 v54, v54, v226, s[34:35]
	v_cndmask_b32_e64 v55, v55, v227, s[34:35]
	s_waitcnt vmcnt(27)
;     __device__ __forceinline__ void operator()(const f32x4 (&acc)[2][2][4][2], const Unit& u, int wr, int wc, int fr, int fq) const {
;     ...
;         for (int ai = 0; ai < 2; ++ai)
; #pragma unroll
;             for (int m = 0; m < 4; ++m) {
;                 const int row = row0 + ai * HALF + m * 16;
;                 const size_t off = (size_t)row * ldc + col0;
;                 float q = 0.f;
; #pragma unroll
;                 for (int bj = 0; bj < 2; ++bj)
; #pragma unroll
;                     for (int n = 0; n < 2; ++n) {
;                         const f32x4 rv = *(const f32x4*)(rbase + off + bj * HALF + n * 16);
;                         const f32x4 v = rv + acc[ai][bj][m][n] * scale;
;                         if (out) *(f32x4*)(out + off + bj * HALF + n * 16) = v;
;                         if (xn) { q += (v.x * v.x + v.y * v.y) + (v.z * v.z + v.w * v.w); const f32x4 o = v * wv[bj][n];
;                             u32x2 p; p.x = pk2(o.x, o.y); p.y = pk2(o.z, o.w); *(u32x2*)(xn + off + bj * HALF + n * 16) = p; }
;                     }
;                 if (xn) { q += __shfl_xor(q, 16); q += __shfl_xor(q, 32); if (fq == 0) (void)__hip_atomic_fetch_add(ss + row, q, __ATOMIC_RELAXED, __HIP_MEMORY_SCOPE_AGENT); }
;             }
	v_pk_add_f32 v[58:59], v[58:59], v[186:187]
	v_pk_add_f32 v[56:57], v[56:57], v[184:185]
	global_store_dwordx4 v[234:235], v[56:59], off
	v_pk_mul_f32 v[240:241], v[64:65], v[56:57]
	v_pk_mul_f32 v[242:243], v[66:67], v[58:59]
	v_mul_f32_e32 v173, v56, v56
	v_add_u32_e32 v240, 0x8000, v240
	v_add_u32_e32 v241, 0x8000, v241
	v_add_u32_e32 v242, 0x8000, v242
	v_add_u32_e32 v243, 0x8000, v243
	v_fmac_f32_e32 v173, v57, v57
	v_fmac_f32_e32 v173, v58, v58
	v_fmac_f32_e32 v173, v59, v59
	v_perm_b32 v230, v241, v240, s58
	v_perm_b32 v231, v243, v242, s58
	global_store_dwordx2 v[218:219], v[230:231], off
	v_pk_add_f32 v[50:51], v[50:51], v[190:191]
	v_pk_add_f32 v[48:49], v[48:49], v[188:189]
	global_store_dwordx4 v[234:235], v[48:51], off offset:512
	v_pk_mul_f32 v[244:245], v[72:73], v[48:49]
	v_pk_mul_f32 v[246:247], v[74:75], v[50:51]
	v_fmac_f32_e32 v173, v48, v48
	v_add_u32_e32 v244, 0x8000, v244
	v_add_u32_e32 v245, 0x8000, v245
	v_add_u32_e32 v246, 0x8000, v246
	v_add_u32_e32 v247, 0x8000, v247
	v_fmac_f32_e32 v173, v49, v49
	v_fmac_f32_e32 v173, v50, v50
	v_fmac_f32_e32 v173, v51, v51
	v_perm_b32 v232, v245, v244, s58
	v_perm_b32 v233, v247, v246, s58
	global_store_dwordx2 v[218:219], v[232:233], off offset:256
	v_pk_add_f32 v[62:63], v[62:63], v[194:195]
	v_pk_add_f32 v[60:61], v[60:61], v[192:193]
	global_store_dwordx4 v[236:237], v[60:63], off
	v_pk_mul_f32 v[240:241], v[76:77], v[60:61]
	v_pk_mul_f32 v[242:243], v[78:79], v[62:63]
	v_mul_f32_e32 v238, v60, v60
	v_add_u32_e32 v240, 0x8000, v240
	v_add_u32_e32 v241, 0x8000, v241
	v_add_u32_e32 v242, 0x8000, v242
	v_add_u32_e32 v243, 0x8000, v243
	v_fmac_f32_e32 v238, v61, v61
	v_fmac_f32_e32 v238, v62, v62
	v_fmac_f32_e32 v238, v63, v63
	v_perm_b32 v230, v241, v240, s58
	v_perm_b32 v231, v243, v242, s58
	global_store_dwordx2 v[220:221], v[230:231], off
	v_pk_add_f32 v[54:55], v[54:55], v[198:199]
	v_pk_add_f32 v[52:53], v[52:53], v[196:197]
	global_store_dwordx4 v[236:237], v[52:55], off offset:512
	v_pk_mul_f32 v[244:245], v[84:85], v[52:53]
	v_pk_mul_f32 v[246:247], v[86:87], v[54:55]
	v_fmac_f32_e32 v238, v52, v52
	v_add_u32_e32 v244, 0x8000, v244
	v_add_u32_e32 v245, 0x8000, v245
	v_add_u32_e32 v246, 0x8000, v246
	v_add_u32_e32 v247, 0x8000, v247
	v_fmac_f32_e32 v238, v53, v53
	v_fmac_f32_e32 v238, v54, v54
	v_fmac_f32_e32 v238, v55, v55
	v_perm_b32 v232, v245, v244, s58
	v_perm_b32 v233, v247, v246, s58
	global_store_dwordx2 v[220:221], v[232:233], off offset:256
	s_nop 1
	v_mov_b32_dpp v228, v173 row_ror:8 row_mask:0xf bank_mask:0xf
	v_mov_b32_dpp v229, v238 row_ror:8 row_mask:0xf bank_mask:0xf
	v_add_f32_e32 v173, v173, v228
	v_add_f32_e32 v238, v238, v229
	v_cndmask_b32_e64 v173, v238, v173, s[34:35]
	s_nop 0
	ds_bpermute_b32 v228, v239, v173
	global_load_dwordx4 v[184:187], v[174:175], off
	global_load_dwordx4 v[188:191], v[174:175], off offset:512
	global_load_dwordx4 v[192:195], v[216:217], off
	global_load_dwordx4 v[196:199], v[216:217], off offset:512
	s_mov_b64 vcc, 0x20000
	v_lshl_add_u64 v[234:235], v[234:235], 0, vcc
	v_lshl_add_u64 v[236:237], v[236:237], 0, vcc
	s_mov_b64 vcc, 0x10000
	v_lshl_add_u64 v[218:219], v[218:219], 0, vcc
	v_lshl_add_u64 v[220:221], v[220:221], 0, vcc
	s_waitcnt lgkmcnt(0)
	v_add_f32_e32 v173, v173, v228
	s_nop 0
	ds_bpermute_b32 v229, v248, v173
	s_waitcnt lgkmcnt(0)
	v_add_f32_e32 v173, v173, v229
	s_mov_b64 exec, s[0:1]
	global_atomic_add_f32 v[222:223], v173, off
	s_mov_b64 exec, -1
	s_mov_b64 vcc, 64
	v_lshl_add_u64 v[222:223], v[222:223], 0, vcc
	v_mov_b32_dpp v224, v40 row_ror:8 row_mask:0xf bank_mask:0xf
	v_mov_b32_dpp v225, v41 row_ror:8 row_mask:0xf bank_mask:0xf
	v_mov_b32_dpp v226, v42 row_ror:8 row_mask:0xf bank_mask:0xf
	v_mov_b32_dpp v227, v43 row_ror:8 row_mask:0xf bank_mask:0xf
	v_cndmask_b32_e64 v40, v224, v44, s[34:35]
	v_cndmask_b32_e64 v41, v225, v45, s[34:35]
	v_cndmask_b32_e64 v42, v226, v46, s[34:35]
	v_cndmask_b32_e64 v43, v227, v47, s[34:35]
	v_cndmask_b32_e64 v44, v44, v224, s[34:35]
	v_cndmask_b32_e64 v45, v45, v225, s[34:35]
	v_cndmask_b32_e64 v46, v46, v226, s[34:35]
	v_cndmask_b32_e64 v47, v47, v227, s[34:35]
	v_mov_b32_dpp v224, v32 row_ror:8 row_mask:0xf bank_mask:0xf
	v_mov_b32_dpp v225, v33 row_ror:8 row_mask:0xf bank_mask:0xf
	v_mov_b32_dpp v226, v34 row_ror:8 row_mask:0xf bank_mask:0xf
	v_mov_b32_dpp v227, v35 row_ror:8 row_mask:0xf bank_mask:0xf
	v_cndmask_b32_e64 v32, v224, v36, s[34:35]
	v_cndmask_b32_e64 v33, v225, v37, s[34:35]
	v_cndmask_b32_e64 v34, v226, v38, s[34:35]
	v_cndmask_b32_e64 v35, v227, v39, s[34:35]
	v_cndmask_b32_e64 v36, v36, v224, s[34:35]
	v_cndmask_b32_e64 v37, v37, v225, s[34:35]
	v_cndmask_b32_e64 v38, v38, v226, s[34:35]
	v_cndmask_b32_e64 v39, v39, v227, s[34:35]
	s_waitcnt vmcnt(27)
;     __device__ __forceinline__ void operator()(const f32x4 (&acc)[2][2][4][2], const Unit& u, int wr, int wc, int fr, int fq) const {
;     ...
;         for (int ai = 0; ai < 2; ++ai)
; #pragma unroll
;             for (int m = 0; m < 4; ++m) {
;                 const int row = row0 + ai * HALF + m * 16;
;                 const size_t off = (size_t)row * ldc + col0;
;                 float q = 0.f;
; #pragma unroll
;                 for (int bj = 0; bj < 2; ++bj)
; #pragma unroll
;                     for (int n = 0; n < 2; ++n) {
;                         const f32x4 rv = *(const f32x4*)(rbase + off + bj * HALF + n * 16);
;                         const f32x4 v = rv + acc[ai][bj][m][n] * scale;
;                         if (out) *(f32x4*)(out + off + bj * HALF + n * 16) = v;
;                         if (xn) { q += (v.x * v.x + v.y * v.y) + (v.z * v.z + v.w * v.w); const f32x4 o = v * wv[bj][n];
;                             u32x2 p; p.x = pk2(o.x, o.y); p.y = pk2(o.z, o.w); *(u32x2*)(xn + off + bj * HALF + n * 16) = p; }
;                     }
;                 if (xn) { q += __shfl_xor(q, 16); q += __shfl_xor(q, 32); if (fq == 0) (void)__hip_atomic_fetch_add(ss + row, q, __ATOMIC_RELAXED, __HIP_MEMORY_SCOPE_AGENT); }
;             }
	v_pk_add_f32 v[42:43], v[42:43], v[202:203]
	v_pk_add_f32 v[40:41], v[40:41], v[200:201]
	global_store_dwordx4 v[234:235], v[40:43], off
	v_pk_mul_f32 v[240:241], v[64:65], v[40:41]
	v_pk_mul_f32 v[242:243], v[66:67], v[42:43]
	v_mul_f32_e32 v173, v40, v40
	v_add_u32_e32 v240, 0x8000, v240
	v_add_u32_e32 v241, 0x8000, v241
	v_add_u32_e32 v242, 0x8000, v242
	v_add_u32_e32 v243, 0x8000, v243
	v_fmac_f32_e32 v173, v41, v41
	v_fmac_f32_e32 v173, v42, v42
	v_fmac_f32_e32 v173, v43, v43
	v_perm_b32 v230, v241, v240, s58
	v_perm_b32 v231, v243, v242, s58
	global_store_dwordx2 v[218:219], v[230:231], off
	v_pk_add_f32 v[34:35], v[34:35], v[206:207]
	v_pk_add_f32 v[32:33], v[32:33], v[204:205]
	global_store_dwordx4 v[234:235], v[32:35], off offset:512
	v_pk_mul_f32 v[244:245], v[72:73], v[32:33]
	v_pk_mul_f32 v[246:247], v[74:75], v[34:35]
	v_fmac_f32_e32 v173, v32, v32
	v_add_u32_e32 v244, 0x8000, v244
	v_add_u32_e32 v245, 0x8000, v245
	v_add_u32_e32 v246, 0x8000, v246
	v_add_u32_e32 v247, 0x8000, v247
	v_fmac_f32_e32 v173, v33, v33
	v_fmac_f32_e32 v173, v34, v34
	v_fmac_f32_e32 v173, v35, v35
	v_perm_b32 v232, v245, v244, s58
	v_perm_b32 v233, v247, v246, s58
	global_store_dwordx2 v[218:219], v[232:233], off offset:256
	v_pk_add_f32 v[46:47], v[46:47], v[210:211]
	v_pk_add_f32 v[44:45], v[44:45], v[208:209]
	global_store_dwordx4 v[236:237], v[44:47], off
	v_pk_mul_f32 v[240:241], v[76:77], v[44:45]
	v_pk_mul_f32 v[242:243], v[78:79], v[46:47]
	v_mul_f32_e32 v238, v44, v44
	v_add_u32_e32 v240, 0x8000, v240
	v_add_u32_e32 v241, 0x8000, v241
	v_add_u32_e32 v242, 0x8000, v242
	v_add_u32_e32 v243, 0x8000, v243
	v_fmac_f32_e32 v238, v45, v45
	v_fmac_f32_e32 v238, v46, v46
	v_fmac_f32_e32 v238, v47, v47
	v_perm_b32 v230, v241, v240, s58
	v_perm_b32 v231, v243, v242, s58
	global_store_dwordx2 v[220:221], v[230:231], off
	v_pk_add_f32 v[38:39], v[38:39], v[214:215]
	v_pk_add_f32 v[36:37], v[36:37], v[212:213]
	global_store_dwordx4 v[236:237], v[36:39], off offset:512
	v_pk_mul_f32 v[244:245], v[84:85], v[36:37]
	v_pk_mul_f32 v[246:247], v[86:87], v[38:39]
	v_fmac_f32_e32 v238, v36, v36
	v_add_u32_e32 v244, 0x8000, v244
	v_add_u32_e32 v245, 0x8000, v245
	v_add_u32_e32 v246, 0x8000, v246
	v_add_u32_e32 v247, 0x8000, v247
	v_fmac_f32_e32 v238, v37, v37
	v_fmac_f32_e32 v238, v38, v38
	v_fmac_f32_e32 v238, v39, v39
	v_perm_b32 v232, v245, v244, s58
	v_perm_b32 v233, v247, v246, s58
	global_store_dwordx2 v[220:221], v[232:233], off offset:256
	s_nop 1
	v_mov_b32_dpp v228, v173 row_ror:8 row_mask:0xf bank_mask:0xf
	v_mov_b32_dpp v229, v238 row_ror:8 row_mask:0xf bank_mask:0xf
	v_add_f32_e32 v173, v173, v228
	v_add_f32_e32 v238, v238, v229
	v_cndmask_b32_e64 v173, v238, v173, s[34:35]
	s_nop 0
	ds_bpermute_b32 v228, v239, v173
	s_mov_b64 vcc, 0x20000
	v_lshl_add_u64 v[234:235], v[234:235], 0, vcc
	v_lshl_add_u64 v[236:237], v[236:237], 0, vcc
	s_mov_b64 vcc, 0x10000
	v_lshl_add_u64 v[218:219], v[218:219], 0, vcc
	v_lshl_add_u64 v[220:221], v[220:221], 0, vcc
	s_waitcnt lgkmcnt(0)
	v_add_f32_e32 v173, v173, v228
	s_nop 0
	ds_bpermute_b32 v229, v248, v173
	s_waitcnt lgkmcnt(0)
	v_add_f32_e32 v173, v173, v229
	s_mov_b64 exec, s[0:1]
	global_atomic_add_f32 v[222:223], v173, off
	s_mov_b64 exec, -1
	s_mov_b64 vcc, 64
	v_lshl_add_u64 v[222:223], v[222:223], 0, vcc
	v_mov_b32_dpp v224, v24 row_ror:8 row_mask:0xf bank_mask:0xf
	v_mov_b32_dpp v225, v25 row_ror:8 row_mask:0xf bank_mask:0xf
	v_mov_b32_dpp v226, v26 row_ror:8 row_mask:0xf bank_mask:0xf
	v_mov_b32_dpp v227, v27 row_ror:8 row_mask:0xf bank_mask:0xf
	v_cndmask_b32_e64 v24, v224, v28, s[34:35]
	v_cndmask_b32_e64 v25, v225, v29, s[34:35]
	v_cndmask_b32_e64 v26, v226, v30, s[34:35]
	v_cndmask_b32_e64 v27, v227, v31, s[34:35]
	v_cndmask_b32_e64 v28, v28, v224, s[34:35]
	v_cndmask_b32_e64 v29, v29, v225, s[34:35]
	v_cndmask_b32_e64 v30, v30, v226, s[34:35]
	v_cndmask_b32_e64 v31, v31, v227, s[34:35]
	v_mov_b32_dpp v224, v16 row_ror:8 row_mask:0xf bank_mask:0xf
	v_mov_b32_dpp v225, v17 row_ror:8 row_mask:0xf bank_mask:0xf
	v_mov_b32_dpp v226, v18 row_ror:8 row_mask:0xf bank_mask:0xf
	v_mov_b32_dpp v227, v19 row_ror:8 row_mask:0xf bank_mask:0xf
	v_cndmask_b32_e64 v16, v224, v20, s[34:35]
	v_cndmask_b32_e64 v17, v225, v21, s[34:35]
	v_cndmask_b32_e64 v18, v226, v22, s[34:35]
	v_cndmask_b32_e64 v19, v227, v23, s[34:35]
	v_cndmask_b32_e64 v20, v20, v224, s[34:35]
	v_cndmask_b32_e64 v21, v21, v225, s[34:35]
	v_cndmask_b32_e64 v22, v22, v226, s[34:35]
	v_cndmask_b32_e64 v23, v23, v227, s[34:35]
	s_waitcnt vmcnt(23)
;     __device__ __forceinline__ void operator()(const f32x4 (&acc)[2][2][4][2], const Unit& u, int wr, int wc, int fr, int fq) const {
;     ...
;         for (int ai = 0; ai < 2; ++ai)
; #pragma unroll
;             for (int m = 0; m < 4; ++m) {
;                 const int row = row0 + ai * HALF + m * 16;
;                 const size_t off = (size_t)row * ldc + col0;
;                 float q = 0.f;
; #pragma unroll
;                 for (int bj = 0; bj < 2; ++bj)
; #pragma unroll
;                     for (int n = 0; n < 2; ++n) {
;                         const f32x4 rv = *(const f32x4*)(rbase + off + bj * HALF + n * 16);
;                         const f32x4 v = rv + acc[ai][bj][m][n] * scale;
;                         if (out) *(f32x4*)(out + off + bj * HALF + n * 16) = v;
;                         if (xn) { q += (v.x * v.x + v.y * v.y) + (v.z * v.z + v.w * v.w); const f32x4 o = v * wv[bj][n];
;                             u32x2 p; p.x = pk2(o.x, o.y); p.y = pk2(o.z, o.w); *(u32x2*)(xn + off + bj * HALF + n * 16) = p; }
;                     }
;                 if (xn) { q += __shfl_xor(q, 16); q += __shfl_xor(q, 32); if (fq == 0) (void)__hip_atomic_fetch_add(ss + row, q, __ATOMIC_RELAXED, __HIP_MEMORY_SCOPE_AGENT); }
;             }
	v_pk_add_f32 v[26:27], v[26:27], v[158:159]
	v_pk_add_f32 v[24:25], v[24:25], v[156:157]
	global_store_dwordx4 v[234:235], v[24:27], off
	v_pk_mul_f32 v[240:241], v[64:65], v[24:25]
	v_pk_mul_f32 v[242:243], v[66:67], v[26:27]
	v_mul_f32_e32 v173, v24, v24
	v_add_u32_e32 v240, 0x8000, v240
	v_add_u32_e32 v241, 0x8000, v241
	v_add_u32_e32 v242, 0x8000, v242
	v_add_u32_e32 v243, 0x8000, v243
	v_fmac_f32_e32 v173, v25, v25
	v_fmac_f32_e32 v173, v26, v26
	v_fmac_f32_e32 v173, v27, v27
	v_perm_b32 v230, v241, v240, s58
	v_perm_b32 v231, v243, v242, s58
	global_store_dwordx2 v[218:219], v[230:231], off
	v_pk_add_f32 v[18:19], v[18:19], v[162:163]
	v_pk_add_f32 v[16:17], v[16:17], v[160:161]
	global_store_dwordx4 v[234:235], v[16:19], off offset:512
	v_pk_mul_f32 v[244:245], v[72:73], v[16:17]
	v_pk_mul_f32 v[246:247], v[74:75], v[18:19]
	v_fmac_f32_e32 v173, v16, v16
	v_add_u32_e32 v244, 0x8000, v244
	v_add_u32_e32 v245, 0x8000, v245
	v_add_u32_e32 v246, 0x8000, v246
	v_add_u32_e32 v247, 0x8000, v247
	v_fmac_f32_e32 v173, v17, v17
	v_fmac_f32_e32 v173, v18, v18
	v_fmac_f32_e32 v173, v19, v19
	v_perm_b32 v232, v245, v244, s58
	v_perm_b32 v233, v247, v246, s58
	global_store_dwordx2 v[218:219], v[232:233], off offset:256
	v_pk_add_f32 v[30:31], v[30:31], v[178:179]
	v_pk_add_f32 v[28:29], v[28:29], v[176:177]
	global_store_dwordx4 v[236:237], v[28:31], off
	v_pk_mul_f32 v[240:241], v[76:77], v[28:29]
	v_pk_mul_f32 v[242:243], v[78:79], v[30:31]
	v_mul_f32_e32 v238, v28, v28
	v_add_u32_e32 v240, 0x8000, v240
	v_add_u32_e32 v241, 0x8000, v241
	v_add_u32_e32 v242, 0x8000, v242
	v_add_u32_e32 v243, 0x8000, v243
	v_fmac_f32_e32 v238, v29, v29
	v_fmac_f32_e32 v238, v30, v30
	v_fmac_f32_e32 v238, v31, v31
	v_perm_b32 v230, v241, v240, s58
	v_perm_b32 v231, v243, v242, s58
	global_store_dwordx2 v[220:221], v[230:231], off
	v_pk_add_f32 v[22:23], v[22:23], v[182:183]
	v_pk_add_f32 v[20:21], v[20:21], v[180:181]
	global_store_dwordx4 v[236:237], v[20:23], off offset:512
	v_pk_mul_f32 v[244:245], v[84:85], v[20:21]
	v_pk_mul_f32 v[246:247], v[86:87], v[22:23]
	v_fmac_f32_e32 v238, v20, v20
	v_add_u32_e32 v244, 0x8000, v244
	v_add_u32_e32 v245, 0x8000, v245
	v_add_u32_e32 v246, 0x8000, v246
	v_add_u32_e32 v247, 0x8000, v247
	v_fmac_f32_e32 v238, v21, v21
	v_fmac_f32_e32 v238, v22, v22
	v_fmac_f32_e32 v238, v23, v23
	v_perm_b32 v232, v245, v244, s58
	v_perm_b32 v233, v247, v246, s58
	global_store_dwordx2 v[220:221], v[232:233], off offset:256
	s_nop 1
	v_mov_b32_dpp v228, v173 row_ror:8 row_mask:0xf bank_mask:0xf
	v_mov_b32_dpp v229, v238 row_ror:8 row_mask:0xf bank_mask:0xf
	v_add_f32_e32 v173, v173, v228
	v_add_f32_e32 v238, v238, v229
	v_cndmask_b32_e64 v173, v238, v173, s[34:35]
	s_nop 0
	ds_bpermute_b32 v228, v239, v173
	s_mov_b64 vcc, 0x20000
	v_lshl_add_u64 v[234:235], v[234:235], 0, vcc
	v_lshl_add_u64 v[236:237], v[236:237], 0, vcc
	s_mov_b64 vcc, 0x10000
	v_lshl_add_u64 v[218:219], v[218:219], 0, vcc
	v_lshl_add_u64 v[220:221], v[220:221], 0, vcc
	s_waitcnt lgkmcnt(0)
	v_add_f32_e32 v173, v173, v228
	s_nop 0
	ds_bpermute_b32 v229, v248, v173
	s_waitcnt lgkmcnt(0)
	v_add_f32_e32 v173, v173, v229
	s_mov_b64 exec, s[0:1]
	global_atomic_add_f32 v[222:223], v173, off
	s_mov_b64 exec, -1
	s_mov_b64 vcc, 64
	v_lshl_add_u64 v[222:223], v[222:223], 0, vcc
	v_mov_b32_dpp v224, v8 row_ror:8 row_mask:0xf bank_mask:0xf
	v_mov_b32_dpp v225, v9 row_ror:8 row_mask:0xf bank_mask:0xf
	v_mov_b32_dpp v226, v10 row_ror:8 row_mask:0xf bank_mask:0xf
	v_mov_b32_dpp v227, v11 row_ror:8 row_mask:0xf bank_mask:0xf
	v_cndmask_b32_e64 v8, v224, v12, s[34:35]
	v_cndmask_b32_e64 v9, v225, v13, s[34:35]
	v_cndmask_b32_e64 v10, v226, v14, s[34:35]
	v_cndmask_b32_e64 v11, v227, v15, s[34:35]
	v_cndmask_b32_e64 v12, v12, v224, s[34:35]
	v_cndmask_b32_e64 v13, v13, v225, s[34:35]
	v_cndmask_b32_e64 v14, v14, v226, s[34:35]
	v_cndmask_b32_e64 v15, v15, v227, s[34:35]
	v_mov_b32_dpp v224, v0 row_ror:8 row_mask:0xf bank_mask:0xf
	v_mov_b32_dpp v225, v1 row_ror:8 row_mask:0xf bank_mask:0xf
	v_mov_b32_dpp v226, v2 row_ror:8 row_mask:0xf bank_mask:0xf
	v_mov_b32_dpp v227, v3 row_ror:8 row_mask:0xf bank_mask:0xf
	v_cndmask_b32_e64 v0, v224, v4, s[34:35]
	v_cndmask_b32_e64 v1, v225, v5, s[34:35]
	v_cndmask_b32_e64 v2, v226, v6, s[34:35]
	v_cndmask_b32_e64 v3, v227, v7, s[34:35]
	v_cndmask_b32_e64 v4, v4, v224, s[34:35]
	v_cndmask_b32_e64 v5, v5, v225, s[34:35]
	v_cndmask_b32_e64 v6, v6, v226, s[34:35]
	v_cndmask_b32_e64 v7, v7, v227, s[34:35]
	s_waitcnt vmcnt(19)
; #define PG8_BAR __builtin_amdgcn_s_barrier()
;     __device__ __forceinline__ void operator()(const f32x4 (&acc)[2][2][4][2], const Unit& u, int wr, int wc, int fr, int fq) const {
;     ...
;                 for (int bj = 0; bj < 2; ++bj)
; #pragma unroll
;                     for (int n = 0; n < 2; ++n) {
;                         const f32x4 rv = *(const f32x4*)(rbase + off + bj * HALF + n * 16);
;                         const f32x4 v = rv + acc[ai][bj][m][n] * scale;
;                         if (out) *(f32x4*)(out + off + bj * HALF + n * 16) = v;
;                         if (xn) { q += (v.x * v.x + v.y * v.y) + (v.z * v.z + v.w * v.w); const f32x4 o = v * wv[bj][n];
;                             u32x2 p; p.x = pk2(o.x, o.y); p.y = pk2(o.z, o.w); *(u32x2*)(xn + off + bj * HALF + n * 16) = p; }
;                     }
;                 if (xn) { q += __shfl_xor(q, 16); q += __shfl_xor(q, 32); if (fq == 0) (void)__hip_atomic_fetch_add(ss + row, q, __ATOMIC_RELAXED, __HIP_MEMORY_SCOPE_AGENT); }
; template <class Epi, bool ALIGN_EPI>
; __device__ __forceinline__ void gemm_phase(LAS unsigned char* lds, const Gemm g, const StaticOrder& S, const Epi& E) {
;     ...
;         if (!has_next) break;
; #pragma unroll
;         for (int a = 0; a < 2; ++a)
; #pragma unroll
;             for (int b = 0; b < 2; ++b)
; #pragma unroll
;                 for (int m = 0; m < 4; ++m)
; #pragma unroll
;                     for (int n = 0; n < 2; ++n) acc[a][b][m][n] = (f32x4){0.f, 0.f, 0.f, 0.f};
;         cur = nxt; cA = nA; cB = nB; ++ui;
;         if constexpr (ALIGN_EPI) { if (wr == 1) PG8_BAR; }
	v_pk_add_f32 v[10:11], v[10:11], v[186:187]
	v_pk_add_f32 v[8:9], v[8:9], v[184:185]
	global_store_dwordx4 v[234:235], v[8:11], off
	v_pk_mul_f32 v[240:241], v[64:65], v[8:9]
	v_pk_mul_f32 v[242:243], v[66:67], v[10:11]
	v_mul_f32_e32 v173, v8, v8
	v_add_u32_e32 v240, 0x8000, v240
	v_add_u32_e32 v241, 0x8000, v241
	v_add_u32_e32 v242, 0x8000, v242
	v_add_u32_e32 v243, 0x8000, v243
	v_fmac_f32_e32 v173, v9, v9
	v_fmac_f32_e32 v173, v10, v10
	v_fmac_f32_e32 v173, v11, v11
	v_perm_b32 v230, v241, v240, s58
	v_perm_b32 v231, v243, v242, s58
	global_store_dwordx2 v[218:219], v[230:231], off
	v_pk_add_f32 v[2:3], v[2:3], v[190:191]
	v_pk_add_f32 v[0:1], v[0:1], v[188:189]
	global_store_dwordx4 v[234:235], v[0:3], off offset:512
	v_pk_mul_f32 v[244:245], v[72:73], v[0:1]
	v_pk_mul_f32 v[246:247], v[74:75], v[2:3]
	v_fmac_f32_e32 v173, v0, v0
	v_add_u32_e32 v244, 0x8000, v244
	v_add_u32_e32 v245, 0x8000, v245
	v_add_u32_e32 v246, 0x8000, v246
	v_add_u32_e32 v247, 0x8000, v247
	v_fmac_f32_e32 v173, v1, v1
	v_fmac_f32_e32 v173, v2, v2
	v_fmac_f32_e32 v173, v3, v3
	v_perm_b32 v232, v245, v244, s58
	v_perm_b32 v233, v247, v246, s58
	global_store_dwordx2 v[218:219], v[232:233], off offset:256
	v_pk_add_f32 v[14:15], v[14:15], v[194:195]
	v_pk_add_f32 v[12:13], v[12:13], v[192:193]
	global_store_dwordx4 v[236:237], v[12:15], off
	v_pk_mul_f32 v[240:241], v[76:77], v[12:13]
	v_pk_mul_f32 v[242:243], v[78:79], v[14:15]
	v_mul_f32_e32 v238, v12, v12
	v_add_u32_e32 v240, 0x8000, v240
	v_add_u32_e32 v241, 0x8000, v241
	v_add_u32_e32 v242, 0x8000, v242
	v_add_u32_e32 v243, 0x8000, v243
	v_fmac_f32_e32 v238, v13, v13
	v_fmac_f32_e32 v238, v14, v14
	v_fmac_f32_e32 v238, v15, v15
	v_perm_b32 v230, v241, v240, s58
	v_perm_b32 v231, v243, v242, s58
	global_store_dwordx2 v[220:221], v[230:231], off
	v_pk_add_f32 v[6:7], v[6:7], v[198:199]
	v_pk_add_f32 v[4:5], v[4:5], v[196:197]
	global_store_dwordx4 v[236:237], v[4:7], off offset:512
	v_pk_mul_f32 v[244:245], v[84:85], v[4:5]
	v_pk_mul_f32 v[246:247], v[86:87], v[6:7]
	v_fmac_f32_e32 v238, v4, v4
	v_add_u32_e32 v244, 0x8000, v244
	v_add_u32_e32 v245, 0x8000, v245
	v_add_u32_e32 v246, 0x8000, v246
	v_add_u32_e32 v247, 0x8000, v247
	v_fmac_f32_e32 v238, v5, v5
	v_fmac_f32_e32 v238, v6, v6
	v_fmac_f32_e32 v238, v7, v7
	v_perm_b32 v232, v245, v244, s58
	v_perm_b32 v233, v247, v246, s58
	global_store_dwordx2 v[220:221], v[232:233], off offset:256
	s_nop 1
	v_mov_b32_dpp v228, v173 row_ror:8 row_mask:0xf bank_mask:0xf
	v_mov_b32_dpp v229, v238 row_ror:8 row_mask:0xf bank_mask:0xf
	v_add_f32_e32 v173, v173, v228
	v_add_f32_e32 v238, v238, v229
	v_cndmask_b32_e64 v173, v238, v173, s[34:35]
	s_nop 0
	ds_bpermute_b32 v228, v239, v173
	s_waitcnt lgkmcnt(0)
	v_add_f32_e32 v173, v173, v228
	s_nop 0
	ds_bpermute_b32 v229, v248, v173
	s_waitcnt lgkmcnt(0)
	v_add_f32_e32 v173, v173, v229
	s_mov_b64 exec, s[0:1]
	global_atomic_add_f32 v[222:223], v173, off
	s_mov_b64 exec, -1
	s_andn2_b64 vcc, exec, s[6:7]
	s_mov_b64 s[4:5], -1
	s_cbranch_vccnz .LBB0_1078
	s_andn2_b64 vcc, exec, s[12:13]
	s_cbranch_vccnz .LBB0_1077
	s_barrier
	s_branch .LBB0_1077

;     __device__ __forceinline__ void operator()(const f32x4 (&acc)[2][2][4][2], const Unit& u, int wr, int wc, int fr, int fq) const {
;         const int row0 = u.pm * BM + wr * 64 + fr, col0 = u.pn * BM + wc * 32 + 4 * fq;
;         const float* rbase = (u.pm * BM < SEQ_P) ? resA : (resB - (size_t)SEQ_P * ldc);
;         f32x4 wv[2][2];
;         if (xn) {
; #pragma unroll
;             for (int bj = 0; bj < 2; ++bj)
; #pragma unroll
;                 for (int n = 0; n < 2; ++n) wv[bj][n] = *(const f32x4*)(wn + col0 + bj * HALF + n * 16);
;         }
; #pragma unroll
;         for (int ai = 0; ai < 2; ++ai)
; #pragma unroll
;             for (int m = 0; m < 4; ++m) {
;                 const int row = row0 + ai * HALF + m * 16;
;                 const size_t off = (size_t)row * ldc + col0;
;                 float q = 0.f;
; #pragma unroll
;                 for (int bj = 0; bj < 2; ++bj)
; #pragma unroll
;                     for (int n = 0; n < 2; ++n) {
;                         const f32x4 rv = *(const f32x4*)(rbase + off + bj * HALF + n * 16);
;                         const f32x4 v = rv + acc[ai][bj][m][n] * scale;
;                         if (out) *(f32x4*)(out + off + bj * HALF + n * 16) = v;
;                         if (xn) { q += (v.x * v.x + v.y * v.y) + (v.z * v.z + v.w * v.w); const f32x4 o = v * wv[bj][n];
;                             u32x2 p; p.x = pk2(o.x, o.y); p.y = pk2(o.z, o.w); *(u32x2*)(xn + off + bj * HALF + n * 16) = p; }
;                     }
;                 if (xn) { q += __shfl_xor(q, 16); q += __shfl_xor(q, 32); if (fq == 0) (void)__hip_atomic_fetch_add(ss + row, q, __ATOMIC_RELAXED, __HIP_MEMORY_SCOPE_AGENT); }
.LBB0_1382:
	v_lshl_add_u32 v226, s54, 8, v160
	v_lshl_or_b32 v228, s53, 8, v162
	v_and_b32_e32 v244, 8, v167
	v_mov_b32_e32 v227, 0
	v_cmp_eq_u32_e64 s[24:25], 0, v244
	v_lshlrev_b32_e32 v240, 1, v244
	v_add_u32_e32 v230, v228, v240
	v_sub_u32_e32 v241, 16, v240
	v_add_u32_e32 v241, v228, v241
	v_mov_b32_e32 v228, v230
	v_mov_b32_e32 v230, v241
	v_mov_b32_e32 v229, 0
	v_mov_b32_e32 v231, 0
	v_sub_u32_e32 v224, v226, v244
	v_mov_b32_e32 v225, 0
	v_lshlrev_b64 v[222:223], 11, v[224:225]
	v_add_u32_e32 v224, 8, v224
	v_lshlrev_b64 v[224:225], 11, v[224:225]
	v_lshl_add_u64 v[222:223], v[222:223], 0, v[228:229]
	v_lshl_add_u64 v[224:225], v[224:225], 0, v[230:231]
	v_lshl_add_u64 v[212:213], v[222:223], 2, s[8:9]
	v_lshl_add_u64 v[214:215], v[224:225], 2, s[8:9]
	v_lshl_add_u64 v[216:217], v[228:229], 2, s[10:11]
	v_lshl_add_u64 v[218:219], v[230:231], 2, s[10:11]
	global_load_dwordx4 v[72:75], v[216:217], off
	global_load_dwordx4 v[84:87], v[216:217], off offset:512
	global_load_dwordx4 v[88:91], v[218:219], off
	global_load_dwordx4 v[96:99], v[218:219], off offset:512
	global_load_dwordx4 v[156:159], v[212:213], off
	global_load_dwordx4 v[168:171], v[212:213], off offset:512
	global_load_dwordx4 v[172:175], v[214:215], off
	global_load_dwordx4 v[176:179], v[214:215], off offset:512
	s_mov_b64 vcc, 0x20000
	v_lshl_add_u64 v[212:213], v[212:213], 0, vcc
	v_lshl_add_u64 v[214:215], v[214:215], 0, vcc
	global_load_dwordx4 v[180:183], v[212:213], off
	global_load_dwordx4 v[184:187], v[212:213], off offset:512
	global_load_dwordx4 v[188:191], v[214:215], off
	global_load_dwordx4 v[192:195], v[214:215], off offset:512
	s_mov_b64 vcc, 0x20000
	v_lshl_add_u64 v[212:213], v[212:213], 0, vcc
	v_lshl_add_u64 v[214:215], v[214:215], 0, vcc
	global_load_dwordx4 v[196:199], v[212:213], off
	global_load_dwordx4 v[200:203], v[212:213], off offset:512
	global_load_dwordx4 v[204:207], v[214:215], off
	global_load_dwordx4 v[208:211], v[214:215], off offset:512
	s_mov_b64 vcc, 0x20000
	v_lshl_add_u64 v[212:213], v[212:213], 0, vcc
	v_lshl_add_u64 v[214:215], v[214:215], 0, vcc
	v_lshl_add_u64 v[216:217], v[222:223], 1, s[14:15]
	v_lshl_add_u64 v[218:219], v[224:225], 1, s[14:15]
	v_lshl_add_u64 v[220:221], v[226:227], 2, s[16:17]
	v_xor_b32_e32 v242, 16, v167
	v_xor_b32_e32 v243, 32, v167
	v_lshlrev_b32_e32 v242, 2, v242
	v_lshlrev_b32_e32 v243, 2, v243
	v_mov_b32_dpp v222, v136 row_ror:8 row_mask:0xf bank_mask:0xf
	v_mov_b32_dpp v223, v137 row_ror:8 row_mask:0xf bank_mask:0xf
	v_mov_b32_dpp v224, v138 row_ror:8 row_mask:0xf bank_mask:0xf
	v_mov_b32_dpp v225, v139 row_ror:8 row_mask:0xf bank_mask:0xf
	v_cndmask_b32_e64 v136, v222, v140, s[24:25]
	v_cndmask_b32_e64 v137, v223, v141, s[24:25]
	v_cndmask_b32_e64 v138, v224, v142, s[24:25]
	v_cndmask_b32_e64 v139, v225, v143, s[24:25]
	v_cndmask_b32_e64 v140, v140, v222, s[24:25]
	v_cndmask_b32_e64 v141, v141, v223, s[24:25]
	v_cndmask_b32_e64 v142, v142, v224, s[24:25]
	v_cndmask_b32_e64 v143, v143, v225, s[24:25]
	v_mov_b32_dpp v222, v128 row_ror:8 row_mask:0xf bank_mask:0xf
	v_mov_b32_dpp v223, v129 row_ror:8 row_mask:0xf bank_mask:0xf
	v_mov_b32_dpp v224, v130 row_ror:8 row_mask:0xf bank_mask:0xf
	v_mov_b32_dpp v225, v131 row_ror:8 row_mask:0xf bank_mask:0xf
	v_cndmask_b32_e64 v128, v222, v132, s[24:25]
	v_cndmask_b32_e64 v129, v223, v133, s[24:25]
	v_cndmask_b32_e64 v130, v224, v134, s[24:25]
	v_cndmask_b32_e64 v131, v225, v135, s[24:25]
	v_cndmask_b32_e64 v132, v132, v222, s[24:25]
	v_cndmask_b32_e64 v133, v133, v223, s[24:25]
	v_cndmask_b32_e64 v134, v134, v224, s[24:25]
	v_cndmask_b32_e64 v135, v135, v225, s[24:25]
	s_waitcnt vmcnt(8)
	v_pk_fma_f32 v[138:139], v[138:139], 0.5, v[158:159] op_sel_hi:[1,0,1]
	v_pk_fma_f32 v[136:137], v[136:137], 0.5, v[156:157] op_sel_hi:[1,0,1]
	v_pk_mul_f32 v[232:233], v[72:73], v[136:137]
	v_pk_mul_f32 v[234:235], v[74:75], v[138:139]
	v_mul_f32_e32 v240, v136, v136
	v_add_u32_e32 v232, 0x8000, v232
	v_add_u32_e32 v233, 0x8000, v233
	v_add_u32_e32 v234, 0x8000, v234
	v_add_u32_e32 v235, 0x8000, v235
	v_fmac_f32_e32 v240, v137, v137
	v_fmac_f32_e32 v240, v138, v138
	v_fmac_f32_e32 v240, v139, v139
	v_perm_b32 v228, v233, v232, s50
	v_perm_b32 v229, v235, v234, s50
	global_store_dwordx2 v[216:217], v[228:229], off
	v_pk_fma_f32 v[130:131], v[130:131], 0.5, v[170:171] op_sel_hi:[1,0,1]
	v_pk_fma_f32 v[128:129], v[128:129], 0.5, v[168:169] op_sel_hi:[1,0,1]
	v_pk_mul_f32 v[236:237], v[84:85], v[128:129]
	v_pk_mul_f32 v[238:239], v[86:87], v[130:131]
	v_fmac_f32_e32 v240, v128, v128
	v_add_u32_e32 v236, 0x8000, v236
	v_add_u32_e32 v237, 0x8000, v237
	v_add_u32_e32 v238, 0x8000, v238
	v_add_u32_e32 v239, 0x8000, v239
	v_fmac_f32_e32 v240, v129, v129
	v_fmac_f32_e32 v240, v130, v130
	v_fmac_f32_e32 v240, v131, v131
	v_perm_b32 v230, v237, v236, s50
	v_perm_b32 v231, v239, v238, s50
	global_store_dwordx2 v[216:217], v[230:231], off offset:256
	v_pk_fma_f32 v[142:143], v[142:143], 0.5, v[174:175] op_sel_hi:[1,0,1]
	v_pk_fma_f32 v[140:141], v[140:141], 0.5, v[172:173] op_sel_hi:[1,0,1]
	v_pk_mul_f32 v[232:233], v[88:89], v[140:141]
	v_pk_mul_f32 v[234:235], v[90:91], v[142:143]
	v_mul_f32_e32 v241, v140, v140
	v_add_u32_e32 v232, 0x8000, v232
	v_add_u32_e32 v233, 0x8000, v233
	v_add_u32_e32 v234, 0x8000, v234
	v_add_u32_e32 v235, 0x8000, v235
	v_fmac_f32_e32 v241, v141, v141
	v_fmac_f32_e32 v241, v142, v142
	v_fmac_f32_e32 v241, v143, v143
	v_perm_b32 v228, v233, v232, s50
	v_perm_b32 v229, v235, v234, s50
	global_store_dwordx2 v[218:219], v[228:229], off
	v_pk_fma_f32 v[134:135], v[134:135], 0.5, v[178:179] op_sel_hi:[1,0,1]
	v_pk_fma_f32 v[132:133], v[132:133], 0.5, v[176:177] op_sel_hi:[1,0,1]
	v_pk_mul_f32 v[236:237], v[96:97], v[132:133]
	v_pk_mul_f32 v[238:239], v[98:99], v[134:135]
	v_fmac_f32_e32 v241, v132, v132
	v_add_u32_e32 v236, 0x8000, v236
	v_add_u32_e32 v237, 0x8000, v237
	v_add_u32_e32 v238, 0x8000, v238
	v_add_u32_e32 v239, 0x8000, v239
	v_fmac_f32_e32 v241, v133, v133
	v_fmac_f32_e32 v241, v134, v134
	v_fmac_f32_e32 v241, v135, v135
	v_perm_b32 v230, v237, v236, s50
	v_perm_b32 v231, v239, v238, s50
	global_store_dwordx2 v[218:219], v[230:231], off offset:256
	s_nop 1
	v_mov_b32_dpp v226, v240 row_ror:8 row_mask:0xf bank_mask:0xf
	v_mov_b32_dpp v227, v241 row_ror:8 row_mask:0xf bank_mask:0xf
	v_add_f32_e32 v240, v240, v226
	v_add_f32_e32 v241, v241, v227
	v_cndmask_b32_e64 v240, v241, v240, s[24:25]
	s_nop 0
	ds_bpermute_b32 v226, v242, v240
	global_load_dwordx4 v[156:159], v[212:213], off
	global_load_dwordx4 v[168:171], v[212:213], off offset:512
	global_load_dwordx4 v[172:175], v[214:215], off
	global_load_dwordx4 v[176:179], v[214:215], off offset:512
	s_mov_b64 vcc, 0xa0000
	v_lshl_add_u64 v[212:213], v[212:213], 0, vcc
	v_lshl_add_u64 v[214:215], v[214:215], 0, vcc
	s_mov_b64 vcc, 0x20000
	s_mov_b64 vcc, 0x10000
	v_lshl_add_u64 v[216:217], v[216:217], 0, vcc
	v_lshl_add_u64 v[218:219], v[218:219], 0, vcc
	s_waitcnt lgkmcnt(0)
;     __device__ __forceinline__ void operator()(const f32x4 (&acc)[2][2][4][2], const Unit& u, int wr, int wc, int fr, int fq) const {
;     ...
;         for (int ai = 0; ai < 2; ++ai)
; #pragma unroll
;             for (int m = 0; m < 4; ++m) {
;                 const int row = row0 + ai * HALF + m * 16;
;                 const size_t off = (size_t)row * ldc + col0;
;                 float q = 0.f;
; #pragma unroll
;                 for (int bj = 0; bj < 2; ++bj)
; #pragma unroll
;                     for (int n = 0; n < 2; ++n) {
;                         const f32x4 rv = *(const f32x4*)(rbase + off + bj * HALF + n * 16);
;                         const f32x4 v = rv + acc[ai][bj][m][n] * scale;
;                         if (out) *(f32x4*)(out + off + bj * HALF + n * 16) = v;
;                         if (xn) { q += (v.x * v.x + v.y * v.y) + (v.z * v.z + v.w * v.w); const f32x4 o = v * wv[bj][n];
;                             u32x2 p; p.x = pk2(o.x, o.y); p.y = pk2(o.z, o.w); *(u32x2*)(xn + off + bj * HALF + n * 16) = p; }
;                     }
;                 if (xn) { q += __shfl_xor(q, 16); q += __shfl_xor(q, 32); if (fq == 0) (void)__hip_atomic_fetch_add(ss + row, q, __ATOMIC_RELAXED, __HIP_MEMORY_SCOPE_AGENT); }
	v_add_f32_e32 v240, v240, v226
	s_nop 0
	ds_bpermute_b32 v227, v243, v240
	s_waitcnt lgkmcnt(0)
	v_add_f32_e32 v240, v240, v227
	s_mov_b64 exec, s[0:1]
	global_atomic_add_f32 v[220:221], v240, off
	s_mov_b64 exec, -1
	s_mov_b64 vcc, 64
	v_lshl_add_u64 v[220:221], v[220:221], 0, vcc
	v_mov_b32_dpp v222, v120 row_ror:8 row_mask:0xf bank_mask:0xf
	v_mov_b32_dpp v223, v121 row_ror:8 row_mask:0xf bank_mask:0xf
	v_mov_b32_dpp v224, v122 row_ror:8 row_mask:0xf bank_mask:0xf
	v_mov_b32_dpp v225, v123 row_ror:8 row_mask:0xf bank_mask:0xf
	v_cndmask_b32_e64 v120, v222, v124, s[24:25]
	v_cndmask_b32_e64 v121, v223, v125, s[24:25]
	v_cndmask_b32_e64 v122, v224, v126, s[24:25]
	v_cndmask_b32_e64 v123, v225, v127, s[24:25]
	v_cndmask_b32_e64 v124, v124, v222, s[24:25]
	v_cndmask_b32_e64 v125, v125, v223, s[24:25]
	v_cndmask_b32_e64 v126, v126, v224, s[24:25]
	v_cndmask_b32_e64 v127, v127, v225, s[24:25]
	v_mov_b32_dpp v222, v112 row_ror:8 row_mask:0xf bank_mask:0xf
	v_mov_b32_dpp v223, v113 row_ror:8 row_mask:0xf bank_mask:0xf
	v_mov_b32_dpp v224, v114 row_ror:8 row_mask:0xf bank_mask:0xf
	v_mov_b32_dpp v225, v115 row_ror:8 row_mask:0xf bank_mask:0xf
	v_cndmask_b32_e64 v112, v222, v116, s[24:25]
	v_cndmask_b32_e64 v113, v223, v117, s[24:25]
	v_cndmask_b32_e64 v114, v224, v118, s[24:25]
	v_cndmask_b32_e64 v115, v225, v119, s[24:25]
	v_cndmask_b32_e64 v116, v116, v222, s[24:25]
	v_cndmask_b32_e64 v117, v117, v223, s[24:25]
	v_cndmask_b32_e64 v118, v118, v224, s[24:25]
	v_cndmask_b32_e64 v119, v119, v225, s[24:25]
	s_waitcnt vmcnt(13)
	v_pk_fma_f32 v[122:123], v[122:123], 0.5, v[182:183] op_sel_hi:[1,0,1]
	v_pk_fma_f32 v[120:121], v[120:121], 0.5, v[180:181] op_sel_hi:[1,0,1]
	v_pk_mul_f32 v[232:233], v[72:73], v[120:121]
	v_pk_mul_f32 v[234:235], v[74:75], v[122:123]
	v_mul_f32_e32 v240, v120, v120
	v_add_u32_e32 v232, 0x8000, v232
	v_add_u32_e32 v233, 0x8000, v233
	v_add_u32_e32 v234, 0x8000, v234
	v_add_u32_e32 v235, 0x8000, v235
	v_fmac_f32_e32 v240, v121, v121
	v_fmac_f32_e32 v240, v122, v122
	v_fmac_f32_e32 v240, v123, v123
	v_perm_b32 v228, v233, v232, s50
	v_perm_b32 v229, v235, v234, s50
	global_store_dwordx2 v[216:217], v[228:229], off
	v_pk_fma_f32 v[114:115], v[114:115], 0.5, v[186:187] op_sel_hi:[1,0,1]
	v_pk_fma_f32 v[112:113], v[112:113], 0.5, v[184:185] op_sel_hi:[1,0,1]
	v_pk_mul_f32 v[236:237], v[84:85], v[112:113]
	v_pk_mul_f32 v[238:239], v[86:87], v[114:115]
	v_fmac_f32_e32 v240, v112, v112
	v_add_u32_e32 v236, 0x8000, v236
	v_add_u32_e32 v237, 0x8000, v237
	v_add_u32_e32 v238, 0x8000, v238
	v_add_u32_e32 v239, 0x8000, v239
	v_fmac_f32_e32 v240, v113, v113
	v_fmac_f32_e32 v240, v114, v114
	v_fmac_f32_e32 v240, v115, v115
	v_perm_b32 v230, v237, v236, s50
	v_perm_b32 v231, v239, v238, s50
	global_store_dwordx2 v[216:217], v[230:231], off offset:256
	v_pk_fma_f32 v[126:127], v[126:127], 0.5, v[190:191] op_sel_hi:[1,0,1]
	v_pk_fma_f32 v[124:125], v[124:125], 0.5, v[188:189] op_sel_hi:[1,0,1]
	v_pk_mul_f32 v[232:233], v[88:89], v[124:125]
	v_pk_mul_f32 v[234:235], v[90:91], v[126:127]
	v_mul_f32_e32 v241, v124, v124
	v_add_u32_e32 v232, 0x8000, v232
	v_add_u32_e32 v233, 0x8000, v233
	v_add_u32_e32 v234, 0x8000, v234
	v_add_u32_e32 v235, 0x8000, v235
	v_fmac_f32_e32 v241, v125, v125
	v_fmac_f32_e32 v241, v126, v126
	v_fmac_f32_e32 v241, v127, v127
	v_perm_b32 v228, v233, v232, s50
	v_perm_b32 v229, v235, v234, s50
	global_store_dwordx2 v[218:219], v[228:229], off
	v_pk_fma_f32 v[118:119], v[118:119], 0.5, v[194:195] op_sel_hi:[1,0,1]
	v_pk_fma_f32 v[116:117], v[116:117], 0.5, v[192:193] op_sel_hi:[1,0,1]
	v_pk_mul_f32 v[236:237], v[96:97], v[116:117]
	v_pk_mul_f32 v[238:239], v[98:99], v[118:119]
	v_fmac_f32_e32 v241, v116, v116
	v_add_u32_e32 v236, 0x8000, v236
	v_add_u32_e32 v237, 0x8000, v237
	v_add_u32_e32 v238, 0x8000, v238
	v_add_u32_e32 v239, 0x8000, v239
	v_fmac_f32_e32 v241, v117, v117
	v_fmac_f32_e32 v241, v118, v118
	v_fmac_f32_e32 v241, v119, v119
	v_perm_b32 v230, v237, v236, s50
	v_perm_b32 v231, v239, v238, s50
	global_store_dwordx2 v[218:219], v[230:231], off offset:256
	s_nop 1
	v_mov_b32_dpp v226, v240 row_ror:8 row_mask:0xf bank_mask:0xf
	v_mov_b32_dpp v227, v241 row_ror:8 row_mask:0xf bank_mask:0xf
	v_add_f32_e32 v240, v240, v226
	v_add_f32_e32 v241, v241, v227
	v_cndmask_b32_e64 v240, v241, v240, s[24:25]
	s_nop 0
	ds_bpermute_b32 v226, v242, v240
	global_load_dwordx4 v[180:183], v[212:213], off
	global_load_dwordx4 v[184:187], v[212:213], off offset:512
	global_load_dwordx4 v[188:191], v[214:215], off
	global_load_dwordx4 v[192:195], v[214:215], off offset:512
	s_mov_b64 vcc, 0x20000
	v_lshl_add_u64 v[212:213], v[212:213], 0, vcc
	v_lshl_add_u64 v[214:215], v[214:215], 0, vcc
	s_mov_b64 vcc, 0x20000
	s_mov_b64 vcc, 0x10000
	v_lshl_add_u64 v[216:217], v[216:217], 0, vcc
	v_lshl_add_u64 v[218:219], v[218:219], 0, vcc
	s_waitcnt lgkmcnt(0)
	v_add_f32_e32 v240, v240, v226
	s_nop 0
	ds_bpermute_b32 v227, v243, v240
	s_waitcnt lgkmcnt(0)
;     __device__ __forceinline__ void operator()(const f32x4 (&acc)[2][2][4][2], const Unit& u, int wr, int wc, int fr, int fq) const {
;     ...
;         for (int ai = 0; ai < 2; ++ai)
; #pragma unroll
;             for (int m = 0; m < 4; ++m) {
;                 const int row = row0 + ai * HALF + m * 16;
;                 const size_t off = (size_t)row * ldc + col0;
;                 float q = 0.f;
; #pragma unroll
;                 for (int bj = 0; bj < 2; ++bj)
; #pragma unroll
;                     for (int n = 0; n < 2; ++n) {
;                         const f32x4 rv = *(const f32x4*)(rbase + off + bj * HALF + n * 16);
;                         const f32x4 v = rv + acc[ai][bj][m][n] * scale;
;                         if (out) *(f32x4*)(out + off + bj * HALF + n * 16) = v;
;                         if (xn) { q += (v.x * v.x + v.y * v.y) + (v.z * v.z + v.w * v.w); const f32x4 o = v * wv[bj][n];
;                             u32x2 p; p.x = pk2(o.x, o.y); p.y = pk2(o.z, o.w); *(u32x2*)(xn + off + bj * HALF + n * 16) = p; }
;                     }
;                 if (xn) { q += __shfl_xor(q, 16); q += __shfl_xor(q, 32); if (fq == 0) (void)__hip_atomic_fetch_add(ss + row, q, __ATOMIC_RELAXED, __HIP_MEMORY_SCOPE_AGENT); }
	v_add_f32_e32 v240, v240, v227
	s_mov_b64 exec, s[0:1]
	global_atomic_add_f32 v[220:221], v240, off
	s_mov_b64 exec, -1
	s_mov_b64 vcc, 64
	v_lshl_add_u64 v[220:221], v[220:221], 0, vcc
	v_mov_b32_dpp v222, v104 row_ror:8 row_mask:0xf bank_mask:0xf
	v_mov_b32_dpp v223, v105 row_ror:8 row_mask:0xf bank_mask:0xf
	v_mov_b32_dpp v224, v106 row_ror:8 row_mask:0xf bank_mask:0xf
	v_mov_b32_dpp v225, v107 row_ror:8 row_mask:0xf bank_mask:0xf
	v_cndmask_b32_e64 v104, v222, v108, s[24:25]
	v_cndmask_b32_e64 v105, v223, v109, s[24:25]
	v_cndmask_b32_e64 v106, v224, v110, s[24:25]
	v_cndmask_b32_e64 v107, v225, v111, s[24:25]
	v_cndmask_b32_e64 v108, v108, v222, s[24:25]
	v_cndmask_b32_e64 v109, v109, v223, s[24:25]
	v_cndmask_b32_e64 v110, v110, v224, s[24:25]
	v_cndmask_b32_e64 v111, v111, v225, s[24:25]
	v_mov_b32_dpp v222, v92 row_ror:8 row_mask:0xf bank_mask:0xf
	v_mov_b32_dpp v223, v93 row_ror:8 row_mask:0xf bank_mask:0xf
	v_mov_b32_dpp v224, v94 row_ror:8 row_mask:0xf bank_mask:0xf
	v_mov_b32_dpp v225, v95 row_ror:8 row_mask:0xf bank_mask:0xf
	v_cndmask_b32_e64 v92, v222, v100, s[24:25]
	v_cndmask_b32_e64 v93, v223, v101, s[24:25]
	v_cndmask_b32_e64 v94, v224, v102, s[24:25]
	v_cndmask_b32_e64 v95, v225, v103, s[24:25]
	v_cndmask_b32_e64 v100, v100, v222, s[24:25]
	v_cndmask_b32_e64 v101, v101, v223, s[24:25]
	v_cndmask_b32_e64 v102, v102, v224, s[24:25]
	v_cndmask_b32_e64 v103, v103, v225, s[24:25]
	s_waitcnt vmcnt(18)
	v_pk_fma_f32 v[106:107], v[106:107], 0.5, v[198:199] op_sel_hi:[1,0,1]
	v_pk_fma_f32 v[104:105], v[104:105], 0.5, v[196:197] op_sel_hi:[1,0,1]
	v_pk_mul_f32 v[232:233], v[72:73], v[104:105]
	v_pk_mul_f32 v[234:235], v[74:75], v[106:107]
	v_mul_f32_e32 v240, v104, v104
	v_add_u32_e32 v232, 0x8000, v232
	v_add_u32_e32 v233, 0x8000, v233
	v_add_u32_e32 v234, 0x8000, v234
	v_add_u32_e32 v235, 0x8000, v235
	v_fmac_f32_e32 v240, v105, v105
	v_fmac_f32_e32 v240, v106, v106
	v_fmac_f32_e32 v240, v107, v107
	v_perm_b32 v228, v233, v232, s50
	v_perm_b32 v229, v235, v234, s50
	global_store_dwordx2 v[216:217], v[228:229], off
	v_pk_fma_f32 v[94:95], v[94:95], 0.5, v[202:203] op_sel_hi:[1,0,1]
	v_pk_fma_f32 v[92:93], v[92:93], 0.5, v[200:201] op_sel_hi:[1,0,1]
	v_pk_mul_f32 v[236:237], v[84:85], v[92:93]
	v_pk_mul_f32 v[238:239], v[86:87], v[94:95]
	v_fmac_f32_e32 v240, v92, v92
	v_add_u32_e32 v236, 0x8000, v236
	v_add_u32_e32 v237, 0x8000, v237
	v_add_u32_e32 v238, 0x8000, v238
	v_add_u32_e32 v239, 0x8000, v239
	v_fmac_f32_e32 v240, v93, v93
	v_fmac_f32_e32 v240, v94, v94
	v_fmac_f32_e32 v240, v95, v95
	v_perm_b32 v230, v237, v236, s50
	v_perm_b32 v231, v239, v238, s50
	global_store_dwordx2 v[216:217], v[230:231], off offset:256
	v_pk_fma_f32 v[110:111], v[110:111], 0.5, v[206:207] op_sel_hi:[1,0,1]
	v_pk_fma_f32 v[108:109], v[108:109], 0.5, v[204:205] op_sel_hi:[1,0,1]
	v_pk_mul_f32 v[232:233], v[88:89], v[108:109]
	v_pk_mul_f32 v[234:235], v[90:91], v[110:111]
	v_mul_f32_e32 v241, v108, v108
	v_add_u32_e32 v232, 0x8000, v232
	v_add_u32_e32 v233, 0x8000, v233
	v_add_u32_e32 v234, 0x8000, v234
	v_add_u32_e32 v235, 0x8000, v235
	v_fmac_f32_e32 v241, v109, v109
	v_fmac_f32_e32 v241, v110, v110
	v_fmac_f32_e32 v241, v111, v111
	v_perm_b32 v228, v233, v232, s50
	v_perm_b32 v229, v235, v234, s50
	global_store_dwordx2 v[218:219], v[228:229], off
	v_pk_fma_f32 v[102:103], v[102:103], 0.5, v[210:211] op_sel_hi:[1,0,1]
	v_pk_fma_f32 v[100:101], v[100:101], 0.5, v[208:209] op_sel_hi:[1,0,1]
	v_pk_mul_f32 v[236:237], v[96:97], v[100:101]
	v_pk_mul_f32 v[238:239], v[98:99], v[102:103]
	v_fmac_f32_e32 v241, v100, v100
	v_add_u32_e32 v236, 0x8000, v236
	v_add_u32_e32 v237, 0x8000, v237
	v_add_u32_e32 v238, 0x8000, v238
	v_add_u32_e32 v239, 0x8000, v239
	v_fmac_f32_e32 v241, v101, v101
	v_fmac_f32_e32 v241, v102, v102
	v_fmac_f32_e32 v241, v103, v103
	v_perm_b32 v230, v237, v236, s50
	v_perm_b32 v231, v239, v238, s50
	global_store_dwordx2 v[218:219], v[230:231], off offset:256
	s_nop 1
	v_mov_b32_dpp v226, v240 row_ror:8 row_mask:0xf bank_mask:0xf
	v_mov_b32_dpp v227, v241 row_ror:8 row_mask:0xf bank_mask:0xf
	v_add_f32_e32 v240, v240, v226
	v_add_f32_e32 v241, v241, v227
	v_cndmask_b32_e64 v240, v241, v240, s[24:25]
	s_nop 0
	ds_bpermute_b32 v226, v242, v240
	global_load_dwordx4 v[196:199], v[212:213], off
	global_load_dwordx4 v[200:203], v[212:213], off offset:512
	global_load_dwordx4 v[204:207], v[214:215], off
	global_load_dwordx4 v[208:211], v[214:215], off offset:512
	s_mov_b64 vcc, 0x20000
	v_lshl_add_u64 v[212:213], v[212:213], 0, vcc
	v_lshl_add_u64 v[214:215], v[214:215], 0, vcc
	s_mov_b64 vcc, 0x20000
	s_mov_b64 vcc, 0x10000
	v_lshl_add_u64 v[216:217], v[216:217], 0, vcc
	v_lshl_add_u64 v[218:219], v[218:219], 0, vcc
	s_waitcnt lgkmcnt(0)
	v_add_f32_e32 v240, v240, v226
	s_nop 0
	ds_bpermute_b32 v227, v243, v240
	s_waitcnt lgkmcnt(0)
	v_add_f32_e32 v240, v240, v227
	s_mov_b64 exec, s[0:1]
	global_atomic_add_f32 v[220:221], v240, off
	s_mov_b64 exec, -1
	s_mov_b64 vcc, 64
	v_lshl_add_u64 v[220:221], v[220:221], 0, vcc
	v_mov_b32_dpp v222, v76 row_ror:8 row_mask:0xf bank_mask:0xf
	v_mov_b32_dpp v223, v77 row_ror:8 row_mask:0xf bank_mask:0xf
	v_mov_b32_dpp v224, v78 row_ror:8 row_mask:0xf bank_mask:0xf
	v_mov_b32_dpp v225, v79 row_ror:8 row_mask:0xf bank_mask:0xf
	v_cndmask_b32_e64 v76, v222, v80, s[24:25]
	v_cndmask_b32_e64 v77, v223, v81, s[24:25]
	v_cndmask_b32_e64 v78, v224, v82, s[24:25]
	v_cndmask_b32_e64 v79, v225, v83, s[24:25]
	v_cndmask_b32_e64 v80, v80, v222, s[24:25]
	v_cndmask_b32_e64 v81, v81, v223, s[24:25]
	v_cndmask_b32_e64 v82, v82, v224, s[24:25]
	v_cndmask_b32_e64 v83, v83, v225, s[24:25]
	v_mov_b32_dpp v222, v64 row_ror:8 row_mask:0xf bank_mask:0xf
	v_mov_b32_dpp v223, v65 row_ror:8 row_mask:0xf bank_mask:0xf
	v_mov_b32_dpp v224, v66 row_ror:8 row_mask:0xf bank_mask:0xf
	v_mov_b32_dpp v225, v67 row_ror:8 row_mask:0xf bank_mask:0xf
	v_cndmask_b32_e64 v64, v222, v68, s[24:25]
	v_cndmask_b32_e64 v65, v223, v69, s[24:25]
	v_cndmask_b32_e64 v66, v224, v70, s[24:25]
	v_cndmask_b32_e64 v67, v225, v71, s[24:25]
	v_cndmask_b32_e64 v68, v68, v222, s[24:25]
	v_cndmask_b32_e64 v69, v69, v223, s[24:25]
	v_cndmask_b32_e64 v70, v70, v224, s[24:25]
	v_cndmask_b32_e64 v71, v71, v225, s[24:25]
	s_waitcnt vmcnt(19)
;     __device__ __forceinline__ void operator()(const f32x4 (&acc)[2][2][4][2], const Unit& u, int wr, int wc, int fr, int fq) const {
;     ...
;         for (int ai = 0; ai < 2; ++ai)
; #pragma unroll
;             for (int m = 0; m < 4; ++m) {
;                 const int row = row0 + ai * HALF + m * 16;
;                 const size_t off = (size_t)row * ldc + col0;
;                 float q = 0.f;
; #pragma unroll
;                 for (int bj = 0; bj < 2; ++bj)
; #pragma unroll
;                     for (int n = 0; n < 2; ++n) {
;                         const f32x4 rv = *(const f32x4*)(rbase + off + bj * HALF + n * 16);
;                         const f32x4 v = rv + acc[ai][bj][m][n] * scale;
;                         if (out) *(f32x4*)(out + off + bj * HALF + n * 16) = v;
;                         if (xn) { q += (v.x * v.x + v.y * v.y) + (v.z * v.z + v.w * v.w); const f32x4 o = v * wv[bj][n];
;                             u32x2 p; p.x = pk2(o.x, o.y); p.y = pk2(o.z, o.w); *(u32x2*)(xn + off + bj * HALF + n * 16) = p; }
;                     }
;                 if (xn) { q += __shfl_xor(q, 16); q += __shfl_xor(q, 32); if (fq == 0) (void)__hip_atomic_fetch_add(ss + row, q, __ATOMIC_RELAXED, __HIP_MEMORY_SCOPE_AGENT); }
	v_pk_fma_f32 v[78:79], v[78:79], 0.5, v[158:159] op_sel_hi:[1,0,1]
	v_pk_fma_f32 v[76:77], v[76:77], 0.5, v[156:157] op_sel_hi:[1,0,1]
	v_pk_mul_f32 v[232:233], v[72:73], v[76:77]
	v_pk_mul_f32 v[234:235], v[74:75], v[78:79]
	v_mul_f32_e32 v240, v76, v76
	v_add_u32_e32 v232, 0x8000, v232
	v_add_u32_e32 v233, 0x8000, v233
	v_add_u32_e32 v234, 0x8000, v234
	v_add_u32_e32 v235, 0x8000, v235
	v_fmac_f32_e32 v240, v77, v77
	v_fmac_f32_e32 v240, v78, v78
	v_fmac_f32_e32 v240, v79, v79
	v_perm_b32 v228, v233, v232, s50
	v_perm_b32 v229, v235, v234, s50
	global_store_dwordx2 v[216:217], v[228:229], off
	v_pk_fma_f32 v[66:67], v[66:67], 0.5, v[170:171] op_sel_hi:[1,0,1]
	v_pk_fma_f32 v[64:65], v[64:65], 0.5, v[168:169] op_sel_hi:[1,0,1]
	v_pk_mul_f32 v[236:237], v[84:85], v[64:65]
	v_pk_mul_f32 v[238:239], v[86:87], v[66:67]
	v_fmac_f32_e32 v240, v64, v64
	v_add_u32_e32 v236, 0x8000, v236
	v_add_u32_e32 v237, 0x8000, v237
	v_add_u32_e32 v238, 0x8000, v238
	v_add_u32_e32 v239, 0x8000, v239
	v_fmac_f32_e32 v240, v65, v65
	v_fmac_f32_e32 v240, v66, v66
	v_fmac_f32_e32 v240, v67, v67
	v_perm_b32 v230, v237, v236, s50
	v_perm_b32 v231, v239, v238, s50
	global_store_dwordx2 v[216:217], v[230:231], off offset:256
	v_pk_fma_f32 v[82:83], v[82:83], 0.5, v[174:175] op_sel_hi:[1,0,1]
	v_pk_fma_f32 v[80:81], v[80:81], 0.5, v[172:173] op_sel_hi:[1,0,1]
	v_pk_mul_f32 v[232:233], v[88:89], v[80:81]
	v_pk_mul_f32 v[234:235], v[90:91], v[82:83]
	v_mul_f32_e32 v241, v80, v80
	v_add_u32_e32 v232, 0x8000, v232
	v_add_u32_e32 v233, 0x8000, v233
	v_add_u32_e32 v234, 0x8000, v234
	v_add_u32_e32 v235, 0x8000, v235
	v_fmac_f32_e32 v241, v81, v81
	v_fmac_f32_e32 v241, v82, v82
	v_fmac_f32_e32 v241, v83, v83
	v_perm_b32 v228, v233, v232, s50
	v_perm_b32 v229, v235, v234, s50
	global_store_dwordx2 v[218:219], v[228:229], off
	v_pk_fma_f32 v[70:71], v[70:71], 0.5, v[178:179] op_sel_hi:[1,0,1]
	v_pk_fma_f32 v[68:69], v[68:69], 0.5, v[176:177] op_sel_hi:[1,0,1]
	v_pk_mul_f32 v[236:237], v[96:97], v[68:69]
	v_pk_mul_f32 v[238:239], v[98:99], v[70:71]
	v_fmac_f32_e32 v241, v68, v68
	v_add_u32_e32 v236, 0x8000, v236
	v_add_u32_e32 v237, 0x8000, v237
	v_add_u32_e32 v238, 0x8000, v238
	v_add_u32_e32 v239, 0x8000, v239
	v_fmac_f32_e32 v241, v69, v69
	v_fmac_f32_e32 v241, v70, v70
	v_fmac_f32_e32 v241, v71, v71
	v_perm_b32 v230, v237, v236, s50
	v_perm_b32 v231, v239, v238, s50
	global_store_dwordx2 v[218:219], v[230:231], off offset:256
	s_nop 1
	v_mov_b32_dpp v226, v240 row_ror:8 row_mask:0xf bank_mask:0xf
	v_mov_b32_dpp v227, v241 row_ror:8 row_mask:0xf bank_mask:0xf
	v_add_f32_e32 v240, v240, v226
	v_add_f32_e32 v241, v241, v227
	v_cndmask_b32_e64 v240, v241, v240, s[24:25]
	s_nop 0
	ds_bpermute_b32 v226, v242, v240
	global_load_dwordx4 v[156:159], v[212:213], off
	global_load_dwordx4 v[168:171], v[212:213], off offset:512
	global_load_dwordx4 v[172:175], v[214:215], off
	global_load_dwordx4 v[176:179], v[214:215], off offset:512
	s_mov_b64 vcc, 0x20000
	v_lshl_add_u64 v[212:213], v[212:213], 0, vcc
	v_lshl_add_u64 v[214:215], v[214:215], 0, vcc
	s_mov_b64 vcc, 0xa0000
	s_mov_b64 vcc, 0x50000
	v_lshl_add_u64 v[216:217], v[216:217], 0, vcc
	v_lshl_add_u64 v[218:219], v[218:219], 0, vcc
	s_waitcnt lgkmcnt(0)
	v_add_f32_e32 v240, v240, v226
	s_nop 0
	ds_bpermute_b32 v227, v243, v240
	s_waitcnt lgkmcnt(0)
	v_add_f32_e32 v240, v240, v227
	s_mov_b64 exec, s[0:1]
	global_atomic_add_f32 v[220:221], v240, off
	s_mov_b64 exec, -1
	s_mov_b64 vcc, 320
	v_lshl_add_u64 v[220:221], v[220:221], 0, vcc
	v_mov_b32_dpp v222, v56 row_ror:8 row_mask:0xf bank_mask:0xf
	v_mov_b32_dpp v223, v57 row_ror:8 row_mask:0xf bank_mask:0xf
	v_mov_b32_dpp v224, v58 row_ror:8 row_mask:0xf bank_mask:0xf
	v_mov_b32_dpp v225, v59 row_ror:8 row_mask:0xf bank_mask:0xf
	v_cndmask_b32_e64 v56, v222, v60, s[24:25]
	v_cndmask_b32_e64 v57, v223, v61, s[24:25]
	v_cndmask_b32_e64 v58, v224, v62, s[24:25]
	v_cndmask_b32_e64 v59, v225, v63, s[24:25]
	v_cndmask_b32_e64 v60, v60, v222, s[24:25]
	v_cndmask_b32_e64 v61, v61, v223, s[24:25]
	v_cndmask_b32_e64 v62, v62, v224, s[24:25]
	v_cndmask_b32_e64 v63, v63, v225, s[24:25]
	v_mov_b32_dpp v222, v48 row_ror:8 row_mask:0xf bank_mask:0xf
	v_mov_b32_dpp v223, v49 row_ror:8 row_mask:0xf bank_mask:0xf
	v_mov_b32_dpp v224, v50 row_ror:8 row_mask:0xf bank_mask:0xf
	v_mov_b32_dpp v225, v51 row_ror:8 row_mask:0xf bank_mask:0xf
	v_cndmask_b32_e64 v48, v222, v52, s[24:25]
	v_cndmask_b32_e64 v49, v223, v53, s[24:25]
	v_cndmask_b32_e64 v50, v224, v54, s[24:25]
	v_cndmask_b32_e64 v51, v225, v55, s[24:25]
	v_cndmask_b32_e64 v52, v52, v222, s[24:25]
	v_cndmask_b32_e64 v53, v53, v223, s[24:25]
	v_cndmask_b32_e64 v54, v54, v224, s[24:25]
	v_cndmask_b32_e64 v55, v55, v225, s[24:25]
	s_waitcnt vmcnt(19)
;     __device__ __forceinline__ void operator()(const f32x4 (&acc)[2][2][4][2], const Unit& u, int wr, int wc, int fr, int fq) const {
;     ...
;         for (int ai = 0; ai < 2; ++ai)
; #pragma unroll
;             for (int m = 0; m < 4; ++m) {
;                 const int row = row0 + ai * HALF + m * 16;
;                 const size_t off = (size_t)row * ldc + col0;
;                 float q = 0.f;
; #pragma unroll
;                 for (int bj = 0; bj < 2; ++bj)
; #pragma unroll
;                     for (int n = 0; n < 2; ++n) {
;                         const f32x4 rv = *(const f32x4*)(rbase + off + bj * HALF + n * 16);
;                         const f32x4 v = rv + acc[ai][bj][m][n] * scale;
;                         if (out) *(f32x4*)(out + off + bj * HALF + n * 16) = v;
;                         if (xn) { q += (v.x * v.x + v.y * v.y) + (v.z * v.z + v.w * v.w); const f32x4 o = v * wv[bj][n];
;                             u32x2 p; p.x = pk2(o.x, o.y); p.y = pk2(o.z, o.w); *(u32x2*)(xn + off + bj * HALF + n * 16) = p; }
;                     }
;                 if (xn) { q += __shfl_xor(q, 16); q += __shfl_xor(q, 32); if (fq == 0) (void)__hip_atomic_fetch_add(ss + row, q, __ATOMIC_RELAXED, __HIP_MEMORY_SCOPE_AGENT); }
	v_pk_fma_f32 v[58:59], v[58:59], 0.5, v[182:183] op_sel_hi:[1,0,1]
	v_pk_fma_f32 v[56:57], v[56:57], 0.5, v[180:181] op_sel_hi:[1,0,1]
	v_pk_mul_f32 v[232:233], v[72:73], v[56:57]
	v_pk_mul_f32 v[234:235], v[74:75], v[58:59]
	v_mul_f32_e32 v240, v56, v56
	v_add_u32_e32 v232, 0x8000, v232
	v_add_u32_e32 v233, 0x8000, v233
	v_add_u32_e32 v234, 0x8000, v234
	v_add_u32_e32 v235, 0x8000, v235
	v_fmac_f32_e32 v240, v57, v57
	v_fmac_f32_e32 v240, v58, v58
	v_fmac_f32_e32 v240, v59, v59
	v_perm_b32 v228, v233, v232, s50
	v_perm_b32 v229, v235, v234, s50
	global_store_dwordx2 v[216:217], v[228:229], off
	v_pk_fma_f32 v[50:51], v[50:51], 0.5, v[186:187] op_sel_hi:[1,0,1]
	v_pk_fma_f32 v[48:49], v[48:49], 0.5, v[184:185] op_sel_hi:[1,0,1]
	v_pk_mul_f32 v[236:237], v[84:85], v[48:49]
	v_pk_mul_f32 v[238:239], v[86:87], v[50:51]
	v_fmac_f32_e32 v240, v48, v48
	v_add_u32_e32 v236, 0x8000, v236
	v_add_u32_e32 v237, 0x8000, v237
	v_add_u32_e32 v238, 0x8000, v238
	v_add_u32_e32 v239, 0x8000, v239
	v_fmac_f32_e32 v240, v49, v49
	v_fmac_f32_e32 v240, v50, v50
	v_fmac_f32_e32 v240, v51, v51
	v_perm_b32 v230, v237, v236, s50
	v_perm_b32 v231, v239, v238, s50
	global_store_dwordx2 v[216:217], v[230:231], off offset:256
	v_pk_fma_f32 v[62:63], v[62:63], 0.5, v[190:191] op_sel_hi:[1,0,1]
	v_pk_fma_f32 v[60:61], v[60:61], 0.5, v[188:189] op_sel_hi:[1,0,1]
	v_pk_mul_f32 v[232:233], v[88:89], v[60:61]
	v_pk_mul_f32 v[234:235], v[90:91], v[62:63]
	v_mul_f32_e32 v241, v60, v60
	v_add_u32_e32 v232, 0x8000, v232
	v_add_u32_e32 v233, 0x8000, v233
	v_add_u32_e32 v234, 0x8000, v234
	v_add_u32_e32 v235, 0x8000, v235
	v_fmac_f32_e32 v241, v61, v61
	v_fmac_f32_e32 v241, v62, v62
	v_fmac_f32_e32 v241, v63, v63
	v_perm_b32 v228, v233, v232, s50
	v_perm_b32 v229, v235, v234, s50
	global_store_dwordx2 v[218:219], v[228:229], off
	v_pk_fma_f32 v[54:55], v[54:55], 0.5, v[194:195] op_sel_hi:[1,0,1]
	v_pk_fma_f32 v[52:53], v[52:53], 0.5, v[192:193] op_sel_hi:[1,0,1]
	v_pk_mul_f32 v[236:237], v[96:97], v[52:53]
	v_pk_mul_f32 v[238:239], v[98:99], v[54:55]
	v_fmac_f32_e32 v241, v52, v52
	v_add_u32_e32 v236, 0x8000, v236
	v_add_u32_e32 v237, 0x8000, v237
	v_add_u32_e32 v238, 0x8000, v238
	v_add_u32_e32 v239, 0x8000, v239
	v_fmac_f32_e32 v241, v53, v53
	v_fmac_f32_e32 v241, v54, v54
	v_fmac_f32_e32 v241, v55, v55
	v_perm_b32 v230, v237, v236, s50
	v_perm_b32 v231, v239, v238, s50
	global_store_dwordx2 v[218:219], v[230:231], off offset:256
	s_nop 1
	v_mov_b32_dpp v226, v240 row_ror:8 row_mask:0xf bank_mask:0xf
	v_mov_b32_dpp v227, v241 row_ror:8 row_mask:0xf bank_mask:0xf
	v_add_f32_e32 v240, v240, v226
	v_add_f32_e32 v241, v241, v227
	v_cndmask_b32_e64 v240, v241, v240, s[24:25]
	s_nop 0
	ds_bpermute_b32 v226, v242, v240
	global_load_dwordx4 v[180:183], v[212:213], off
	global_load_dwordx4 v[184:187], v[212:213], off offset:512
	global_load_dwordx4 v[188:191], v[214:215], off
	global_load_dwordx4 v[192:195], v[214:215], off offset:512
	s_mov_b64 vcc, 0x20000
	s_mov_b64 vcc, 0x10000
	v_lshl_add_u64 v[216:217], v[216:217], 0, vcc
	v_lshl_add_u64 v[218:219], v[218:219], 0, vcc
	s_waitcnt lgkmcnt(0)
	v_add_f32_e32 v240, v240, v226
	s_nop 0
	ds_bpermute_b32 v227, v243, v240
	s_waitcnt lgkmcnt(0)
	v_add_f32_e32 v240, v240, v227
	s_mov_b64 exec, s[0:1]
	global_atomic_add_f32 v[220:221], v240, off
	s_mov_b64 exec, -1
	s_mov_b64 vcc, 64
	v_lshl_add_u64 v[220:221], v[220:221], 0, vcc
	v_mov_b32_dpp v222, v40 row_ror:8 row_mask:0xf bank_mask:0xf
	v_mov_b32_dpp v223, v41 row_ror:8 row_mask:0xf bank_mask:0xf
	v_mov_b32_dpp v224, v42 row_ror:8 row_mask:0xf bank_mask:0xf
	v_mov_b32_dpp v225, v43 row_ror:8 row_mask:0xf bank_mask:0xf
	v_cndmask_b32_e64 v40, v222, v44, s[24:25]
	v_cndmask_b32_e64 v41, v223, v45, s[24:25]
	v_cndmask_b32_e64 v42, v224, v46, s[24:25]
	v_cndmask_b32_e64 v43, v225, v47, s[24:25]
	v_cndmask_b32_e64 v44, v44, v222, s[24:25]
	v_cndmask_b32_e64 v45, v45, v223, s[24:25]
	v_cndmask_b32_e64 v46, v46, v224, s[24:25]
	v_cndmask_b32_e64 v47, v47, v225, s[24:25]
	v_mov_b32_dpp v222, v32 row_ror:8 row_mask:0xf bank_mask:0xf
	v_mov_b32_dpp v223, v33 row_ror:8 row_mask:0xf bank_mask:0xf
	v_mov_b32_dpp v224, v34 row_ror:8 row_mask:0xf bank_mask:0xf
	v_mov_b32_dpp v225, v35 row_ror:8 row_mask:0xf bank_mask:0xf
	v_cndmask_b32_e64 v32, v222, v36, s[24:25]
	v_cndmask_b32_e64 v33, v223, v37, s[24:25]
	v_cndmask_b32_e64 v34, v224, v38, s[24:25]
	v_cndmask_b32_e64 v35, v225, v39, s[24:25]
	v_cndmask_b32_e64 v36, v36, v222, s[24:25]
	v_cndmask_b32_e64 v37, v37, v223, s[24:25]
	v_cndmask_b32_e64 v38, v38, v224, s[24:25]
	v_cndmask_b32_e64 v39, v39, v225, s[24:25]
	s_waitcnt vmcnt(19)
;     __device__ __forceinline__ void operator()(const f32x4 (&acc)[2][2][4][2], const Unit& u, int wr, int wc, int fr, int fq) const {
;     ...
;         for (int ai = 0; ai < 2; ++ai)
; #pragma unroll
;             for (int m = 0; m < 4; ++m) {
;                 const int row = row0 + ai * HALF + m * 16;
;                 const size_t off = (size_t)row * ldc + col0;
;                 float q = 0.f;
; #pragma unroll
;                 for (int bj = 0; bj < 2; ++bj)
; #pragma unroll
;                     for (int n = 0; n < 2; ++n) {
;                         const f32x4 rv = *(const f32x4*)(rbase + off + bj * HALF + n * 16);
;                         const f32x4 v = rv + acc[ai][bj][m][n] * scale;
;                         if (out) *(f32x4*)(out + off + bj * HALF + n * 16) = v;
;                         if (xn) { q += (v.x * v.x + v.y * v.y) + (v.z * v.z + v.w * v.w); const f32x4 o = v * wv[bj][n];
;                             u32x2 p; p.x = pk2(o.x, o.y); p.y = pk2(o.z, o.w); *(u32x2*)(xn + off + bj * HALF + n * 16) = p; }
;                     }
;                 if (xn) { q += __shfl_xor(q, 16); q += __shfl_xor(q, 32); if (fq == 0) (void)__hip_atomic_fetch_add(ss + row, q, __ATOMIC_RELAXED, __HIP_MEMORY_SCOPE_AGENT); }
	v_pk_fma_f32 v[42:43], v[42:43], 0.5, v[198:199] op_sel_hi:[1,0,1]
	v_pk_fma_f32 v[40:41], v[40:41], 0.5, v[196:197] op_sel_hi:[1,0,1]
	v_pk_mul_f32 v[232:233], v[72:73], v[40:41]
	v_pk_mul_f32 v[234:235], v[74:75], v[42:43]
	v_mul_f32_e32 v240, v40, v40
	v_add_u32_e32 v232, 0x8000, v232
	v_add_u32_e32 v233, 0x8000, v233
	v_add_u32_e32 v234, 0x8000, v234
	v_add_u32_e32 v235, 0x8000, v235
	v_fmac_f32_e32 v240, v41, v41
	v_fmac_f32_e32 v240, v42, v42
	v_fmac_f32_e32 v240, v43, v43
	v_perm_b32 v228, v233, v232, s50
	v_perm_b32 v229, v235, v234, s50
	global_store_dwordx2 v[216:217], v[228:229], off
	v_pk_fma_f32 v[34:35], v[34:35], 0.5, v[202:203] op_sel_hi:[1,0,1]
	v_pk_fma_f32 v[32:33], v[32:33], 0.5, v[200:201] op_sel_hi:[1,0,1]
	v_pk_mul_f32 v[236:237], v[84:85], v[32:33]
	v_pk_mul_f32 v[238:239], v[86:87], v[34:35]
	v_fmac_f32_e32 v240, v32, v32
	v_add_u32_e32 v236, 0x8000, v236
	v_add_u32_e32 v237, 0x8000, v237
	v_add_u32_e32 v238, 0x8000, v238
	v_add_u32_e32 v239, 0x8000, v239
	v_fmac_f32_e32 v240, v33, v33
	v_fmac_f32_e32 v240, v34, v34
	v_fmac_f32_e32 v240, v35, v35
	v_perm_b32 v230, v237, v236, s50
	v_perm_b32 v231, v239, v238, s50
	global_store_dwordx2 v[216:217], v[230:231], off offset:256
	v_pk_fma_f32 v[46:47], v[46:47], 0.5, v[206:207] op_sel_hi:[1,0,1]
	v_pk_fma_f32 v[44:45], v[44:45], 0.5, v[204:205] op_sel_hi:[1,0,1]
	v_pk_mul_f32 v[232:233], v[88:89], v[44:45]
	v_pk_mul_f32 v[234:235], v[90:91], v[46:47]
	v_mul_f32_e32 v241, v44, v44
	v_add_u32_e32 v232, 0x8000, v232
	v_add_u32_e32 v233, 0x8000, v233
	v_add_u32_e32 v234, 0x8000, v234
	v_add_u32_e32 v235, 0x8000, v235
	v_fmac_f32_e32 v241, v45, v45
	v_fmac_f32_e32 v241, v46, v46
	v_fmac_f32_e32 v241, v47, v47
	v_perm_b32 v228, v233, v232, s50
	v_perm_b32 v229, v235, v234, s50
	global_store_dwordx2 v[218:219], v[228:229], off
	v_pk_fma_f32 v[38:39], v[38:39], 0.5, v[210:211] op_sel_hi:[1,0,1]
	v_pk_fma_f32 v[36:37], v[36:37], 0.5, v[208:209] op_sel_hi:[1,0,1]
	v_pk_mul_f32 v[236:237], v[96:97], v[36:37]
	v_pk_mul_f32 v[238:239], v[98:99], v[38:39]
	v_fmac_f32_e32 v241, v36, v36
	v_add_u32_e32 v236, 0x8000, v236
	v_add_u32_e32 v237, 0x8000, v237
	v_add_u32_e32 v238, 0x8000, v238
	v_add_u32_e32 v239, 0x8000, v239
	v_fmac_f32_e32 v241, v37, v37
	v_fmac_f32_e32 v241, v38, v38
	v_fmac_f32_e32 v241, v39, v39
	v_perm_b32 v230, v237, v236, s50
	v_perm_b32 v231, v239, v238, s50
	global_store_dwordx2 v[218:219], v[230:231], off offset:256
	s_nop 1
	v_mov_b32_dpp v226, v240 row_ror:8 row_mask:0xf bank_mask:0xf
	v_mov_b32_dpp v227, v241 row_ror:8 row_mask:0xf bank_mask:0xf
	v_add_f32_e32 v240, v240, v226
	v_add_f32_e32 v241, v241, v227
	v_cndmask_b32_e64 v240, v241, v240, s[24:25]
	s_nop 0
	ds_bpermute_b32 v226, v242, v240
	s_mov_b64 vcc, 0x20000
	s_mov_b64 vcc, 0x10000
	v_lshl_add_u64 v[216:217], v[216:217], 0, vcc
	v_lshl_add_u64 v[218:219], v[218:219], 0, vcc
	s_waitcnt lgkmcnt(0)
	v_add_f32_e32 v240, v240, v226
	s_nop 0
	ds_bpermute_b32 v227, v243, v240
	s_waitcnt lgkmcnt(0)
	v_add_f32_e32 v240, v240, v227
	s_mov_b64 exec, s[0:1]
	global_atomic_add_f32 v[220:221], v240, off
	s_mov_b64 exec, -1
	s_mov_b64 vcc, 64
	v_lshl_add_u64 v[220:221], v[220:221], 0, vcc
	v_mov_b32_dpp v222, v24 row_ror:8 row_mask:0xf bank_mask:0xf
	v_mov_b32_dpp v223, v25 row_ror:8 row_mask:0xf bank_mask:0xf
	v_mov_b32_dpp v224, v26 row_ror:8 row_mask:0xf bank_mask:0xf
	v_mov_b32_dpp v225, v27 row_ror:8 row_mask:0xf bank_mask:0xf
	v_cndmask_b32_e64 v24, v222, v28, s[24:25]
	v_cndmask_b32_e64 v25, v223, v29, s[24:25]
	v_cndmask_b32_e64 v26, v224, v30, s[24:25]
	v_cndmask_b32_e64 v27, v225, v31, s[24:25]
	v_cndmask_b32_e64 v28, v28, v222, s[24:25]
	v_cndmask_b32_e64 v29, v29, v223, s[24:25]
	v_cndmask_b32_e64 v30, v30, v224, s[24:25]
	v_cndmask_b32_e64 v31, v31, v225, s[24:25]
	v_mov_b32_dpp v222, v16 row_ror:8 row_mask:0xf bank_mask:0xf
	v_mov_b32_dpp v223, v17 row_ror:8 row_mask:0xf bank_mask:0xf
	v_mov_b32_dpp v224, v18 row_ror:8 row_mask:0xf bank_mask:0xf
	v_mov_b32_dpp v225, v19 row_ror:8 row_mask:0xf bank_mask:0xf
	v_cndmask_b32_e64 v16, v222, v20, s[24:25]
	v_cndmask_b32_e64 v17, v223, v21, s[24:25]
	v_cndmask_b32_e64 v18, v224, v22, s[24:25]
	v_cndmask_b32_e64 v19, v225, v23, s[24:25]
	v_cndmask_b32_e64 v20, v20, v222, s[24:25]
	v_cndmask_b32_e64 v21, v21, v223, s[24:25]
	v_cndmask_b32_e64 v22, v22, v224, s[24:25]
	v_cndmask_b32_e64 v23, v23, v225, s[24:25]
	s_waitcnt vmcnt(15)
;     __device__ __forceinline__ void operator()(const f32x4 (&acc)[2][2][4][2], const Unit& u, int wr, int wc, int fr, int fq) const {
;     ...
;         for (int ai = 0; ai < 2; ++ai)
; #pragma unroll
;             for (int m = 0; m < 4; ++m) {
;                 const int row = row0 + ai * HALF + m * 16;
;                 const size_t off = (size_t)row * ldc + col0;
;                 float q = 0.f;
; #pragma unroll
;                 for (int bj = 0; bj < 2; ++bj)
; #pragma unroll
;                     for (int n = 0; n < 2; ++n) {
;                         const f32x4 rv = *(const f32x4*)(rbase + off + bj * HALF + n * 16);
;                         const f32x4 v = rv + acc[ai][bj][m][n] * scale;
;                         if (out) *(f32x4*)(out + off + bj * HALF + n * 16) = v;
;                         if (xn) { q += (v.x * v.x + v.y * v.y) + (v.z * v.z + v.w * v.w); const f32x4 o = v * wv[bj][n];
;                             u32x2 p; p.x = pk2(o.x, o.y); p.y = pk2(o.z, o.w); *(u32x2*)(xn + off + bj * HALF + n * 16) = p; }
;                     }
;                 if (xn) { q += __shfl_xor(q, 16); q += __shfl_xor(q, 32); if (fq == 0) (void)__hip_atomic_fetch_add(ss + row, q, __ATOMIC_RELAXED, __HIP_MEMORY_SCOPE_AGENT); }
	v_pk_fma_f32 v[26:27], v[26:27], 0.5, v[158:159] op_sel_hi:[1,0,1]
	v_pk_fma_f32 v[24:25], v[24:25], 0.5, v[156:157] op_sel_hi:[1,0,1]
	v_pk_mul_f32 v[232:233], v[72:73], v[24:25]
	v_pk_mul_f32 v[234:235], v[74:75], v[26:27]
	v_mul_f32_e32 v240, v24, v24
	v_add_u32_e32 v232, 0x8000, v232
	v_add_u32_e32 v233, 0x8000, v233
	v_add_u32_e32 v234, 0x8000, v234
	v_add_u32_e32 v235, 0x8000, v235
	v_fmac_f32_e32 v240, v25, v25
	v_fmac_f32_e32 v240, v26, v26
	v_fmac_f32_e32 v240, v27, v27
	v_perm_b32 v228, v233, v232, s50
	v_perm_b32 v229, v235, v234, s50
	global_store_dwordx2 v[216:217], v[228:229], off
	v_pk_fma_f32 v[18:19], v[18:19], 0.5, v[170:171] op_sel_hi:[1,0,1]
	v_pk_fma_f32 v[16:17], v[16:17], 0.5, v[168:169] op_sel_hi:[1,0,1]
	v_pk_mul_f32 v[236:237], v[84:85], v[16:17]
	v_pk_mul_f32 v[238:239], v[86:87], v[18:19]
	v_fmac_f32_e32 v240, v16, v16
	v_add_u32_e32 v236, 0x8000, v236
	v_add_u32_e32 v237, 0x8000, v237
	v_add_u32_e32 v238, 0x8000, v238
	v_add_u32_e32 v239, 0x8000, v239
	v_fmac_f32_e32 v240, v17, v17
	v_fmac_f32_e32 v240, v18, v18
	v_fmac_f32_e32 v240, v19, v19
	v_perm_b32 v230, v237, v236, s50
	v_perm_b32 v231, v239, v238, s50
	global_store_dwordx2 v[216:217], v[230:231], off offset:256
	v_pk_fma_f32 v[30:31], v[30:31], 0.5, v[174:175] op_sel_hi:[1,0,1]
	v_pk_fma_f32 v[28:29], v[28:29], 0.5, v[172:173] op_sel_hi:[1,0,1]
	v_pk_mul_f32 v[232:233], v[88:89], v[28:29]
	v_pk_mul_f32 v[234:235], v[90:91], v[30:31]
	v_mul_f32_e32 v241, v28, v28
	v_add_u32_e32 v232, 0x8000, v232
	v_add_u32_e32 v233, 0x8000, v233
	v_add_u32_e32 v234, 0x8000, v234
	v_add_u32_e32 v235, 0x8000, v235
	v_fmac_f32_e32 v241, v29, v29
	v_fmac_f32_e32 v241, v30, v30
	v_fmac_f32_e32 v241, v31, v31
	v_perm_b32 v228, v233, v232, s50
	v_perm_b32 v229, v235, v234, s50
	global_store_dwordx2 v[218:219], v[228:229], off
	v_pk_fma_f32 v[22:23], v[22:23], 0.5, v[178:179] op_sel_hi:[1,0,1]
	v_pk_fma_f32 v[20:21], v[20:21], 0.5, v[176:177] op_sel_hi:[1,0,1]
	v_pk_mul_f32 v[236:237], v[96:97], v[20:21]
	v_pk_mul_f32 v[238:239], v[98:99], v[22:23]
	v_fmac_f32_e32 v241, v20, v20
	v_add_u32_e32 v236, 0x8000, v236
	v_add_u32_e32 v237, 0x8000, v237
	v_add_u32_e32 v238, 0x8000, v238
	v_add_u32_e32 v239, 0x8000, v239
	v_fmac_f32_e32 v241, v21, v21
	v_fmac_f32_e32 v241, v22, v22
	v_fmac_f32_e32 v241, v23, v23
	v_perm_b32 v230, v237, v236, s50
	v_perm_b32 v231, v239, v238, s50
	global_store_dwordx2 v[218:219], v[230:231], off offset:256
	s_nop 1
	v_mov_b32_dpp v226, v240 row_ror:8 row_mask:0xf bank_mask:0xf
	v_mov_b32_dpp v227, v241 row_ror:8 row_mask:0xf bank_mask:0xf
	v_add_f32_e32 v240, v240, v226
	v_add_f32_e32 v241, v241, v227
	v_cndmask_b32_e64 v240, v241, v240, s[24:25]
	s_nop 0
	ds_bpermute_b32 v226, v242, v240
	s_mov_b64 vcc, 0x20000
	s_mov_b64 vcc, 0x10000
	v_lshl_add_u64 v[216:217], v[216:217], 0, vcc
	v_lshl_add_u64 v[218:219], v[218:219], 0, vcc
	s_waitcnt lgkmcnt(0)
	v_add_f32_e32 v240, v240, v226
	s_nop 0
	ds_bpermute_b32 v227, v243, v240
	s_waitcnt lgkmcnt(0)
	v_add_f32_e32 v240, v240, v227
	s_mov_b64 exec, s[0:1]
	global_atomic_add_f32 v[220:221], v240, off
	s_mov_b64 exec, -1
	s_mov_b64 vcc, 64
	v_lshl_add_u64 v[220:221], v[220:221], 0, vcc
	v_mov_b32_dpp v222, v8 row_ror:8 row_mask:0xf bank_mask:0xf
	v_mov_b32_dpp v223, v9 row_ror:8 row_mask:0xf bank_mask:0xf
	v_mov_b32_dpp v224, v10 row_ror:8 row_mask:0xf bank_mask:0xf
	v_mov_b32_dpp v225, v11 row_ror:8 row_mask:0xf bank_mask:0xf
	v_cndmask_b32_e64 v8, v222, v12, s[24:25]
	v_cndmask_b32_e64 v9, v223, v13, s[24:25]
	v_cndmask_b32_e64 v10, v224, v14, s[24:25]
	v_cndmask_b32_e64 v11, v225, v15, s[24:25]
	v_cndmask_b32_e64 v12, v12, v222, s[24:25]
	v_cndmask_b32_e64 v13, v13, v223, s[24:25]
	v_cndmask_b32_e64 v14, v14, v224, s[24:25]
	v_cndmask_b32_e64 v15, v15, v225, s[24:25]
	v_mov_b32_dpp v222, v0 row_ror:8 row_mask:0xf bank_mask:0xf
	v_mov_b32_dpp v223, v1 row_ror:8 row_mask:0xf bank_mask:0xf
	v_mov_b32_dpp v224, v2 row_ror:8 row_mask:0xf bank_mask:0xf
	v_mov_b32_dpp v225, v3 row_ror:8 row_mask:0xf bank_mask:0xf
	v_cndmask_b32_e64 v0, v222, v4, s[24:25]
	v_cndmask_b32_e64 v1, v223, v5, s[24:25]
	v_cndmask_b32_e64 v2, v224, v6, s[24:25]
	v_cndmask_b32_e64 v3, v225, v7, s[24:25]
	v_cndmask_b32_e64 v4, v4, v222, s[24:25]
	v_cndmask_b32_e64 v5, v5, v223, s[24:25]
	v_cndmask_b32_e64 v6, v6, v224, s[24:25]
	v_cndmask_b32_e64 v7, v7, v225, s[24:25]
	s_waitcnt vmcnt(11)
; #define PG8_BAR __builtin_amdgcn_s_barrier()
;     __device__ __forceinline__ void operator()(const f32x4 (&acc)[2][2][4][2], const Unit& u, int wr, int wc, int fr, int fq) const {
;     ...
;                 for (int bj = 0; bj < 2; ++bj)
; #pragma unroll
;                     for (int n = 0; n < 2; ++n) {
;                         const f32x4 rv = *(const f32x4*)(rbase + off + bj * HALF + n * 16);
;                         const f32x4 v = rv + acc[ai][bj][m][n] * scale;
;                         if (out) *(f32x4*)(out + off + bj * HALF + n * 16) = v;
;                         if (xn) { q += (v.x * v.x + v.y * v.y) + (v.z * v.z + v.w * v.w); const f32x4 o = v * wv[bj][n];
;                             u32x2 p; p.x = pk2(o.x, o.y); p.y = pk2(o.z, o.w); *(u32x2*)(xn + off + bj * HALF + n * 16) = p; }
;                     }
;                 if (xn) { q += __shfl_xor(q, 16); q += __shfl_xor(q, 32); if (fq == 0) (void)__hip_atomic_fetch_add(ss + row, q, __ATOMIC_RELAXED, __HIP_MEMORY_SCOPE_AGENT); }
; template <class Epi, bool ALIGN_EPI>
; __device__ __forceinline__ void gemm_phase(LAS unsigned char* lds, const Gemm g, const StaticOrder& S, const Epi& E) {
;     ...
;         if (!has_next) break;
; #pragma unroll
;         for (int a = 0; a < 2; ++a)
; #pragma unroll
;             for (int b = 0; b < 2; ++b)
; #pragma unroll
;                 for (int m = 0; m < 4; ++m)
; #pragma unroll
;                     for (int n = 0; n < 2; ++n) acc[a][b][m][n] = (f32x4){0.f, 0.f, 0.f, 0.f};
;         cur = nxt; cA = nA; cB = nB; ++ui;
;         if constexpr (ALIGN_EPI) { if (wr == 1) PG8_BAR; }
	v_pk_fma_f32 v[10:11], v[10:11], 0.5, v[182:183] op_sel_hi:[1,0,1]
	v_pk_fma_f32 v[8:9], v[8:9], 0.5, v[180:181] op_sel_hi:[1,0,1]
	v_pk_mul_f32 v[232:233], v[72:73], v[8:9]
	v_pk_mul_f32 v[234:235], v[74:75], v[10:11]
	v_mul_f32_e32 v240, v8, v8
	v_add_u32_e32 v232, 0x8000, v232
	v_add_u32_e32 v233, 0x8000, v233
	v_add_u32_e32 v234, 0x8000, v234
	v_add_u32_e32 v235, 0x8000, v235
	v_fmac_f32_e32 v240, v9, v9
	v_fmac_f32_e32 v240, v10, v10
	v_fmac_f32_e32 v240, v11, v11
	v_perm_b32 v228, v233, v232, s50
	v_perm_b32 v229, v235, v234, s50
	global_store_dwordx2 v[216:217], v[228:229], off
	v_pk_fma_f32 v[2:3], v[2:3], 0.5, v[186:187] op_sel_hi:[1,0,1]
	v_pk_fma_f32 v[0:1], v[0:1], 0.5, v[184:185] op_sel_hi:[1,0,1]
	v_pk_mul_f32 v[236:237], v[84:85], v[0:1]
	v_pk_mul_f32 v[238:239], v[86:87], v[2:3]
	v_fmac_f32_e32 v240, v0, v0
	v_add_u32_e32 v236, 0x8000, v236
	v_add_u32_e32 v237, 0x8000, v237
	v_add_u32_e32 v238, 0x8000, v238
	v_add_u32_e32 v239, 0x8000, v239
	v_fmac_f32_e32 v240, v1, v1
	v_fmac_f32_e32 v240, v2, v2
	v_fmac_f32_e32 v240, v3, v3
	v_perm_b32 v230, v237, v236, s50
	v_perm_b32 v231, v239, v238, s50
	global_store_dwordx2 v[216:217], v[230:231], off offset:256
	v_pk_fma_f32 v[14:15], v[14:15], 0.5, v[190:191] op_sel_hi:[1,0,1]
	v_pk_fma_f32 v[12:13], v[12:13], 0.5, v[188:189] op_sel_hi:[1,0,1]
	v_pk_mul_f32 v[232:233], v[88:89], v[12:13]
	v_pk_mul_f32 v[234:235], v[90:91], v[14:15]
	v_mul_f32_e32 v241, v12, v12
	v_add_u32_e32 v232, 0x8000, v232
	v_add_u32_e32 v233, 0x8000, v233
	v_add_u32_e32 v234, 0x8000, v234
	v_add_u32_e32 v235, 0x8000, v235
	v_fmac_f32_e32 v241, v13, v13
	v_fmac_f32_e32 v241, v14, v14
	v_fmac_f32_e32 v241, v15, v15
	v_perm_b32 v228, v233, v232, s50
	v_perm_b32 v229, v235, v234, s50
	global_store_dwordx2 v[218:219], v[228:229], off
	v_pk_fma_f32 v[6:7], v[6:7], 0.5, v[194:195] op_sel_hi:[1,0,1]
	v_pk_fma_f32 v[4:5], v[4:5], 0.5, v[192:193] op_sel_hi:[1,0,1]
	v_pk_mul_f32 v[236:237], v[96:97], v[4:5]
	v_pk_mul_f32 v[238:239], v[98:99], v[6:7]
	v_fmac_f32_e32 v241, v4, v4
	v_add_u32_e32 v236, 0x8000, v236
	v_add_u32_e32 v237, 0x8000, v237
	v_add_u32_e32 v238, 0x8000, v238
	v_add_u32_e32 v239, 0x8000, v239
	v_fmac_f32_e32 v241, v5, v5
	v_fmac_f32_e32 v241, v6, v6
	v_fmac_f32_e32 v241, v7, v7
	v_perm_b32 v230, v237, v236, s50
	v_perm_b32 v231, v239, v238, s50
	global_store_dwordx2 v[218:219], v[230:231], off offset:256
	s_nop 1
	v_mov_b32_dpp v226, v240 row_ror:8 row_mask:0xf bank_mask:0xf
	v_mov_b32_dpp v227, v241 row_ror:8 row_mask:0xf bank_mask:0xf
	v_add_f32_e32 v240, v240, v226
	v_add_f32_e32 v241, v241, v227
	v_cndmask_b32_e64 v240, v241, v240, s[24:25]
	s_nop 0
	ds_bpermute_b32 v226, v242, v240
	s_waitcnt lgkmcnt(0)
	v_add_f32_e32 v240, v240, v226
	s_nop 0
	ds_bpermute_b32 v227, v243, v240
	s_waitcnt lgkmcnt(0)
	v_add_f32_e32 v240, v240, v227
	s_mov_b64 exec, s[0:1]
	global_atomic_add_f32 v[220:221], v240, off
	s_mov_b64 exec, -1
	s_and_b64 vcc, exec, s[6:7]
	s_mov_b64 s[6:7], -1
	s_cbranch_vccnz .LBB0_1371
	s_andn2_b64 vcc, exec, s[12:13]
	s_cbranch_vccnz .LBB0_1370
	s_barrier
	s_branch .LBB0_1370
